# plus GEMM loops: m0-hazard nops replaced by hoisted m0 writes / reordered ds_read fillers; attention: no-op scalar adds removed
# speedup vs baseline: 1.0174x; 1.0022x over previous
.LBB0_35:
	s_add_u32 s0, s8, 0xfff80080
	s_addc_u32 s1, s9, -1
	s_add_i32 s2, 0, 0x10000
	v_add_u32_e32 v138, s2, v182
	ds_read_b128 v[154:157], v138
	ds_read_b128 v[158:161], v138 offset:1024
	ds_read_b128 v[162:165], v138 offset:2048
	ds_read_b128 v[166:169], v138 offset:3072
	s_cmp_eq_u32 s15, 28
	s_cselect_b32 s65, s67, s1
	s_cselect_b32 s64, s66, s0
	s_cselect_b32 s1, s45, s13
	s_cselect_b32 s0, s44, s11
	s_add_i32 m0, s17, 0xc000
	ds_read_b128 v[170:173], v183
	ds_read_b128 v[174:177], v183 offset:1024
	ds_read_b128 v[178:181], v183 offset:2048
	ds_read_b128 v[184:187], v183 offset:3072
	ds_read_b128 v[188:191], v183 offset:4096
	ds_read_b128 v[192:195], v183 offset:5120
	ds_read_b128 v[196:199], v183 offset:6144
	global_load_lds_dwordx4 v136, s[8:9]
	s_add_i32 m0, s17, 0xe000
	ds_read_b128 v[200:203], v183 offset:7168
	global_load_lds_dwordx4 v134, s[8:9]
	s_waitcnt lgkmcnt(8)
	s_barrier
	s_waitcnt lgkmcnt(0)
	s_setprio 1
	v_mfma_f32_16x16x32_bf16 v[124:127], v[154:157], v[170:173], v[124:127]
	v_mfma_f32_16x16x32_bf16 v[92:95], v[162:165], v[170:173], v[92:95]
	v_mfma_f32_16x16x32_bf16 v[120:123], v[154:157], v[178:181], v[120:123]
	v_mfma_f32_16x16x32_bf16 v[88:91], v[162:165], v[178:181], v[88:91]
	v_mfma_f32_16x16x32_bf16 v[116:119], v[154:157], v[188:191], v[116:119]
	v_mfma_f32_16x16x32_bf16 v[84:87], v[162:165], v[188:191], v[84:87]
	v_mfma_f32_16x16x32_bf16 v[112:115], v[154:157], v[196:199], v[112:115]
	v_mfma_f32_16x16x32_bf16 v[80:83], v[162:165], v[196:199], v[80:83]
	v_mfma_f32_16x16x32_bf16 v[124:127], v[158:161], v[174:177], v[124:127]
	v_mfma_f32_16x16x32_bf16 v[92:95], v[166:169], v[174:177], v[92:95]
	v_mfma_f32_16x16x32_bf16 v[120:123], v[158:161], v[184:187], v[120:123]
	v_mfma_f32_16x16x32_bf16 v[88:91], v[166:169], v[184:187], v[88:91]
	v_mfma_f32_16x16x32_bf16 v[116:119], v[158:161], v[192:195], v[116:119]
	v_mfma_f32_16x16x32_bf16 v[84:87], v[166:169], v[192:195], v[84:87]
	v_mfma_f32_16x16x32_bf16 v[112:115], v[158:161], v[200:203], v[112:115]
	v_mfma_f32_16x16x32_bf16 v[80:83], v[166:169], v[200:203], v[80:83]
	s_setprio 0
	s_barrier
	s_add_i32 s20, 0, 0x14000
	v_add_u32_e32 v138, s20, v182
	s_add_i32 s2, s2, s69
	ds_read_b128 v[204:207], v138
	ds_read_b128 v[208:211], v138 offset:1024
	ds_read_b128 v[228:231], v138 offset:2048
	s_mov_b32 m0, s2
	ds_read_b128 v[232:235], v138 offset:3072
	global_load_lds_dwordx4 v140, s[0:1]
	s_add_i32 m0, s2, 0x2000
	s_nop 0
	global_load_lds_dwordx4 v132, s[0:1]
	s_barrier
	s_waitcnt lgkmcnt(0)
	s_setprio 1
	v_mfma_f32_16x16x32_bf16 v[60:63], v[204:207], v[170:173], v[60:63]
	v_mfma_f32_16x16x32_bf16 v[28:31], v[228:231], v[170:173], v[28:31]
	v_mfma_f32_16x16x32_bf16 v[56:59], v[204:207], v[178:181], v[56:59]
	v_mfma_f32_16x16x32_bf16 v[24:27], v[228:231], v[178:181], v[24:27]
	v_mfma_f32_16x16x32_bf16 v[52:55], v[204:207], v[188:191], v[52:55]
	v_mfma_f32_16x16x32_bf16 v[20:23], v[228:231], v[188:191], v[20:23]
	v_mfma_f32_16x16x32_bf16 v[48:51], v[204:207], v[196:199], v[48:51]
	v_mfma_f32_16x16x32_bf16 v[16:19], v[228:231], v[196:199], v[16:19]
	v_mfma_f32_16x16x32_bf16 v[60:63], v[208:211], v[174:177], v[60:63]
	v_mfma_f32_16x16x32_bf16 v[28:31], v[232:235], v[174:177], v[28:31]
	v_mfma_f32_16x16x32_bf16 v[56:59], v[208:211], v[184:187], v[56:59]
	v_mfma_f32_16x16x32_bf16 v[24:27], v[232:235], v[184:187], v[24:27]
	v_mfma_f32_16x16x32_bf16 v[52:55], v[208:211], v[192:195], v[52:55]
	v_mfma_f32_16x16x32_bf16 v[20:23], v[232:235], v[192:195], v[20:23]
	v_mfma_f32_16x16x32_bf16 v[48:51], v[208:211], v[200:203], v[48:51]
	v_mfma_f32_16x16x32_bf16 v[16:19], v[232:235], v[200:203], v[16:19]
	s_setprio 0
	s_mov_b32 m0, s17
	s_barrier
	ds_read_b128 v[170:173], v183 offset:16384
	ds_read_b128 v[174:177], v183 offset:17408
	ds_read_b128 v[178:181], v183 offset:18432
	ds_read_b128 v[184:187], v183 offset:19456
	ds_read_b128 v[188:191], v183 offset:20480
	ds_read_b128 v[192:195], v183 offset:21504
	ds_read_b128 v[196:199], v183 offset:22528
	global_load_lds_dwordx4 v128, s[64:65]
	s_mov_b32 m0, s71
	ds_read_b128 v[200:203], v183 offset:23552
	global_load_lds_dwordx4 v130, s[64:65]
	s_barrier
	s_waitcnt lgkmcnt(0)
	s_setprio 1
	v_mfma_f32_16x16x32_bf16 v[108:111], v[154:157], v[170:173], v[108:111]
	v_mfma_f32_16x16x32_bf16 v[76:79], v[162:165], v[170:173], v[76:79]
	v_mfma_f32_16x16x32_bf16 v[104:107], v[154:157], v[178:181], v[104:107]
	v_mfma_f32_16x16x32_bf16 v[72:75], v[162:165], v[178:181], v[72:75]
	v_mfma_f32_16x16x32_bf16 v[100:103], v[154:157], v[188:191], v[100:103]
	v_mfma_f32_16x16x32_bf16 v[68:71], v[162:165], v[188:191], v[68:71]
	v_mfma_f32_16x16x32_bf16 v[96:99], v[154:157], v[196:199], v[96:99]
	v_mfma_f32_16x16x32_bf16 v[64:67], v[162:165], v[196:199], v[64:67]
	v_mfma_f32_16x16x32_bf16 v[108:111], v[158:161], v[174:177], v[108:111]
	v_mfma_f32_16x16x32_bf16 v[76:79], v[166:169], v[174:177], v[76:79]
	v_mfma_f32_16x16x32_bf16 v[104:107], v[158:161], v[184:187], v[104:107]
	v_mfma_f32_16x16x32_bf16 v[72:75], v[166:169], v[184:187], v[72:75]
	v_mfma_f32_16x16x32_bf16 v[100:103], v[158:161], v[192:195], v[100:103]
	v_mfma_f32_16x16x32_bf16 v[68:71], v[166:169], v[192:195], v[68:71]
	v_mfma_f32_16x16x32_bf16 v[96:99], v[158:161], v[200:203], v[96:99]
	v_mfma_f32_16x16x32_bf16 v[64:67], v[166:169], v[200:203], v[64:67]
	s_setprio 0
	s_barrier
	s_add_u32 s18, s0, 0x100000
	s_addc_u32 s19, s1, 0
	s_add_i32 s2, s20, s69
	s_mov_b32 m0, s2
	s_nop 0
	global_load_lds_dwordx4 v140, s[18:19]
	s_add_i32 m0, s2, 0x2000
	s_nop 0
	global_load_lds_dwordx4 v132, s[18:19]
	s_waitcnt vmcnt(6)
	s_barrier
	s_setprio 1
	v_mfma_f32_16x16x32_bf16 v[44:47], v[204:207], v[170:173], v[44:47]
	v_mfma_f32_16x16x32_bf16 v[12:15], v[228:231], v[170:173], v[12:15]
	v_mfma_f32_16x16x32_bf16 v[40:43], v[204:207], v[178:181], v[40:43]
	v_mfma_f32_16x16x32_bf16 v[8:11], v[228:231], v[178:181], v[8:11]
	v_mfma_f32_16x16x32_bf16 v[36:39], v[204:207], v[188:191], v[36:39]
	v_mfma_f32_16x16x32_bf16 v[4:7], v[228:231], v[188:191], v[4:7]
	v_mfma_f32_16x16x32_bf16 v[32:35], v[204:207], v[196:199], v[32:35]
	v_mfma_f32_16x16x32_bf16 v[0:3], v[228:231], v[196:199], v[0:3]
	v_mfma_f32_16x16x32_bf16 v[44:47], v[208:211], v[174:177], v[44:47]
	v_mfma_f32_16x16x32_bf16 v[12:15], v[232:235], v[174:177], v[12:15]
	v_mfma_f32_16x16x32_bf16 v[40:43], v[208:211], v[184:187], v[40:43]
	v_mfma_f32_16x16x32_bf16 v[8:11], v[232:235], v[184:187], v[8:11]
	v_mfma_f32_16x16x32_bf16 v[36:39], v[208:211], v[192:195], v[36:39]
	v_mfma_f32_16x16x32_bf16 v[4:7], v[232:235], v[192:195], v[4:7]
	v_mfma_f32_16x16x32_bf16 v[32:35], v[208:211], v[200:203], v[32:35]
	v_mfma_f32_16x16x32_bf16 v[0:3], v[232:235], v[200:203], v[0:3]
	s_setprio 0
	s_add_i32 s2, 0, 0x18000
	v_add_u32_e32 v166, s2, v182
	s_barrier
	ds_read_b128 v[154:157], v166
	ds_read_b128 v[158:161], v166 offset:1024
	ds_read_b128 v[162:165], v166 offset:2048
	ds_read_b128 v[166:169], v166 offset:3072
	s_add_u32 s18, s64, 0x80000
	s_addc_u32 s19, s65, 0
	s_mov_b32 m0, s72
	ds_read_b128 v[170:173], v183 offset:32768
	ds_read_b128 v[174:177], v183 offset:33792
	ds_read_b128 v[178:181], v183 offset:34816
	ds_read_b128 v[184:187], v183 offset:35840
	ds_read_b128 v[188:191], v183 offset:36864
	ds_read_b128 v[192:195], v183 offset:37888
	ds_read_b128 v[196:199], v183 offset:38912
	global_load_lds_dwordx4 v128, s[18:19]
	s_mov_b32 m0, s73
	ds_read_b128 v[200:203], v183 offset:39936
	global_load_lds_dwordx4 v130, s[18:19]
	s_waitcnt lgkmcnt(8)
	s_barrier
	s_waitcnt lgkmcnt(0)
	s_setprio 1
	v_mfma_f32_16x16x32_bf16 v[124:127], v[154:157], v[170:173], v[124:127]
	v_mfma_f32_16x16x32_bf16 v[92:95], v[162:165], v[170:173], v[92:95]
	v_mfma_f32_16x16x32_bf16 v[120:123], v[154:157], v[178:181], v[120:123]
	v_mfma_f32_16x16x32_bf16 v[88:91], v[162:165], v[178:181], v[88:91]
	v_mfma_f32_16x16x32_bf16 v[116:119], v[154:157], v[188:191], v[116:119]
	v_mfma_f32_16x16x32_bf16 v[84:87], v[162:165], v[188:191], v[84:87]
	v_mfma_f32_16x16x32_bf16 v[112:115], v[154:157], v[196:199], v[112:115]
	v_mfma_f32_16x16x32_bf16 v[80:83], v[162:165], v[196:199], v[80:83]
	v_mfma_f32_16x16x32_bf16 v[124:127], v[158:161], v[174:177], v[124:127]
	v_mfma_f32_16x16x32_bf16 v[92:95], v[166:169], v[174:177], v[92:95]
	v_mfma_f32_16x16x32_bf16 v[120:123], v[158:161], v[184:187], v[120:123]
	v_mfma_f32_16x16x32_bf16 v[88:91], v[166:169], v[184:187], v[88:91]
	v_mfma_f32_16x16x32_bf16 v[116:119], v[158:161], v[192:195], v[116:119]
	v_mfma_f32_16x16x32_bf16 v[84:87], v[166:169], v[192:195], v[84:87]
	v_mfma_f32_16x16x32_bf16 v[112:115], v[158:161], v[200:203], v[112:115]
	v_mfma_f32_16x16x32_bf16 v[80:83], v[166:169], v[200:203], v[80:83]
	s_setprio 0
	s_barrier
	s_add_i32 s18, 0, 0x1c000
	s_add_i32 s2, s2, s69
	v_add_u32_e32 v232, s18, v182
	s_mov_b32 m0, s2
	ds_read_b128 v[204:207], v232
	ds_read_b128 v[208:211], v232 offset:1024
	ds_read_b128 v[228:231], v232 offset:2048
	ds_read_b128 v[232:235], v232 offset:3072
	s_add_u32 s100, s0, 0x80
	s_addc_u32 s101, s1, 0
	global_load_lds_dwordx4 v140, s[100:101]
	s_add_i32 m0, s2, 0x2000
	s_nop 0
	global_load_lds_dwordx4 v132, s[100:101]
	s_barrier
	s_waitcnt lgkmcnt(0)
	s_setprio 1
	v_mfma_f32_16x16x32_bf16 v[60:63], v[204:207], v[170:173], v[60:63]
	v_mfma_f32_16x16x32_bf16 v[28:31], v[228:231], v[170:173], v[28:31]
	v_mfma_f32_16x16x32_bf16 v[56:59], v[204:207], v[178:181], v[56:59]
	v_mfma_f32_16x16x32_bf16 v[24:27], v[228:231], v[178:181], v[24:27]
	v_mfma_f32_16x16x32_bf16 v[52:55], v[204:207], v[188:191], v[52:55]
	v_mfma_f32_16x16x32_bf16 v[20:23], v[228:231], v[188:191], v[20:23]
	v_mfma_f32_16x16x32_bf16 v[48:51], v[204:207], v[196:199], v[48:51]
	v_mfma_f32_16x16x32_bf16 v[16:19], v[228:231], v[196:199], v[16:19]
	v_mfma_f32_16x16x32_bf16 v[60:63], v[208:211], v[174:177], v[60:63]
	v_mfma_f32_16x16x32_bf16 v[28:31], v[232:235], v[174:177], v[28:31]
	v_mfma_f32_16x16x32_bf16 v[56:59], v[208:211], v[184:187], v[56:59]
	v_mfma_f32_16x16x32_bf16 v[24:27], v[232:235], v[184:187], v[24:27]
	v_mfma_f32_16x16x32_bf16 v[52:55], v[208:211], v[192:195], v[52:55]
	v_mfma_f32_16x16x32_bf16 v[20:23], v[232:235], v[192:195], v[20:23]
	v_mfma_f32_16x16x32_bf16 v[48:51], v[208:211], v[200:203], v[48:51]
	v_mfma_f32_16x16x32_bf16 v[16:19], v[232:235], v[200:203], v[16:19]
	s_setprio 0
	s_mov_b32 m0, s77
	s_barrier
	ds_read_b128 v[170:173], v183 offset:49152
	ds_read_b128 v[174:177], v183 offset:50176
	ds_read_b128 v[178:181], v183 offset:51200
	ds_read_b128 v[184:187], v183 offset:52224
	ds_read_b128 v[188:191], v183 offset:53248
	ds_read_b128 v[192:195], v183 offset:54272
	ds_read_b128 v[196:199], v183 offset:55296
	ds_read_b128 v[200:203], v183 offset:56320
	s_add_u32 s100, s64, 0x80
	s_addc_u32 s101, s65, 0
	global_load_lds_dwordx4 v128, s[100:101]
	s_mov_b32 m0, s80
	s_nop 0
	global_load_lds_dwordx4 v130, s[100:101]
	s_barrier
	s_waitcnt lgkmcnt(0)
	s_setprio 1
	v_mfma_f32_16x16x32_bf16 v[108:111], v[154:157], v[170:173], v[108:111]
	v_mfma_f32_16x16x32_bf16 v[76:79], v[162:165], v[170:173], v[76:79]
	v_mfma_f32_16x16x32_bf16 v[104:107], v[154:157], v[178:181], v[104:107]
	v_mfma_f32_16x16x32_bf16 v[72:75], v[162:165], v[178:181], v[72:75]
	v_mfma_f32_16x16x32_bf16 v[100:103], v[154:157], v[188:191], v[100:103]
	v_mfma_f32_16x16x32_bf16 v[68:71], v[162:165], v[188:191], v[68:71]
	v_mfma_f32_16x16x32_bf16 v[96:99], v[154:157], v[196:199], v[96:99]
	v_mfma_f32_16x16x32_bf16 v[64:67], v[162:165], v[196:199], v[64:67]
	v_mfma_f32_16x16x32_bf16 v[108:111], v[158:161], v[174:177], v[108:111]
	v_mfma_f32_16x16x32_bf16 v[76:79], v[166:169], v[174:177], v[76:79]
	v_mfma_f32_16x16x32_bf16 v[104:107], v[158:161], v[184:187], v[104:107]
	v_mfma_f32_16x16x32_bf16 v[72:75], v[166:169], v[184:187], v[72:75]
	v_mfma_f32_16x16x32_bf16 v[100:103], v[158:161], v[192:195], v[100:103]
	v_mfma_f32_16x16x32_bf16 v[68:71], v[166:169], v[192:195], v[68:71]
	v_mfma_f32_16x16x32_bf16 v[96:99], v[158:161], v[200:203], v[96:99]
	v_mfma_f32_16x16x32_bf16 v[64:67], v[166:169], v[200:203], v[64:67]
	s_setprio 0
	s_barrier
	s_add_u32 s0, s0, 0x100080
	s_addc_u32 s1, s1, 0
	s_add_i32 s2, s18, s69
	s_mov_b32 m0, s2
	s_nop 0
	global_load_lds_dwordx4 v140, s[0:1]
	s_add_i32 m0, s2, 0x2000
	s_nop 0
	global_load_lds_dwordx4 v132, s[0:1]
	s_waitcnt vmcnt(6)
	s_barrier
	s_setprio 1
	v_mfma_f32_16x16x32_bf16 v[44:47], v[204:207], v[170:173], v[44:47]
	v_mfma_f32_16x16x32_bf16 v[12:15], v[228:231], v[170:173], v[12:15]
	v_mfma_f32_16x16x32_bf16 v[40:43], v[204:207], v[178:181], v[40:43]
	v_mfma_f32_16x16x32_bf16 v[8:11], v[228:231], v[178:181], v[8:11]
	v_mfma_f32_16x16x32_bf16 v[36:39], v[204:207], v[188:191], v[36:39]
	v_mfma_f32_16x16x32_bf16 v[4:7], v[228:231], v[188:191], v[4:7]
	v_mfma_f32_16x16x32_bf16 v[32:35], v[204:207], v[196:199], v[32:35]
	v_mfma_f32_16x16x32_bf16 v[0:3], v[228:231], v[196:199], v[0:3]
	v_mfma_f32_16x16x32_bf16 v[44:47], v[208:211], v[174:177], v[44:47]
	v_mfma_f32_16x16x32_bf16 v[12:15], v[232:235], v[174:177], v[12:15]
	v_mfma_f32_16x16x32_bf16 v[40:43], v[208:211], v[184:187], v[40:43]
	v_mfma_f32_16x16x32_bf16 v[8:11], v[232:235], v[184:187], v[8:11]
	v_mfma_f32_16x16x32_bf16 v[36:39], v[208:211], v[192:195], v[36:39]
	v_mfma_f32_16x16x32_bf16 v[4:7], v[232:235], v[192:195], v[4:7]
	v_mfma_f32_16x16x32_bf16 v[32:35], v[208:211], v[200:203], v[32:35]
	v_mfma_f32_16x16x32_bf16 v[0:3], v[232:235], v[200:203], v[0:3]
	s_setprio 0
	s_add_i32 s15, s15, 2
	s_add_u32 s11, s11, 0x100
	s_addc_u32 s13, s13, 0
	s_add_u32 s8, s8, 0x100
	s_addc_u32 s9, s9, 0
	s_cmp_gt_u32 s15, 29
	s_barrier
	s_cbranch_scc0 .LBB0_35
	v_mbcnt_lo_u32_b32 v170, -1, 0
	v_mbcnt_hi_u32_b32 v170, -1, v170
	s_lshl_b32 s0, s16, 8
	v_ashrrev_i32_e32 v138, 2, v170
	v_and_b32_e32 v138, -4, v138
	s_or_b32 s0, s0, s75
	v_add_u32_e32 v138, s0, v138
	s_lshl_b32 s0, s88, 10
	s_ashr_i32 s1, s0, 31
	s_lshl_b32 s13, s88, 12
	s_lshl_b32 s15, s88, 11
	s_addk_i32 s13, 0x1000
	s_lshl_b64 s[0:1], s[0:1], 2
	v_and_or_b32 v154, v170, 15, s74
	s_add_u32 s0, s49, s0
	v_ashrrev_i32_e32 v139, 31, v138
	v_lshl_add_u32 v184, s10, 8, v154
	s_addc_u32 s1, s76, s1
	v_lshlrev_b64 v[172:173], 2, v[138:139]
	v_add_u32_e32 v156, s15, v184
	v_lshl_add_u64 v[160:161], s[0:1], 0, v[172:173]
	v_ashrrev_i32_e32 v157, 31, v156
	flat_load_dwordx4 v[162:165], v[160:161]
	v_lshlrev_b64 v[154:155], 12, v[156:157]
	v_lshl_add_u64 v[154:155], s[26:27], 0, v[154:155]
	v_lshl_add_u64 v[158:159], v[154:155], 0, v[172:173]
	flat_load_dwordx4 v[166:169], v[158:159] nt
	s_mov_b32 s0, 0x3c800000
	v_and_b32_e32 v155, 1, v170
	v_add_u32_e32 v156, s15, v156
	v_cmp_eq_u32_e64 s[8:9], 0, v155
	v_ashrrev_i32_e32 v157, 31, v156
	v_lshlrev_b64 v[156:157], 11, v[156:157]
	v_sub_u32_e32 v154, s13, v184
	v_lshl_add_u64 v[156:157], s[24:25], 0, v[156:157]
	v_cmp_ne_u32_e32 vcc, 0, v184
	v_lshl_add_u64 v[156:157], v[138:139], 1, v[156:157]
	s_waitcnt vmcnt(0) lgkmcnt(0)
	v_pk_mul_f32 v[164:165], v[164:165], s[0:1] op_sel_hi:[1,0]
	v_pk_mul_f32 v[162:163], v[162:163], s[0:1] op_sel_hi:[1,0]
	v_xor_b32_e32 v170, 0x80000000, v164
	v_xor_b32_e32 v171, 0x80000000, v165
	v_xor_b32_e32 v174, 0x80000000, v162
	v_xor_b32_e32 v175, 0x80000000, v163
	v_cndmask_b32_e64 v177, v171, v165, s[8:9]
	v_cndmask_b32_e64 v176, v170, v164, s[8:9]
	v_cndmask_b32_e64 v179, v175, v163, s[8:9]
	v_cndmask_b32_e64 v178, v174, v162, s[8:9]
	v_pk_add_f32 v[162:163], v[168:169], v[176:177]
	v_pk_add_f32 v[164:165], v[166:167], v[178:179]
	v_sub_f32_e32 v155, v162, v126
	v_sub_f32_e32 v167, v163, v127
	v_sub_f32_e32 v166, v164, v124
	v_cvt_pk_bf16_f32 v167, v155, v167
	v_ashrrev_i32_e32 v155, 31, v154
	v_sub_f32_e32 v168, v165, v125
	v_cvt_pk_bf16_f32 v166, v166, v168
	flat_store_dwordx2 v[156:157], v[166:167]
	s_and_saveexec_b64 s[0:1], vcc
	s_cbranch_execz .LBB0_38
	v_pk_add_f32 v[126:127], v[126:127], v[162:163]
	v_pk_add_f32 v[124:125], v[124:125], v[164:165]
	s_nop 0
	v_cvt_pk_bf16_f32 v124, v124, v125
	v_cvt_pk_bf16_f32 v125, v126, v127
	v_lshlrev_b64 v[126:127], 11, v[154:155]
	v_lshl_add_u64 v[126:127], s[24:25], 0, v[126:127]
	v_lshl_add_u64 v[126:127], v[138:139], 1, v[126:127]
	flat_store_dwordx2 v[126:127], v[124:125]

.LBB0_96:
	s_add_u32 s0, s40, 0xfffc0080
	s_addc_u32 s1, s41, -1
	s_add_i32 s2, 0, 0x10000
	v_add_u32_e32 v138, s2, v154
	ds_read_b128 v[156:159], v138
	ds_read_b128 v[160:163], v138 offset:1024
	ds_read_b128 v[164:167], v138 offset:2048
	ds_read_b128 v[168:171], v138 offset:3072
	s_cmp_eq_u32 s72, 12
	s_cselect_b32 s45, s13, s1
	s_cselect_b32 s44, s12, s0
	s_cselect_b32 s1, s15, s11
	s_cselect_b32 s0, s14, s9
	s_add_i32 m0, s17, 0xc000
	ds_read_b128 v[172:175], v155
	ds_read_b128 v[176:179], v155 offset:1024
	ds_read_b128 v[180:183], v155 offset:2048
	ds_read_b128 v[184:187], v155 offset:3072
	ds_read_b128 v[188:191], v155 offset:4096
	ds_read_b128 v[192:195], v155 offset:5120
	ds_read_b128 v[196:199], v155 offset:6144
	global_load_lds_dwordx4 v136, s[40:41]
	s_add_i32 m0, s17, 0xe000
	ds_read_b128 v[200:203], v155 offset:7168
	global_load_lds_dwordx4 v134, s[40:41]
	s_waitcnt lgkmcnt(8)
	s_barrier
	s_waitcnt lgkmcnt(0)
	s_setprio 1
	v_mfma_f32_16x16x32_bf16 v[124:127], v[156:159], v[172:175], v[124:127]
	v_mfma_f32_16x16x32_bf16 v[120:123], v[164:167], v[172:175], v[120:123]
	v_mfma_f32_16x16x32_bf16 v[116:119], v[156:159], v[180:183], v[116:119]
	v_mfma_f32_16x16x32_bf16 v[108:111], v[164:167], v[180:183], v[108:111]
	v_mfma_f32_16x16x32_bf16 v[100:103], v[156:159], v[188:191], v[100:103]
	v_mfma_f32_16x16x32_bf16 v[92:95], v[164:167], v[188:191], v[92:95]
	v_mfma_f32_16x16x32_bf16 v[84:87], v[156:159], v[196:199], v[84:87]
	v_mfma_f32_16x16x32_bf16 v[76:79], v[164:167], v[196:199], v[76:79]
	v_mfma_f32_16x16x32_bf16 v[124:127], v[160:163], v[176:179], v[124:127]
	v_mfma_f32_16x16x32_bf16 v[120:123], v[168:171], v[176:179], v[120:123]
	v_mfma_f32_16x16x32_bf16 v[116:119], v[160:163], v[184:187], v[116:119]
	v_mfma_f32_16x16x32_bf16 v[108:111], v[168:171], v[184:187], v[108:111]
	v_mfma_f32_16x16x32_bf16 v[100:103], v[160:163], v[192:195], v[100:103]
	v_mfma_f32_16x16x32_bf16 v[92:95], v[168:171], v[192:195], v[92:95]
	v_mfma_f32_16x16x32_bf16 v[84:87], v[160:163], v[200:203], v[84:87]
	v_mfma_f32_16x16x32_bf16 v[76:79], v[168:171], v[200:203], v[76:79]
	s_setprio 0
	s_barrier
	s_add_i32 s30, 0, 0x14000
	v_add_u32_e32 v138, s30, v154
	s_add_i32 s2, s2, s59
	ds_read_b128 v[204:207], v138
	ds_read_b128 v[208:211], v138 offset:1024
	ds_read_b128 v[228:231], v138 offset:2048
	s_mov_b32 m0, s2
	ds_read_b128 v[232:235], v138 offset:3072
	global_load_lds_dwordx4 v140, s[0:1]
	s_add_i32 m0, s2, 0x2000
	s_nop 0
	global_load_lds_dwordx4 v132, s[0:1]
	s_barrier
	s_waitcnt lgkmcnt(0)
	s_setprio 1
	v_mfma_f32_16x16x32_bf16 v[112:115], v[204:207], v[172:175], v[112:115]
	v_mfma_f32_16x16x32_bf16 v[104:107], v[228:231], v[172:175], v[104:107]
	v_mfma_f32_16x16x32_bf16 v[96:99], v[204:207], v[180:183], v[96:99]
	v_mfma_f32_16x16x32_bf16 v[88:91], v[228:231], v[180:183], v[88:91]
	v_mfma_f32_16x16x32_bf16 v[80:83], v[204:207], v[188:191], v[80:83]
	v_mfma_f32_16x16x32_bf16 v[72:75], v[228:231], v[188:191], v[72:75]
	v_mfma_f32_16x16x32_bf16 v[68:71], v[204:207], v[196:199], v[68:71]
	v_mfma_f32_16x16x32_bf16 v[64:67], v[228:231], v[196:199], v[64:67]
	v_mfma_f32_16x16x32_bf16 v[112:115], v[208:211], v[176:179], v[112:115]
	v_mfma_f32_16x16x32_bf16 v[104:107], v[232:235], v[176:179], v[104:107]
	v_mfma_f32_16x16x32_bf16 v[96:99], v[208:211], v[184:187], v[96:99]
	v_mfma_f32_16x16x32_bf16 v[88:91], v[232:235], v[184:187], v[88:91]
	v_mfma_f32_16x16x32_bf16 v[80:83], v[208:211], v[192:195], v[80:83]
	v_mfma_f32_16x16x32_bf16 v[72:75], v[232:235], v[192:195], v[72:75]
	v_mfma_f32_16x16x32_bf16 v[68:71], v[208:211], v[200:203], v[68:71]
	v_mfma_f32_16x16x32_bf16 v[64:67], v[232:235], v[200:203], v[64:67]
	s_setprio 0
	s_mov_b32 m0, s17
	s_barrier
	ds_read_b128 v[172:175], v155 offset:16384
	ds_read_b128 v[176:179], v155 offset:17408
	ds_read_b128 v[180:183], v155 offset:18432
	ds_read_b128 v[184:187], v155 offset:19456
	ds_read_b128 v[188:191], v155 offset:20480
	ds_read_b128 v[192:195], v155 offset:21504
	ds_read_b128 v[196:199], v155 offset:22528
	global_load_lds_dwordx4 v128, s[44:45]
	s_mov_b32 m0, s64
	ds_read_b128 v[200:203], v155 offset:23552
	global_load_lds_dwordx4 v130, s[44:45]
	s_barrier
	s_waitcnt lgkmcnt(0)
	s_setprio 1
	v_mfma_f32_16x16x32_bf16 v[60:63], v[156:159], v[172:175], v[60:63]
	v_mfma_f32_16x16x32_bf16 v[56:59], v[164:167], v[172:175], v[56:59]
	v_mfma_f32_16x16x32_bf16 v[52:55], v[156:159], v[180:183], v[52:55]
	v_mfma_f32_16x16x32_bf16 v[44:47], v[164:167], v[180:183], v[44:47]
	v_mfma_f32_16x16x32_bf16 v[36:39], v[156:159], v[188:191], v[36:39]
	v_mfma_f32_16x16x32_bf16 v[28:31], v[164:167], v[188:191], v[28:31]
	v_mfma_f32_16x16x32_bf16 v[20:23], v[156:159], v[196:199], v[20:23]
	v_mfma_f32_16x16x32_bf16 v[12:15], v[164:167], v[196:199], v[12:15]
	v_mfma_f32_16x16x32_bf16 v[60:63], v[160:163], v[176:179], v[60:63]
	v_mfma_f32_16x16x32_bf16 v[56:59], v[168:171], v[176:179], v[56:59]
	v_mfma_f32_16x16x32_bf16 v[52:55], v[160:163], v[184:187], v[52:55]
	v_mfma_f32_16x16x32_bf16 v[44:47], v[168:171], v[184:187], v[44:47]
	v_mfma_f32_16x16x32_bf16 v[36:39], v[160:163], v[192:195], v[36:39]
	v_mfma_f32_16x16x32_bf16 v[28:31], v[168:171], v[192:195], v[28:31]
	v_mfma_f32_16x16x32_bf16 v[20:23], v[160:163], v[200:203], v[20:23]
	v_mfma_f32_16x16x32_bf16 v[12:15], v[168:171], v[200:203], v[12:15]
	s_setprio 0
	s_barrier
	s_add_u32 s18, s0, 0x40000
	s_addc_u32 s19, s1, 0
	s_add_i32 s2, s30, s59
	s_mov_b32 m0, s2
	s_nop 0
	global_load_lds_dwordx4 v140, s[18:19]
	s_add_i32 m0, s2, 0x2000
	s_nop 0
	global_load_lds_dwordx4 v132, s[18:19]
	s_waitcnt vmcnt(6)
	s_barrier
	s_setprio 1
	v_mfma_f32_16x16x32_bf16 v[48:51], v[204:207], v[172:175], v[48:51]
	v_mfma_f32_16x16x32_bf16 v[40:43], v[228:231], v[172:175], v[40:43]
	v_mfma_f32_16x16x32_bf16 v[32:35], v[204:207], v[180:183], v[32:35]
	v_mfma_f32_16x16x32_bf16 v[24:27], v[228:231], v[180:183], v[24:27]
	v_mfma_f32_16x16x32_bf16 v[16:19], v[204:207], v[188:191], v[16:19]
	v_mfma_f32_16x16x32_bf16 v[8:11], v[228:231], v[188:191], v[8:11]
	v_mfma_f32_16x16x32_bf16 v[4:7], v[204:207], v[196:199], v[4:7]
	v_mfma_f32_16x16x32_bf16 v[0:3], v[228:231], v[196:199], v[0:3]
	v_mfma_f32_16x16x32_bf16 v[48:51], v[208:211], v[176:179], v[48:51]
	v_mfma_f32_16x16x32_bf16 v[40:43], v[232:235], v[176:179], v[40:43]
	v_mfma_f32_16x16x32_bf16 v[32:35], v[208:211], v[184:187], v[32:35]
	v_mfma_f32_16x16x32_bf16 v[24:27], v[232:235], v[184:187], v[24:27]
	v_mfma_f32_16x16x32_bf16 v[16:19], v[208:211], v[192:195], v[16:19]
	v_mfma_f32_16x16x32_bf16 v[8:11], v[232:235], v[192:195], v[8:11]
	v_mfma_f32_16x16x32_bf16 v[4:7], v[208:211], v[200:203], v[4:7]
	v_mfma_f32_16x16x32_bf16 v[0:3], v[232:235], v[200:203], v[0:3]
	s_setprio 0
	s_add_i32 s2, 0, 0x18000
	v_add_u32_e32 v168, s2, v154
	s_barrier
	ds_read_b128 v[156:159], v168
	ds_read_b128 v[160:163], v168 offset:1024
	ds_read_b128 v[164:167], v168 offset:2048
	ds_read_b128 v[168:171], v168 offset:3072
	s_add_u32 s18, s44, 0x40000
	s_addc_u32 s19, s45, 0
	s_mov_b32 m0, s65
	ds_read_b128 v[172:175], v155 offset:32768
	ds_read_b128 v[176:179], v155 offset:33792
	ds_read_b128 v[180:183], v155 offset:34816
	ds_read_b128 v[184:187], v155 offset:35840
	ds_read_b128 v[188:191], v155 offset:36864
	ds_read_b128 v[192:195], v155 offset:37888
	ds_read_b128 v[196:199], v155 offset:38912
	global_load_lds_dwordx4 v128, s[18:19]
	s_mov_b32 m0, s66
	ds_read_b128 v[200:203], v155 offset:39936
	global_load_lds_dwordx4 v130, s[18:19]
	s_waitcnt lgkmcnt(8)
	s_barrier
	s_waitcnt lgkmcnt(0)
	s_setprio 1
	v_mfma_f32_16x16x32_bf16 v[124:127], v[156:159], v[172:175], v[124:127]
	v_mfma_f32_16x16x32_bf16 v[120:123], v[164:167], v[172:175], v[120:123]
	v_mfma_f32_16x16x32_bf16 v[116:119], v[156:159], v[180:183], v[116:119]
	v_mfma_f32_16x16x32_bf16 v[108:111], v[164:167], v[180:183], v[108:111]
	v_mfma_f32_16x16x32_bf16 v[100:103], v[156:159], v[188:191], v[100:103]
	v_mfma_f32_16x16x32_bf16 v[92:95], v[164:167], v[188:191], v[92:95]
	v_mfma_f32_16x16x32_bf16 v[84:87], v[156:159], v[196:199], v[84:87]
	v_mfma_f32_16x16x32_bf16 v[76:79], v[164:167], v[196:199], v[76:79]
	v_mfma_f32_16x16x32_bf16 v[124:127], v[160:163], v[176:179], v[124:127]
	v_mfma_f32_16x16x32_bf16 v[120:123], v[168:171], v[176:179], v[120:123]
	v_mfma_f32_16x16x32_bf16 v[116:119], v[160:163], v[184:187], v[116:119]
	v_mfma_f32_16x16x32_bf16 v[108:111], v[168:171], v[184:187], v[108:111]
	v_mfma_f32_16x16x32_bf16 v[100:103], v[160:163], v[192:195], v[100:103]
	v_mfma_f32_16x16x32_bf16 v[92:95], v[168:171], v[192:195], v[92:95]
	v_mfma_f32_16x16x32_bf16 v[84:87], v[160:163], v[200:203], v[84:87]
	v_mfma_f32_16x16x32_bf16 v[76:79], v[168:171], v[200:203], v[76:79]
	s_setprio 0
	s_barrier
	s_add_i32 s18, 0, 0x1c000
	s_add_i32 s2, s2, s59
	v_add_u32_e32 v232, s18, v154
	s_mov_b32 m0, s2
	ds_read_b128 v[204:207], v232
	ds_read_b128 v[208:211], v232 offset:1024
	ds_read_b128 v[228:231], v232 offset:2048
	ds_read_b128 v[232:235], v232 offset:3072
	s_add_u32 s100, s0, 0x80
	s_addc_u32 s101, s1, 0
	global_load_lds_dwordx4 v140, s[100:101]
	s_add_i32 m0, s2, 0x2000
	s_nop 0
	global_load_lds_dwordx4 v132, s[100:101]
	s_barrier
	s_waitcnt lgkmcnt(0)
	s_setprio 1
	v_mfma_f32_16x16x32_bf16 v[112:115], v[204:207], v[172:175], v[112:115]
	v_mfma_f32_16x16x32_bf16 v[104:107], v[228:231], v[172:175], v[104:107]
	v_mfma_f32_16x16x32_bf16 v[96:99], v[204:207], v[180:183], v[96:99]
	v_mfma_f32_16x16x32_bf16 v[88:91], v[228:231], v[180:183], v[88:91]
	v_mfma_f32_16x16x32_bf16 v[80:83], v[204:207], v[188:191], v[80:83]
	v_mfma_f32_16x16x32_bf16 v[72:75], v[228:231], v[188:191], v[72:75]
	v_mfma_f32_16x16x32_bf16 v[68:71], v[204:207], v[196:199], v[68:71]
	v_mfma_f32_16x16x32_bf16 v[64:67], v[228:231], v[196:199], v[64:67]
	v_mfma_f32_16x16x32_bf16 v[112:115], v[208:211], v[176:179], v[112:115]
	v_mfma_f32_16x16x32_bf16 v[104:107], v[232:235], v[176:179], v[104:107]
	v_mfma_f32_16x16x32_bf16 v[96:99], v[208:211], v[184:187], v[96:99]
	v_mfma_f32_16x16x32_bf16 v[88:91], v[232:235], v[184:187], v[88:91]
	v_mfma_f32_16x16x32_bf16 v[80:83], v[208:211], v[192:195], v[80:83]
	v_mfma_f32_16x16x32_bf16 v[72:75], v[232:235], v[192:195], v[72:75]
	v_mfma_f32_16x16x32_bf16 v[68:71], v[208:211], v[200:203], v[68:71]
	v_mfma_f32_16x16x32_bf16 v[64:67], v[232:235], v[200:203], v[64:67]
	s_setprio 0
	s_mov_b32 m0, s69
	s_barrier
	ds_read_b128 v[172:175], v155 offset:49152
	ds_read_b128 v[176:179], v155 offset:50176
	ds_read_b128 v[180:183], v155 offset:51200
	ds_read_b128 v[184:187], v155 offset:52224
	ds_read_b128 v[188:191], v155 offset:53248
	ds_read_b128 v[192:195], v155 offset:54272
	ds_read_b128 v[196:199], v155 offset:55296
	ds_read_b128 v[200:203], v155 offset:56320
	s_add_u32 s100, s44, 0x80
	s_addc_u32 s101, s45, 0
	global_load_lds_dwordx4 v128, s[100:101]
	s_mov_b32 m0, s71
	s_nop 0
	global_load_lds_dwordx4 v130, s[100:101]
	s_barrier
	s_waitcnt lgkmcnt(0)
	s_setprio 1
	v_mfma_f32_16x16x32_bf16 v[60:63], v[156:159], v[172:175], v[60:63]
	v_mfma_f32_16x16x32_bf16 v[56:59], v[164:167], v[172:175], v[56:59]
	v_mfma_f32_16x16x32_bf16 v[52:55], v[156:159], v[180:183], v[52:55]
	v_mfma_f32_16x16x32_bf16 v[44:47], v[164:167], v[180:183], v[44:47]
	v_mfma_f32_16x16x32_bf16 v[36:39], v[156:159], v[188:191], v[36:39]
	v_mfma_f32_16x16x32_bf16 v[28:31], v[164:167], v[188:191], v[28:31]
	v_mfma_f32_16x16x32_bf16 v[20:23], v[156:159], v[196:199], v[20:23]
	v_mfma_f32_16x16x32_bf16 v[12:15], v[164:167], v[196:199], v[12:15]
	v_mfma_f32_16x16x32_bf16 v[60:63], v[160:163], v[176:179], v[60:63]
	v_mfma_f32_16x16x32_bf16 v[56:59], v[168:171], v[176:179], v[56:59]
	v_mfma_f32_16x16x32_bf16 v[52:55], v[160:163], v[184:187], v[52:55]
	v_mfma_f32_16x16x32_bf16 v[44:47], v[168:171], v[184:187], v[44:47]
	v_mfma_f32_16x16x32_bf16 v[36:39], v[160:163], v[192:195], v[36:39]
	v_mfma_f32_16x16x32_bf16 v[28:31], v[168:171], v[192:195], v[28:31]
	v_mfma_f32_16x16x32_bf16 v[20:23], v[160:163], v[200:203], v[20:23]
	v_mfma_f32_16x16x32_bf16 v[12:15], v[168:171], v[200:203], v[12:15]
	s_setprio 0
	s_barrier
	s_add_u32 s0, s0, 0x40080
	s_addc_u32 s1, s1, 0
	s_add_i32 s2, s18, s59
	s_mov_b32 m0, s2
	s_nop 0
	global_load_lds_dwordx4 v140, s[0:1]
	s_add_i32 m0, s2, 0x2000
	s_nop 0
	global_load_lds_dwordx4 v132, s[0:1]
	s_waitcnt vmcnt(6)
	s_barrier
	s_setprio 1
	v_mfma_f32_16x16x32_bf16 v[48:51], v[204:207], v[172:175], v[48:51]
	v_mfma_f32_16x16x32_bf16 v[40:43], v[228:231], v[172:175], v[40:43]
	v_mfma_f32_16x16x32_bf16 v[32:35], v[204:207], v[180:183], v[32:35]
	v_mfma_f32_16x16x32_bf16 v[24:27], v[228:231], v[180:183], v[24:27]
	v_mfma_f32_16x16x32_bf16 v[16:19], v[204:207], v[188:191], v[16:19]
	v_mfma_f32_16x16x32_bf16 v[8:11], v[228:231], v[188:191], v[8:11]
	v_mfma_f32_16x16x32_bf16 v[4:7], v[204:207], v[196:199], v[4:7]
	v_mfma_f32_16x16x32_bf16 v[0:3], v[228:231], v[196:199], v[0:3]
	v_mfma_f32_16x16x32_bf16 v[48:51], v[208:211], v[176:179], v[48:51]
	v_mfma_f32_16x16x32_bf16 v[40:43], v[232:235], v[176:179], v[40:43]
	v_mfma_f32_16x16x32_bf16 v[32:35], v[208:211], v[184:187], v[32:35]
	v_mfma_f32_16x16x32_bf16 v[24:27], v[232:235], v[184:187], v[24:27]
	v_mfma_f32_16x16x32_bf16 v[16:19], v[208:211], v[192:195], v[16:19]
	v_mfma_f32_16x16x32_bf16 v[8:11], v[232:235], v[192:195], v[8:11]
	v_mfma_f32_16x16x32_bf16 v[4:7], v[208:211], v[200:203], v[4:7]
	v_mfma_f32_16x16x32_bf16 v[0:3], v[232:235], v[200:203], v[0:3]
	s_setprio 0
	s_add_i32 s72, s72, 2
	s_add_u32 s9, s9, 0x100
	s_addc_u32 s11, s11, 0
	s_add_u32 s40, s40, 0x100
	s_addc_u32 s41, s41, 0
	s_cmp_gt_u32 s72, 13
	s_barrier
	s_cbranch_scc0 .LBB0_96
	s_lshl_b32 s0, s16, 8
	v_mbcnt_lo_u32_b32 v139, -1, 0
	v_mbcnt_hi_u32_b32 v139, -1, v139
	s_lshl_b32 s1, s21, 8
	v_ashrrev_i32_e32 v138, 1, v139
	s_add_i32 s0, s0, s67
	v_and_b32_e32 v138, -8, v138
	s_or_b32 s1, s1, s68
	v_and_or_b32 v156, v139, 15, s0
	v_add_u32_e32 v138, s1, v138
	v_ashrrev_i32_e32 v157, 31, v156
	v_ashrrev_i32_e32 v139, 31, v138
	v_lshlrev_b64 v[158:159], 11, v[156:157]
	v_lshl_add_u64 v[158:159], s[26:27], 0, v[158:159]
	v_lshlrev_b64 v[160:161], 1, v[138:139]
	v_lshl_add_u64 v[138:139], v[158:159], 0, v[160:161]
	v_cvt_pk_bf16_f32 v60, v60, v61
	v_cvt_pk_bf16_f32 v61, v62, v63
	v_cvt_pk_bf16_f32 v62, v56, v57
	v_add_co_u32_e32 v56, vcc, s31, v138
	v_cvt_pk_bf16_f32 v112, v112, v113
	v_cvt_pk_bf16_f32 v113, v114, v115
	v_cvt_pk_bf16_f32 v114, v104, v105
	v_or_b32_e32 v104, 16, v156
	s_nop 0
	v_addc_co_u32_e32 v57, vcc, 0, v139, vcc
	v_cvt_pk_bf16_f32 v48, v48, v49
	v_cvt_pk_bf16_f32 v49, v50, v51
	v_cvt_pk_bf16_f32 v51, v42, v43
	v_cvt_pk_bf16_f32 v42, v44, v45
	v_add_co_u32_e32 v44, vcc, s42, v138
	v_ashrrev_i32_e32 v105, 31, v104
	v_cvt_pk_bf16_f32 v96, v96, v97
	v_cvt_pk_bf16_f32 v97, v98, v99
	v_cvt_pk_bf16_f32 v98, v88, v89
	v_or_b32_e32 v88, 32, v156
	v_addc_co_u32_e32 v45, vcc, 0, v139, vcc
	v_lshlrev_b64 v[104:105], 11, v[104:105]
	v_ashrrev_i32_e32 v89, 31, v88
	v_cvt_pk_bf16_f32 v80, v80, v81
	v_cvt_pk_bf16_f32 v81, v82, v83
	v_cvt_pk_bf16_f32 v82, v72, v73
	v_or_b32_e32 v72, 48, v156
	s_mov_b64 s[0:1], 0x40000
	v_cvt_pk_bf16_f32 v32, v32, v33
	v_cvt_pk_bf16_f32 v33, v34, v35
	v_cvt_pk_bf16_f32 v35, v26, v27
	v_cvt_pk_bf16_f32 v26, v28, v29
	v_add_co_u32_e32 v28, vcc, s43, v138
	v_lshl_add_u64 v[104:105], s[26:27], 0, v[104:105]
	v_lshlrev_b64 v[88:89], 11, v[88:89]
	v_ashrrev_i32_e32 v73, 31, v72
	v_cvt_pk_bf16_f32 v68, v68, v69
	v_cvt_pk_bf16_f32 v69, v70, v71
	v_cvt_pk_bf16_f32 v70, v64, v65
	v_lshl_add_u64 v[64:65], v[138:139], 0, s[0:1]
	s_mov_b64 s[0:1], 0x48000
	v_addc_co_u32_e32 v29, vcc, 0, v139, vcc
	v_cvt_pk_bf16_f32 v115, v106, v107
	flat_store_dwordx4 v[138:139], v[112:115] offset:256
	v_lshl_add_u64 v[88:89], s[26:27], 0, v[88:89]
	v_lshlrev_b64 v[72:73], 11, v[72:73]
	v_lshl_add_u64 v[112:113], v[104:105], 0, v[160:161]
	v_cvt_pk_bf16_f32 v50, v40, v41
	flat_store_dwordx4 v[64:65], v[48:51] offset:256
	v_cvt_pk_bf16_f32 v16, v16, v17
	v_cvt_pk_bf16_f32 v17, v18, v19
	v_cvt_pk_bf16_f32 v19, v10, v11
	v_cvt_pk_bf16_f32 v10, v12, v13
	v_add_co_u32_e32 v12, vcc, s47, v138
	s_nop 0
	v_lshl_add_u64 v[48:49], v[138:139], 0, s[0:1]
	s_mov_b64 s[0:1], 0x50000
	v_cvt_pk_bf16_f32 v99, v90, v91
	flat_store_dwordx4 v[112:113], v[96:99] offset:256
	v_lshl_add_u64 v[72:73], s[26:27], 0, v[72:73]
	v_cvt_pk_bf16_f32 v34, v24, v25
	flat_store_dwordx4 v[48:49], v[32:35] offset:256
	v_lshl_add_u64 v[96:97], v[88:89], 0, v[160:161]
	v_addc_co_u32_e32 v13, vcc, 0, v139, vcc
	v_lshl_add_u64 v[32:33], v[138:139], 0, s[0:1]
	s_mov_b64 s[0:1], 0x58000
	v_cvt_pk_bf16_f32 v83, v74, v75
	flat_store_dwordx4 v[96:97], v[80:83] offset:256
	v_cvt_pk_bf16_f32 v18, v8, v9
	flat_store_dwordx4 v[32:33], v[16:19] offset:256
	s_and_b64 vcc, exec, s[6:7]
	v_lshl_add_u64 v[80:81], v[72:73], 0, v[160:161]
	v_lshl_add_u64 v[16:17], v[138:139], 0, s[0:1]
	s_mov_b32 s21, s10
	s_mov_b32 s16, s8
	s_mov_b64 s[40:41], s[14:15]
	s_mov_b64 s[0:1], s[12:13]
	v_cvt_pk_bf16_f32 v124, v124, v125
	v_cvt_pk_bf16_f32 v125, v126, v127
	v_cvt_pk_bf16_f32 v126, v120, v121
	v_cvt_pk_bf16_f32 v127, v122, v123
	flat_store_dwordx4 v[138:139], v[124:127]
	v_cvt_pk_bf16_f32 v104, v116, v117
	v_cvt_pk_bf16_f32 v105, v118, v119
	v_cvt_pk_bf16_f32 v106, v108, v109
	v_cvt_pk_bf16_f32 v107, v110, v111
	flat_store_dwordx4 v[112:113], v[104:107]
	v_cvt_pk_bf16_f32 v88, v100, v101
	v_cvt_pk_bf16_f32 v89, v102, v103
	v_cvt_pk_bf16_f32 v90, v92, v93
	v_cvt_pk_bf16_f32 v91, v94, v95
	flat_store_dwordx4 v[96:97], v[88:91]
	v_cvt_pk_bf16_f32 v72, v84, v85
	v_cvt_pk_bf16_f32 v73, v86, v87
	v_cvt_pk_bf16_f32 v74, v76, v77
	v_cvt_pk_bf16_f32 v75, v78, v79
	flat_store_dwordx4 v[80:81], v[72:75]
	v_cvt_pk_bf16_f32 v71, v66, v67
	flat_store_dwordx4 v[80:81], v[68:71] offset:256
	v_cvt_pk_bf16_f32 v63, v58, v59
	flat_store_dwordx4 v[56:57], v[60:63]
	v_cvt_pk_bf16_f32 v40, v52, v53
	v_cvt_pk_bf16_f32 v41, v54, v55
	v_cvt_pk_bf16_f32 v43, v46, v47
	flat_store_dwordx4 v[44:45], v[40:43]
	v_cvt_pk_bf16_f32 v24, v36, v37
	v_cvt_pk_bf16_f32 v25, v38, v39
	v_cvt_pk_bf16_f32 v27, v30, v31
	flat_store_dwordx4 v[28:29], v[24:27]
	v_cvt_pk_bf16_f32 v8, v20, v21
	v_cvt_pk_bf16_f32 v9, v22, v23
	v_cvt_pk_bf16_f32 v11, v14, v15
	flat_store_dwordx4 v[12:13], v[8:11]
	v_cvt_pk_bf16_f32 v4, v4, v5
	v_cvt_pk_bf16_f32 v5, v6, v7
	v_cvt_pk_bf16_f32 v6, v0, v1
	v_cvt_pk_bf16_f32 v7, v2, v3
	flat_store_dwordx4 v[16:17], v[4:7] offset:256
	s_cbranch_vccz .LBB0_89
	s_waitcnt vmcnt(0)
	s_cmpk_gt_u32 s51, 0xff
	s_cbranch_scc1 .LBB0_100
	s_barrier

.LBB0_126:
	s_add_u32 s0, s8, 0xfff80080
	s_addc_u32 s1, s9, -1
	s_add_i32 s2, 0, 0x10000
	v_add_u32_e32 v138, s2, v238
	ds_read_b128 v[154:157], v138
	ds_read_b128 v[158:161], v138 offset:1024
	ds_read_b128 v[162:165], v138 offset:2048
	ds_read_b128 v[166:169], v138 offset:3072
	s_cmp_eq_u32 s20, 28
	s_cselect_b32 s11, s45, s1
	s_cselect_b32 s10, s44, s0
	s_cselect_b32 s1, s67, s15
	s_cselect_b32 s0, s66, s13
	s_add_i32 m0, s17, 0xc000
	ds_read_b128 v[170:173], v239
	ds_read_b128 v[174:177], v239 offset:1024
	ds_read_b128 v[178:181], v239 offset:2048
	ds_read_b128 v[182:185], v239 offset:3072
	ds_read_b128 v[186:189], v239 offset:4096
	ds_read_b128 v[190:193], v239 offset:5120
	ds_read_b128 v[194:197], v239 offset:6144
	global_load_lds_dwordx4 v136, s[8:9]
	s_add_i32 m0, s17, 0xe000
	ds_read_b128 v[198:201], v239 offset:7168
	global_load_lds_dwordx4 v134, s[8:9]
	s_waitcnt lgkmcnt(8)
	s_barrier
	s_waitcnt lgkmcnt(0)
	s_setprio 1
	v_mfma_f32_16x16x32_bf16 v[124:127], v[154:157], v[170:173], v[124:127]
	v_mfma_f32_16x16x32_bf16 v[120:123], v[162:165], v[170:173], v[120:123]
	v_mfma_f32_16x16x32_bf16 v[116:119], v[154:157], v[178:181], v[116:119]
	v_mfma_f32_16x16x32_bf16 v[112:115], v[162:165], v[178:181], v[112:115]
	v_mfma_f32_16x16x32_bf16 v[104:107], v[154:157], v[186:189], v[104:107]
	v_mfma_f32_16x16x32_bf16 v[96:99], v[162:165], v[186:189], v[96:99]
	v_mfma_f32_16x16x32_bf16 v[88:91], v[154:157], v[194:197], v[88:91]
	v_mfma_f32_16x16x32_bf16 v[80:83], v[162:165], v[194:197], v[80:83]
	v_mfma_f32_16x16x32_bf16 v[124:127], v[158:161], v[174:177], v[124:127]
	v_mfma_f32_16x16x32_bf16 v[120:123], v[166:169], v[174:177], v[120:123]
	v_mfma_f32_16x16x32_bf16 v[116:119], v[158:161], v[182:185], v[116:119]
	v_mfma_f32_16x16x32_bf16 v[112:115], v[166:169], v[182:185], v[112:115]
	v_mfma_f32_16x16x32_bf16 v[104:107], v[158:161], v[190:193], v[104:107]
	v_mfma_f32_16x16x32_bf16 v[96:99], v[166:169], v[190:193], v[96:99]
	v_mfma_f32_16x16x32_bf16 v[88:91], v[158:161], v[198:201], v[88:91]
	v_mfma_f32_16x16x32_bf16 v[80:83], v[166:169], v[198:201], v[80:83]
	s_setprio 0
	s_barrier
	s_add_i32 s21, 0, 0x14000
	v_add_u32_e32 v138, s21, v238
	s_add_i32 s2, s2, s58
	ds_read_b128 v[202:205], v138
	ds_read_b128 v[206:209], v138 offset:1024
	ds_read_b128 v[240:243], v138 offset:2048
	s_mov_b32 m0, s2
	ds_read_b128 v[244:247], v138 offset:3072
	global_load_lds_dwordx4 v140, s[0:1]
	s_add_i32 m0, s2, 0x2000
	s_nop 0
	global_load_lds_dwordx4 v132, s[0:1]
	s_barrier
	s_waitcnt lgkmcnt(0)
	s_setprio 1
	v_mfma_f32_16x16x32_bf16 v[108:111], v[202:205], v[170:173], v[108:111]
	v_mfma_f32_16x16x32_bf16 v[100:103], v[240:243], v[170:173], v[100:103]
	v_mfma_f32_16x16x32_bf16 v[92:95], v[202:205], v[178:181], v[92:95]
	v_mfma_f32_16x16x32_bf16 v[84:87], v[240:243], v[178:181], v[84:87]
	v_mfma_f32_16x16x32_bf16 v[76:79], v[202:205], v[186:189], v[76:79]
	v_mfma_f32_16x16x32_bf16 v[72:75], v[240:243], v[186:189], v[72:75]
	v_mfma_f32_16x16x32_bf16 v[68:71], v[202:205], v[194:197], v[68:71]
	v_mfma_f32_16x16x32_bf16 v[64:67], v[240:243], v[194:197], v[64:67]
	v_mfma_f32_16x16x32_bf16 v[108:111], v[206:209], v[174:177], v[108:111]
	v_mfma_f32_16x16x32_bf16 v[100:103], v[244:247], v[174:177], v[100:103]
	v_mfma_f32_16x16x32_bf16 v[92:95], v[206:209], v[182:185], v[92:95]
	v_mfma_f32_16x16x32_bf16 v[84:87], v[244:247], v[182:185], v[84:87]
	v_mfma_f32_16x16x32_bf16 v[76:79], v[206:209], v[190:193], v[76:79]
	v_mfma_f32_16x16x32_bf16 v[72:75], v[244:247], v[190:193], v[72:75]
	v_mfma_f32_16x16x32_bf16 v[68:71], v[206:209], v[198:201], v[68:71]
	v_mfma_f32_16x16x32_bf16 v[64:67], v[244:247], v[198:201], v[64:67]
	s_setprio 0
	s_mov_b32 m0, s17
	v_lshl_add_u64 v[248:249], s[10:11], 0, v[128:129]
	s_barrier
	ds_read_b128 v[170:173], v239 offset:16384
	ds_read_b128 v[174:177], v239 offset:17408
	ds_read_b128 v[178:181], v239 offset:18432
	ds_read_b128 v[182:185], v239 offset:19456
	ds_read_b128 v[186:189], v239 offset:20480
	ds_read_b128 v[190:193], v239 offset:21504
	ds_read_b128 v[194:197], v239 offset:22528
	ds_read_b128 v[198:201], v239 offset:23552
	global_load_lds_dwordx4 v128, s[10:11]
	v_lshl_add_u64 v[250:251], s[10:11], 0, v[130:131]
	s_mov_b32 m0, s59
	s_nop 0
	global_load_lds_dwordx4 v130, s[10:11]
	s_barrier
	s_waitcnt lgkmcnt(0)
	s_setprio 1
	v_mfma_f32_16x16x32_bf16 v[60:63], v[154:157], v[170:173], v[60:63]
	v_mfma_f32_16x16x32_bf16 v[56:59], v[162:165], v[170:173], v[56:59]
	v_mfma_f32_16x16x32_bf16 v[52:55], v[154:157], v[178:181], v[52:55]
	v_mfma_f32_16x16x32_bf16 v[48:51], v[162:165], v[178:181], v[48:51]
	v_mfma_f32_16x16x32_bf16 v[36:39], v[154:157], v[186:189], v[36:39]
	v_mfma_f32_16x16x32_bf16 v[32:35], v[162:165], v[186:189], v[32:35]
	v_mfma_f32_16x16x32_bf16 v[20:23], v[154:157], v[194:197], v[20:23]
	v_mfma_f32_16x16x32_bf16 v[16:19], v[162:165], v[194:197], v[16:19]
	v_mfma_f32_16x16x32_bf16 v[60:63], v[158:161], v[174:177], v[60:63]
	v_mfma_f32_16x16x32_bf16 v[56:59], v[166:169], v[174:177], v[56:59]
	v_mfma_f32_16x16x32_bf16 v[52:55], v[158:161], v[182:185], v[52:55]
	v_mfma_f32_16x16x32_bf16 v[48:51], v[166:169], v[182:185], v[48:51]
	v_mfma_f32_16x16x32_bf16 v[36:39], v[158:161], v[190:193], v[36:39]
	v_mfma_f32_16x16x32_bf16 v[32:35], v[166:169], v[190:193], v[32:35]
	v_mfma_f32_16x16x32_bf16 v[20:23], v[158:161], v[198:201], v[20:23]
	v_mfma_f32_16x16x32_bf16 v[16:19], v[166:169], v[198:201], v[16:19]
	s_setprio 0
	s_barrier
	s_add_u32 s18, s0, 0x100000
	s_addc_u32 s19, s1, 0
	s_add_i32 s2, s21, s58
	s_mov_b32 m0, s2
	s_nop 0
	global_load_lds_dwordx4 v140, s[18:19]
	s_add_i32 m0, s2, 0x2000
	s_nop 0
	global_load_lds_dwordx4 v132, s[18:19]
	s_waitcnt vmcnt(6)
	s_barrier
	s_setprio 1
	v_mfma_f32_16x16x32_bf16 v[44:47], v[202:205], v[170:173], v[44:47]
	v_mfma_f32_16x16x32_bf16 v[40:43], v[240:243], v[170:173], v[40:43]
	v_mfma_f32_16x16x32_bf16 v[28:31], v[202:205], v[178:181], v[28:31]
	v_mfma_f32_16x16x32_bf16 v[24:27], v[240:243], v[178:181], v[24:27]
	v_mfma_f32_16x16x32_bf16 v[12:15], v[202:205], v[186:189], v[12:15]
	v_mfma_f32_16x16x32_bf16 v[8:11], v[240:243], v[186:189], v[8:11]
	v_mfma_f32_16x16x32_bf16 v[4:7], v[202:205], v[194:197], v[4:7]
	v_mfma_f32_16x16x32_bf16 v[0:3], v[240:243], v[194:197], v[0:3]
	v_mfma_f32_16x16x32_bf16 v[44:47], v[206:209], v[174:177], v[44:47]
	v_mfma_f32_16x16x32_bf16 v[40:43], v[244:247], v[174:177], v[40:43]
	v_mfma_f32_16x16x32_bf16 v[28:31], v[206:209], v[182:185], v[28:31]
	v_mfma_f32_16x16x32_bf16 v[24:27], v[244:247], v[182:185], v[24:27]
	v_mfma_f32_16x16x32_bf16 v[12:15], v[206:209], v[190:193], v[12:15]
	v_mfma_f32_16x16x32_bf16 v[8:11], v[244:247], v[190:193], v[8:11]
	v_mfma_f32_16x16x32_bf16 v[4:7], v[206:209], v[198:201], v[4:7]
	v_mfma_f32_16x16x32_bf16 v[0:3], v[244:247], v[198:201], v[0:3]
	s_setprio 0
	s_add_i32 s2, 0, 0x18000
	v_add_u32_e32 v166, s2, v238
	s_barrier
	ds_read_b128 v[154:157], v166
	ds_read_b128 v[158:161], v166 offset:1024
	ds_read_b128 v[162:165], v166 offset:2048
	ds_read_b128 v[166:169], v166 offset:3072
	s_add_u32 s10, s10, 0x80000
	s_addc_u32 s11, s11, 0
	s_mov_b32 m0, s65
	ds_read_b128 v[170:173], v239 offset:32768
	ds_read_b128 v[174:177], v239 offset:33792
	ds_read_b128 v[178:181], v239 offset:34816
	ds_read_b128 v[182:185], v239 offset:35840
	ds_read_b128 v[186:189], v239 offset:36864
	ds_read_b128 v[190:193], v239 offset:37888
	ds_read_b128 v[194:197], v239 offset:38912
	global_load_lds_dwordx4 v128, s[10:11]
	s_mov_b32 m0, s72
	ds_read_b128 v[198:201], v239 offset:39936
	global_load_lds_dwordx4 v130, s[10:11]
	s_waitcnt lgkmcnt(8)
	s_barrier
	s_waitcnt lgkmcnt(0)
	s_setprio 1
	v_mfma_f32_16x16x32_bf16 v[124:127], v[154:157], v[170:173], v[124:127]
	v_mfma_f32_16x16x32_bf16 v[120:123], v[162:165], v[170:173], v[120:123]
	v_mfma_f32_16x16x32_bf16 v[116:119], v[154:157], v[178:181], v[116:119]
	v_mfma_f32_16x16x32_bf16 v[112:115], v[162:165], v[178:181], v[112:115]
	v_mfma_f32_16x16x32_bf16 v[104:107], v[154:157], v[186:189], v[104:107]
	v_mfma_f32_16x16x32_bf16 v[96:99], v[162:165], v[186:189], v[96:99]
	v_mfma_f32_16x16x32_bf16 v[88:91], v[154:157], v[194:197], v[88:91]
	v_mfma_f32_16x16x32_bf16 v[80:83], v[162:165], v[194:197], v[80:83]
	v_mfma_f32_16x16x32_bf16 v[124:127], v[158:161], v[174:177], v[124:127]
	v_mfma_f32_16x16x32_bf16 v[120:123], v[166:169], v[174:177], v[120:123]
	v_mfma_f32_16x16x32_bf16 v[116:119], v[158:161], v[182:185], v[116:119]
	v_mfma_f32_16x16x32_bf16 v[112:115], v[166:169], v[182:185], v[112:115]
	v_mfma_f32_16x16x32_bf16 v[104:107], v[158:161], v[190:193], v[104:107]
	v_mfma_f32_16x16x32_bf16 v[96:99], v[166:169], v[190:193], v[96:99]
	v_mfma_f32_16x16x32_bf16 v[88:91], v[158:161], v[198:201], v[88:91]
	v_mfma_f32_16x16x32_bf16 v[80:83], v[166:169], v[198:201], v[80:83]
	s_setprio 0
	s_barrier
	s_add_i32 s10, 0, 0x1c000
	s_add_i32 s2, s2, s58
	v_add_u32_e32 v244, s10, v238
	s_mov_b32 m0, s2
	ds_read_b128 v[202:205], v244
	ds_read_b128 v[206:209], v244 offset:1024
	ds_read_b128 v[240:243], v244 offset:2048
	ds_read_b128 v[244:247], v244 offset:3072
	s_add_u32 s100, s0, 0x80
	s_addc_u32 s101, s1, 0
	global_load_lds_dwordx4 v140, s[100:101]
	s_add_i32 m0, s2, 0x2000
	s_nop 0
	global_load_lds_dwordx4 v132, s[100:101]
	s_barrier
	s_waitcnt lgkmcnt(0)
	s_setprio 1
	v_mfma_f32_16x16x32_bf16 v[108:111], v[202:205], v[170:173], v[108:111]
	v_mfma_f32_16x16x32_bf16 v[100:103], v[240:243], v[170:173], v[100:103]
	v_mfma_f32_16x16x32_bf16 v[92:95], v[202:205], v[178:181], v[92:95]
	v_mfma_f32_16x16x32_bf16 v[84:87], v[240:243], v[178:181], v[84:87]
	v_mfma_f32_16x16x32_bf16 v[76:79], v[202:205], v[186:189], v[76:79]
	v_mfma_f32_16x16x32_bf16 v[72:75], v[240:243], v[186:189], v[72:75]
	v_mfma_f32_16x16x32_bf16 v[68:71], v[202:205], v[194:197], v[68:71]
	v_mfma_f32_16x16x32_bf16 v[64:67], v[240:243], v[194:197], v[64:67]
	v_mfma_f32_16x16x32_bf16 v[108:111], v[206:209], v[174:177], v[108:111]
	v_mfma_f32_16x16x32_bf16 v[100:103], v[244:247], v[174:177], v[100:103]
	v_mfma_f32_16x16x32_bf16 v[92:95], v[206:209], v[182:185], v[92:95]
	v_mfma_f32_16x16x32_bf16 v[84:87], v[244:247], v[182:185], v[84:87]
	v_mfma_f32_16x16x32_bf16 v[76:79], v[206:209], v[190:193], v[76:79]
	v_mfma_f32_16x16x32_bf16 v[72:75], v[244:247], v[190:193], v[72:75]
	v_mfma_f32_16x16x32_bf16 v[68:71], v[206:209], v[198:201], v[68:71]
	v_mfma_f32_16x16x32_bf16 v[64:67], v[244:247], v[198:201], v[64:67]
	s_setprio 0
	s_mov_b32 m0, s75
	v_lshl_add_u64 v[138:139], v[248:249], 0, s[82:83]
	s_barrier
	ds_read_b128 v[170:173], v239 offset:49152
	ds_read_b128 v[174:177], v239 offset:50176
	ds_read_b128 v[178:181], v239 offset:51200
	ds_read_b128 v[182:185], v239 offset:52224
	ds_read_b128 v[186:189], v239 offset:53248
	ds_read_b128 v[190:193], v239 offset:54272
	ds_read_b128 v[194:197], v239 offset:55296
	ds_read_b128 v[198:201], v239 offset:56320
	global_load_lds_dwordx4 v[138:139], off
	v_lshl_add_u64 v[138:139], v[250:251], 0, s[82:83]
	s_mov_b32 m0, s77
	s_nop 0
	global_load_lds_dwordx4 v[138:139], off
	s_barrier
	s_waitcnt lgkmcnt(0)
	s_setprio 1
	v_mfma_f32_16x16x32_bf16 v[60:63], v[154:157], v[170:173], v[60:63]
	v_mfma_f32_16x16x32_bf16 v[56:59], v[162:165], v[170:173], v[56:59]
	v_mfma_f32_16x16x32_bf16 v[52:55], v[154:157], v[178:181], v[52:55]
	v_mfma_f32_16x16x32_bf16 v[48:51], v[162:165], v[178:181], v[48:51]
	v_mfma_f32_16x16x32_bf16 v[36:39], v[154:157], v[186:189], v[36:39]
	v_mfma_f32_16x16x32_bf16 v[32:35], v[162:165], v[186:189], v[32:35]
	v_mfma_f32_16x16x32_bf16 v[20:23], v[154:157], v[194:197], v[20:23]
	v_mfma_f32_16x16x32_bf16 v[16:19], v[162:165], v[194:197], v[16:19]
	v_mfma_f32_16x16x32_bf16 v[60:63], v[158:161], v[174:177], v[60:63]
	v_mfma_f32_16x16x32_bf16 v[56:59], v[166:169], v[174:177], v[56:59]
	v_mfma_f32_16x16x32_bf16 v[52:55], v[158:161], v[182:185], v[52:55]
	v_mfma_f32_16x16x32_bf16 v[48:51], v[166:169], v[182:185], v[48:51]
	v_mfma_f32_16x16x32_bf16 v[36:39], v[158:161], v[190:193], v[36:39]
	v_mfma_f32_16x16x32_bf16 v[32:35], v[166:169], v[190:193], v[32:35]
	v_mfma_f32_16x16x32_bf16 v[20:23], v[158:161], v[198:201], v[20:23]
	v_mfma_f32_16x16x32_bf16 v[16:19], v[166:169], v[198:201], v[16:19]
	s_setprio 0
	s_barrier
	s_add_u32 s0, s0, 0x100080
	s_addc_u32 s1, s1, 0
	s_add_i32 s2, s10, s58
	s_mov_b32 m0, s2
	s_nop 0
	global_load_lds_dwordx4 v140, s[0:1]
	s_add_i32 m0, s2, 0x2000
	s_nop 0
	global_load_lds_dwordx4 v132, s[0:1]
	s_waitcnt vmcnt(6)
	s_barrier
	s_setprio 1
	v_mfma_f32_16x16x32_bf16 v[44:47], v[202:205], v[170:173], v[44:47]
	v_mfma_f32_16x16x32_bf16 v[40:43], v[240:243], v[170:173], v[40:43]
	v_mfma_f32_16x16x32_bf16 v[28:31], v[202:205], v[178:181], v[28:31]
	v_mfma_f32_16x16x32_bf16 v[24:27], v[240:243], v[178:181], v[24:27]
	v_mfma_f32_16x16x32_bf16 v[12:15], v[202:205], v[186:189], v[12:15]
	v_mfma_f32_16x16x32_bf16 v[8:11], v[240:243], v[186:189], v[8:11]
	v_mfma_f32_16x16x32_bf16 v[4:7], v[202:205], v[194:197], v[4:7]
	v_mfma_f32_16x16x32_bf16 v[0:3], v[240:243], v[194:197], v[0:3]
	v_mfma_f32_16x16x32_bf16 v[44:47], v[206:209], v[174:177], v[44:47]
	v_mfma_f32_16x16x32_bf16 v[40:43], v[244:247], v[174:177], v[40:43]
	v_mfma_f32_16x16x32_bf16 v[28:31], v[206:209], v[182:185], v[28:31]
	v_mfma_f32_16x16x32_bf16 v[24:27], v[244:247], v[182:185], v[24:27]
	v_mfma_f32_16x16x32_bf16 v[12:15], v[206:209], v[190:193], v[12:15]
	v_mfma_f32_16x16x32_bf16 v[8:11], v[244:247], v[190:193], v[8:11]
	v_mfma_f32_16x16x32_bf16 v[4:7], v[206:209], v[198:201], v[4:7]
	v_mfma_f32_16x16x32_bf16 v[0:3], v[244:247], v[198:201], v[0:3]
	s_setprio 0
	s_add_i32 s20, s20, 2
	s_add_u32 s13, s13, 0x100
	s_addc_u32 s15, s15, 0
	s_add_u32 s8, s8, 0x100
	s_addc_u32 s9, s9, 0
	s_cmp_gt_u32 s20, 29
	s_barrier
	s_cbranch_scc0 .LBB0_126
	v_mbcnt_lo_u32_b32 v154, -1, 0
	v_mbcnt_hi_u32_b32 v154, -1, v154
	s_lshl_b32 s0, s16, 8
	v_ashrrev_i32_e32 v138, 2, v154
	s_or_b32 s0, s0, s74
	v_and_b32_e32 v138, -4, v138
	s_lshl_b32 s13, s64, 8
	v_add_u32_e32 v138, s0, v138
	v_and_b32_e32 v240, 15, v154
	s_cmp_gt_i32 s71, 7
	s_mov_b64 s[0:1], -1
	v_ashrrev_i32_e32 v139, 31, v138
	s_cbranch_scc0 .LBB0_145
	s_add_i32 s0, s71, -8
	s_lshl_b32 s52, s0, 10
	s_lshl_b32 s15, s0, 12
	s_lshl_b32 s16, s0, 11
	s_addk_i32 s15, 0x1000
	s_lshl_b64 s[0:1], s[52:53], 2
	v_or_b32_e32 v155, s73, v240
	s_add_u32 s0, s49, s0
	v_add_u32_e32 v206, s13, v155
	s_addc_u32 s1, s76, s1
	v_lshlrev_b64 v[198:199], 2, v[138:139]
	v_add_u32_e32 v156, s16, v206
	v_lshl_add_u64 v[160:161], s[0:1], 0, v[198:199]
	v_ashrrev_i32_e32 v157, 31, v156
	flat_load_dwordx4 v[162:165], v[160:161]
	v_lshlrev_b64 v[158:159], 12, v[156:157]
	v_lshl_add_u64 v[158:159], s[26:27], 0, v[158:159]
	v_lshl_add_u64 v[158:159], v[158:159], 0, v[198:199]
	flat_load_dwordx4 v[166:169], v[158:159] nt
	s_mov_b32 s0, 0x3c800000
	v_and_b32_e32 v155, 1, v154
	v_add_u32_e32 v156, s16, v156
	v_cmp_eq_u32_e64 s[8:9], 0, v155
	v_ashrrev_i32_e32 v157, 31, v156
	v_lshlrev_b64 v[156:157], 11, v[156:157]
	v_sub_u32_e32 v154, s15, v206
	v_lshl_add_u64 v[156:157], s[24:25], 0, v[156:157]
	v_cmp_ne_u32_e32 vcc, 0, v206
	v_lshl_add_u64 v[156:157], v[138:139], 1, v[156:157]
	s_waitcnt vmcnt(0) lgkmcnt(0)
	v_or_b32_e32 v236, 16, v206
	v_add_u32_e32 v236, s16, v236
	v_ashrrev_i32_e32 v237, 31, v236
	v_lshlrev_b64 v[236:237], 12, v[236:237]
	v_lshl_add_u64 v[236:237], s[26:27], 0, v[236:237]
	v_lshl_add_u64 v[236:237], v[236:237], 0, v[198:199]
	global_load_dwordx4 v[232:235], v[236:237], off nt
	v_or_b32_e32 v236, 32, v206
	v_add_u32_e32 v236, s16, v236
	v_ashrrev_i32_e32 v237, 31, v236
	v_lshlrev_b64 v[236:237], 12, v[236:237]
	v_lshl_add_u64 v[236:237], s[26:27], 0, v[236:237]
	v_lshl_add_u64 v[236:237], v[236:237], 0, v[198:199]
	global_load_dwordx4 v[246:249], v[236:237], off nt
	v_pk_mul_f32 v[164:165], v[164:165], s[0:1] op_sel_hi:[1,0]
	v_pk_mul_f32 v[162:163], v[162:163], s[0:1] op_sel_hi:[1,0]
	v_xor_b32_e32 v170, 0x80000000, v164
	v_xor_b32_e32 v171, 0x80000000, v165
	v_xor_b32_e32 v172, 0x80000000, v162
	v_xor_b32_e32 v173, 0x80000000, v163
	v_cndmask_b32_e64 v201, v171, v165, s[8:9]
	v_cndmask_b32_e64 v200, v170, v164, s[8:9]
	v_cndmask_b32_e64 v205, v173, v163, s[8:9]
	v_cndmask_b32_e64 v204, v172, v162, s[8:9]
	v_pk_add_f32 v[162:163], v[168:169], v[200:201]
	v_pk_add_f32 v[164:165], v[166:167], v[204:205]
	v_sub_f32_e32 v155, v162, v126
	v_sub_f32_e32 v167, v163, v127
	v_sub_f32_e32 v166, v164, v124
	v_cvt_pk_bf16_f32 v167, v155, v167
	v_ashrrev_i32_e32 v155, 31, v154
	v_sub_f32_e32 v168, v165, v125
	v_cvt_pk_bf16_f32 v166, v166, v168
	global_store_dwordx2 v[156:157], v[166:167], off
	s_and_saveexec_b64 s[0:1], vcc
	s_cbranch_execz .LBB0_130
	v_pk_add_f32 v[162:163], v[126:127], v[162:163]
	v_pk_add_f32 v[164:165], v[124:125], v[164:165]
	s_nop 0
	v_cvt_pk_bf16_f32 v164, v164, v165
	v_cvt_pk_bf16_f32 v165, v162, v163
	v_lshlrev_b64 v[162:163], 11, v[154:155]
	v_lshl_add_u64 v[162:163], s[24:25], 0, v[162:163]
	v_lshl_add_u64 v[162:163], v[138:139], 1, v[162:163]
	global_store_dwordx2 v[162:163], v[164:165], off

.LBB0_169:
	s_add_u32 s0, s66, 0xfff80080
	s_addc_u32 s1, s67, -1
	s_add_i32 s2, 0, 0x10000
	v_add_u32_e32 v166, s2, v138
	ds_read_b128 v[154:157], v166
	ds_read_b128 v[158:161], v166 offset:1024
	ds_read_b128 v[162:165], v166 offset:2048
	ds_read_b128 v[166:169], v166 offset:3072
	s_cmp_eq_u32 s45, 28
	s_cselect_b32 s69, s9, s1
	s_cselect_b32 s68, s8, s0
	s_cselect_b32 s1, s65, s41
	s_cselect_b32 s0, s64, s17
	s_add_i32 m0, s11, 0xc000
	ds_read_b128 v[170:173], v139
	ds_read_b128 v[174:177], v139 offset:1024
	ds_read_b128 v[178:181], v139 offset:2048
	ds_read_b128 v[182:185], v139 offset:3072
	ds_read_b128 v[186:189], v139 offset:4096
	ds_read_b128 v[190:193], v139 offset:5120
	ds_read_b128 v[194:197], v139 offset:6144
	global_load_lds_dwordx4 v136, s[66:67]
	s_add_i32 m0, s11, 0xe000
	ds_read_b128 v[198:201], v139 offset:7168
	global_load_lds_dwordx4 v134, s[66:67]
	s_waitcnt lgkmcnt(8)
	s_barrier
	s_waitcnt lgkmcnt(0)
	s_setprio 1
	v_mfma_f32_16x16x32_bf16 v[124:127], v[154:157], v[170:173], v[124:127]
	v_mfma_f32_16x16x32_bf16 v[120:123], v[162:165], v[170:173], v[120:123]
	v_mfma_f32_16x16x32_bf16 v[116:119], v[154:157], v[178:181], v[116:119]
	v_mfma_f32_16x16x32_bf16 v[112:115], v[162:165], v[178:181], v[112:115]
	v_mfma_f32_16x16x32_bf16 v[104:107], v[154:157], v[186:189], v[104:107]
	v_mfma_f32_16x16x32_bf16 v[96:99], v[162:165], v[186:189], v[96:99]
	v_mfma_f32_16x16x32_bf16 v[88:91], v[154:157], v[194:197], v[88:91]
	v_mfma_f32_16x16x32_bf16 v[80:83], v[162:165], v[194:197], v[80:83]
	v_mfma_f32_16x16x32_bf16 v[124:127], v[158:161], v[174:177], v[124:127]
	v_mfma_f32_16x16x32_bf16 v[120:123], v[166:169], v[174:177], v[120:123]
	v_mfma_f32_16x16x32_bf16 v[116:119], v[158:161], v[182:185], v[116:119]
	v_mfma_f32_16x16x32_bf16 v[112:115], v[166:169], v[182:185], v[112:115]
	v_mfma_f32_16x16x32_bf16 v[104:107], v[158:161], v[190:193], v[104:107]
	v_mfma_f32_16x16x32_bf16 v[96:99], v[166:169], v[190:193], v[96:99]
	v_mfma_f32_16x16x32_bf16 v[88:91], v[158:161], v[198:201], v[88:91]
	v_mfma_f32_16x16x32_bf16 v[80:83], v[166:169], v[198:201], v[80:83]
	s_setprio 0
	s_barrier
	s_add_i32 s30, 0, 0x14000
	v_add_u32_e32 v210, s30, v138
	s_add_i32 s2, s2, s20
	ds_read_b128 v[202:205], v210
	ds_read_b128 v[206:209], v210 offset:1024
	ds_read_b128 v[228:231], v210 offset:2048
	s_mov_b32 m0, s2
	ds_read_b128 v[232:235], v210 offset:3072
	global_load_lds_dwordx4 v140, s[0:1]
	s_add_i32 m0, s2, 0x2000
	s_nop 0
	global_load_lds_dwordx4 v132, s[0:1]
	s_barrier
	s_waitcnt lgkmcnt(0)
	s_setprio 1
	v_mfma_f32_16x16x32_bf16 v[108:111], v[202:205], v[170:173], v[108:111]
	v_mfma_f32_16x16x32_bf16 v[100:103], v[228:231], v[170:173], v[100:103]
	v_mfma_f32_16x16x32_bf16 v[92:95], v[202:205], v[178:181], v[92:95]
	v_mfma_f32_16x16x32_bf16 v[84:87], v[228:231], v[178:181], v[84:87]
	v_mfma_f32_16x16x32_bf16 v[76:79], v[202:205], v[186:189], v[76:79]
	v_mfma_f32_16x16x32_bf16 v[72:75], v[228:231], v[186:189], v[72:75]
	v_mfma_f32_16x16x32_bf16 v[68:71], v[202:205], v[194:197], v[68:71]
	v_mfma_f32_16x16x32_bf16 v[64:67], v[228:231], v[194:197], v[64:67]
	v_mfma_f32_16x16x32_bf16 v[108:111], v[206:209], v[174:177], v[108:111]
	v_mfma_f32_16x16x32_bf16 v[100:103], v[232:235], v[174:177], v[100:103]
	v_mfma_f32_16x16x32_bf16 v[92:95], v[206:209], v[182:185], v[92:95]
	v_mfma_f32_16x16x32_bf16 v[84:87], v[232:235], v[182:185], v[84:87]
	v_mfma_f32_16x16x32_bf16 v[76:79], v[206:209], v[190:193], v[76:79]
	v_mfma_f32_16x16x32_bf16 v[72:75], v[232:235], v[190:193], v[72:75]
	v_mfma_f32_16x16x32_bf16 v[68:71], v[206:209], v[198:201], v[68:71]
	v_mfma_f32_16x16x32_bf16 v[64:67], v[232:235], v[198:201], v[64:67]
	s_setprio 0
	s_mov_b32 m0, s11
	s_barrier
	ds_read_b128 v[170:173], v139 offset:16384
	ds_read_b128 v[174:177], v139 offset:17408
	ds_read_b128 v[178:181], v139 offset:18432
	ds_read_b128 v[182:185], v139 offset:19456
	ds_read_b128 v[186:189], v139 offset:20480
	ds_read_b128 v[190:193], v139 offset:21504
	ds_read_b128 v[194:197], v139 offset:22528
	global_load_lds_dwordx4 v128, s[68:69]
	s_mov_b32 m0, s13
	ds_read_b128 v[198:201], v139 offset:23552
	global_load_lds_dwordx4 v130, s[68:69]
	s_barrier
	s_waitcnt lgkmcnt(0)
	s_setprio 1
	v_mfma_f32_16x16x32_bf16 v[60:63], v[154:157], v[170:173], v[60:63]
	v_mfma_f32_16x16x32_bf16 v[56:59], v[162:165], v[170:173], v[56:59]
	v_mfma_f32_16x16x32_bf16 v[52:55], v[154:157], v[178:181], v[52:55]
	v_mfma_f32_16x16x32_bf16 v[48:51], v[162:165], v[178:181], v[48:51]
	v_mfma_f32_16x16x32_bf16 v[36:39], v[154:157], v[186:189], v[36:39]
	v_mfma_f32_16x16x32_bf16 v[32:35], v[162:165], v[186:189], v[32:35]
	v_mfma_f32_16x16x32_bf16 v[20:23], v[154:157], v[194:197], v[20:23]
	v_mfma_f32_16x16x32_bf16 v[16:19], v[162:165], v[194:197], v[16:19]
	v_mfma_f32_16x16x32_bf16 v[60:63], v[158:161], v[174:177], v[60:63]
	v_mfma_f32_16x16x32_bf16 v[56:59], v[166:169], v[174:177], v[56:59]
	v_mfma_f32_16x16x32_bf16 v[52:55], v[158:161], v[182:185], v[52:55]
	v_mfma_f32_16x16x32_bf16 v[48:51], v[166:169], v[182:185], v[48:51]
	v_mfma_f32_16x16x32_bf16 v[36:39], v[158:161], v[190:193], v[36:39]
	v_mfma_f32_16x16x32_bf16 v[32:35], v[166:169], v[190:193], v[32:35]
	v_mfma_f32_16x16x32_bf16 v[20:23], v[158:161], v[198:201], v[20:23]
	v_mfma_f32_16x16x32_bf16 v[16:19], v[166:169], v[198:201], v[16:19]
	s_setprio 0
	s_barrier
	s_add_u32 s18, s0, 0x100000
	s_addc_u32 s19, s1, 0
	s_add_i32 s2, s30, s20
	s_mov_b32 m0, s2
	s_nop 0
	global_load_lds_dwordx4 v140, s[18:19]
	s_add_i32 m0, s2, 0x2000
	s_nop 0
	global_load_lds_dwordx4 v132, s[18:19]
	s_waitcnt vmcnt(6)
	s_barrier
	s_setprio 1
	v_mfma_f32_16x16x32_bf16 v[44:47], v[202:205], v[170:173], v[44:47]
	v_mfma_f32_16x16x32_bf16 v[40:43], v[228:231], v[170:173], v[40:43]
	v_mfma_f32_16x16x32_bf16 v[28:31], v[202:205], v[178:181], v[28:31]
	v_mfma_f32_16x16x32_bf16 v[24:27], v[228:231], v[178:181], v[24:27]
	v_mfma_f32_16x16x32_bf16 v[12:15], v[202:205], v[186:189], v[12:15]
	v_mfma_f32_16x16x32_bf16 v[8:11], v[228:231], v[186:189], v[8:11]
	v_mfma_f32_16x16x32_bf16 v[4:7], v[202:205], v[194:197], v[4:7]
	v_mfma_f32_16x16x32_bf16 v[0:3], v[228:231], v[194:197], v[0:3]
	v_mfma_f32_16x16x32_bf16 v[44:47], v[206:209], v[174:177], v[44:47]
	v_mfma_f32_16x16x32_bf16 v[40:43], v[232:235], v[174:177], v[40:43]
	v_mfma_f32_16x16x32_bf16 v[28:31], v[206:209], v[182:185], v[28:31]
	v_mfma_f32_16x16x32_bf16 v[24:27], v[232:235], v[182:185], v[24:27]
	v_mfma_f32_16x16x32_bf16 v[12:15], v[206:209], v[190:193], v[12:15]
	v_mfma_f32_16x16x32_bf16 v[8:11], v[232:235], v[190:193], v[8:11]
	v_mfma_f32_16x16x32_bf16 v[4:7], v[206:209], v[198:201], v[4:7]
	v_mfma_f32_16x16x32_bf16 v[0:3], v[232:235], v[198:201], v[0:3]
	s_setprio 0
	s_add_i32 s2, 0, 0x18000
	v_add_u32_e32 v166, s2, v138
	s_barrier
	ds_read_b128 v[154:157], v166
	ds_read_b128 v[158:161], v166 offset:1024
	ds_read_b128 v[162:165], v166 offset:2048
	ds_read_b128 v[166:169], v166 offset:3072
	s_add_u32 s18, s68, 0x80000
	s_addc_u32 s19, s69, 0
	s_mov_b32 m0, s15
	ds_read_b128 v[170:173], v139 offset:32768
	ds_read_b128 v[174:177], v139 offset:33792
	ds_read_b128 v[178:181], v139 offset:34816
	ds_read_b128 v[182:185], v139 offset:35840
	ds_read_b128 v[186:189], v139 offset:36864
	ds_read_b128 v[190:193], v139 offset:37888
	ds_read_b128 v[194:197], v139 offset:38912
	global_load_lds_dwordx4 v128, s[18:19]
	s_mov_b32 m0, s21
	ds_read_b128 v[198:201], v139 offset:39936
	global_load_lds_dwordx4 v130, s[18:19]
	s_waitcnt lgkmcnt(8)
	s_barrier
	s_waitcnt lgkmcnt(0)
	s_setprio 1
	v_mfma_f32_16x16x32_bf16 v[124:127], v[154:157], v[170:173], v[124:127]
	v_mfma_f32_16x16x32_bf16 v[120:123], v[162:165], v[170:173], v[120:123]
	v_mfma_f32_16x16x32_bf16 v[116:119], v[154:157], v[178:181], v[116:119]
	v_mfma_f32_16x16x32_bf16 v[112:115], v[162:165], v[178:181], v[112:115]
	v_mfma_f32_16x16x32_bf16 v[104:107], v[154:157], v[186:189], v[104:107]
	v_mfma_f32_16x16x32_bf16 v[96:99], v[162:165], v[186:189], v[96:99]
	v_mfma_f32_16x16x32_bf16 v[88:91], v[154:157], v[194:197], v[88:91]
	v_mfma_f32_16x16x32_bf16 v[80:83], v[162:165], v[194:197], v[80:83]
	v_mfma_f32_16x16x32_bf16 v[124:127], v[158:161], v[174:177], v[124:127]
	v_mfma_f32_16x16x32_bf16 v[120:123], v[166:169], v[174:177], v[120:123]
	v_mfma_f32_16x16x32_bf16 v[116:119], v[158:161], v[182:185], v[116:119]
	v_mfma_f32_16x16x32_bf16 v[112:115], v[166:169], v[182:185], v[112:115]
	v_mfma_f32_16x16x32_bf16 v[104:107], v[158:161], v[190:193], v[104:107]
	v_mfma_f32_16x16x32_bf16 v[96:99], v[166:169], v[190:193], v[96:99]
	v_mfma_f32_16x16x32_bf16 v[88:91], v[158:161], v[198:201], v[88:91]
	v_mfma_f32_16x16x32_bf16 v[80:83], v[166:169], v[198:201], v[80:83]
	s_setprio 0
	s_barrier
	s_add_i32 s18, 0, 0x1c000
	s_add_i32 s2, s2, s20
	v_add_u32_e32 v232, s18, v138
	s_mov_b32 m0, s2
	ds_read_b128 v[202:205], v232
	ds_read_b128 v[206:209], v232 offset:1024
	ds_read_b128 v[228:231], v232 offset:2048
	ds_read_b128 v[232:235], v232 offset:3072
	s_add_u32 s100, s0, 0x80
	s_addc_u32 s101, s1, 0
	global_load_lds_dwordx4 v140, s[100:101]
	s_add_i32 m0, s2, 0x2000
	s_nop 0
	global_load_lds_dwordx4 v132, s[100:101]
	s_barrier
	s_waitcnt lgkmcnt(0)
	s_setprio 1
	v_mfma_f32_16x16x32_bf16 v[108:111], v[202:205], v[170:173], v[108:111]
	v_mfma_f32_16x16x32_bf16 v[100:103], v[228:231], v[170:173], v[100:103]
	v_mfma_f32_16x16x32_bf16 v[92:95], v[202:205], v[178:181], v[92:95]
	v_mfma_f32_16x16x32_bf16 v[84:87], v[228:231], v[178:181], v[84:87]
	v_mfma_f32_16x16x32_bf16 v[76:79], v[202:205], v[186:189], v[76:79]
	v_mfma_f32_16x16x32_bf16 v[72:75], v[228:231], v[186:189], v[72:75]
	v_mfma_f32_16x16x32_bf16 v[68:71], v[202:205], v[194:197], v[68:71]
	v_mfma_f32_16x16x32_bf16 v[64:67], v[228:231], v[194:197], v[64:67]
	v_mfma_f32_16x16x32_bf16 v[108:111], v[206:209], v[174:177], v[108:111]
	v_mfma_f32_16x16x32_bf16 v[100:103], v[232:235], v[174:177], v[100:103]
	v_mfma_f32_16x16x32_bf16 v[92:95], v[206:209], v[182:185], v[92:95]
	v_mfma_f32_16x16x32_bf16 v[84:87], v[232:235], v[182:185], v[84:87]
	v_mfma_f32_16x16x32_bf16 v[76:79], v[206:209], v[190:193], v[76:79]
	v_mfma_f32_16x16x32_bf16 v[72:75], v[232:235], v[190:193], v[72:75]
	v_mfma_f32_16x16x32_bf16 v[68:71], v[206:209], v[198:201], v[68:71]
	v_mfma_f32_16x16x32_bf16 v[64:67], v[232:235], v[198:201], v[64:67]
	s_setprio 0
	s_mov_b32 m0, s59
	s_barrier
	ds_read_b128 v[170:173], v139 offset:49152
	ds_read_b128 v[174:177], v139 offset:50176
	ds_read_b128 v[178:181], v139 offset:51200
	ds_read_b128 v[182:185], v139 offset:52224
	ds_read_b128 v[186:189], v139 offset:53248
	ds_read_b128 v[190:193], v139 offset:54272
	ds_read_b128 v[194:197], v139 offset:55296
	ds_read_b128 v[198:201], v139 offset:56320
	s_add_u32 s100, s68, 0x80
	s_addc_u32 s101, s69, 0
	global_load_lds_dwordx4 v128, s[100:101]
	s_mov_b32 m0, s71
	s_nop 0
	global_load_lds_dwordx4 v130, s[100:101]
	s_barrier
	s_waitcnt lgkmcnt(0)
	s_setprio 1
	v_mfma_f32_16x16x32_bf16 v[60:63], v[154:157], v[170:173], v[60:63]
	v_mfma_f32_16x16x32_bf16 v[56:59], v[162:165], v[170:173], v[56:59]
	v_mfma_f32_16x16x32_bf16 v[52:55], v[154:157], v[178:181], v[52:55]
	v_mfma_f32_16x16x32_bf16 v[48:51], v[162:165], v[178:181], v[48:51]
	v_mfma_f32_16x16x32_bf16 v[36:39], v[154:157], v[186:189], v[36:39]
	v_mfma_f32_16x16x32_bf16 v[32:35], v[162:165], v[186:189], v[32:35]
	v_mfma_f32_16x16x32_bf16 v[20:23], v[154:157], v[194:197], v[20:23]
	v_mfma_f32_16x16x32_bf16 v[16:19], v[162:165], v[194:197], v[16:19]
	v_mfma_f32_16x16x32_bf16 v[60:63], v[158:161], v[174:177], v[60:63]
	v_mfma_f32_16x16x32_bf16 v[56:59], v[166:169], v[174:177], v[56:59]
	v_mfma_f32_16x16x32_bf16 v[52:55], v[158:161], v[182:185], v[52:55]
	v_mfma_f32_16x16x32_bf16 v[48:51], v[166:169], v[182:185], v[48:51]
	v_mfma_f32_16x16x32_bf16 v[36:39], v[158:161], v[190:193], v[36:39]
	v_mfma_f32_16x16x32_bf16 v[32:35], v[166:169], v[190:193], v[32:35]
	v_mfma_f32_16x16x32_bf16 v[20:23], v[158:161], v[198:201], v[20:23]
	v_mfma_f32_16x16x32_bf16 v[16:19], v[166:169], v[198:201], v[16:19]
	s_setprio 0
	s_barrier
	s_add_u32 s0, s0, 0x100080
	s_addc_u32 s1, s1, 0
	s_add_i32 s2, s18, s20
	s_mov_b32 m0, s2
	s_nop 0
	global_load_lds_dwordx4 v140, s[0:1]
	s_add_i32 m0, s2, 0x2000
	s_nop 0
	global_load_lds_dwordx4 v132, s[0:1]
	s_waitcnt vmcnt(6)
	s_barrier
	s_setprio 1
	v_mfma_f32_16x16x32_bf16 v[44:47], v[202:205], v[170:173], v[44:47]
	v_mfma_f32_16x16x32_bf16 v[40:43], v[228:231], v[170:173], v[40:43]
	v_mfma_f32_16x16x32_bf16 v[28:31], v[202:205], v[178:181], v[28:31]
	v_mfma_f32_16x16x32_bf16 v[24:27], v[228:231], v[178:181], v[24:27]
	v_mfma_f32_16x16x32_bf16 v[12:15], v[202:205], v[186:189], v[12:15]
	v_mfma_f32_16x16x32_bf16 v[8:11], v[228:231], v[186:189], v[8:11]
	v_mfma_f32_16x16x32_bf16 v[4:7], v[202:205], v[194:197], v[4:7]
	v_mfma_f32_16x16x32_bf16 v[0:3], v[228:231], v[194:197], v[0:3]
	v_mfma_f32_16x16x32_bf16 v[44:47], v[206:209], v[174:177], v[44:47]
	v_mfma_f32_16x16x32_bf16 v[40:43], v[232:235], v[174:177], v[40:43]
	v_mfma_f32_16x16x32_bf16 v[28:31], v[206:209], v[182:185], v[28:31]
	v_mfma_f32_16x16x32_bf16 v[24:27], v[232:235], v[182:185], v[24:27]
	v_mfma_f32_16x16x32_bf16 v[12:15], v[206:209], v[190:193], v[12:15]
	v_mfma_f32_16x16x32_bf16 v[8:11], v[232:235], v[190:193], v[8:11]
	v_mfma_f32_16x16x32_bf16 v[4:7], v[206:209], v[198:201], v[4:7]
	v_mfma_f32_16x16x32_bf16 v[0:3], v[232:235], v[198:201], v[0:3]
	s_setprio 0
	s_add_i32 s45, s45, 2
	s_add_u32 s17, s17, 0x100
	s_addc_u32 s41, s41, 0
	s_add_u32 s66, s66, 0x100
	s_addc_u32 s67, s67, 0
	s_cmp_gt_u32 s45, 29
	s_barrier
	s_cbranch_scc0 .LBB0_169
	s_lshl_b32 s0, s10, 11
	s_lshl_b32 s1, s14, 8
	s_add_i32 s0, s0, s57
	v_mbcnt_lo_u32_b32 v155, -1, 0
	v_mbcnt_hi_u32_b32 v155, -1, v155
	s_lshl_b32 s2, s12, 8
	v_ashrrev_i32_e32 v154, 2, v155
	s_add_i32 s0, s0, s1
	v_and_b32_e32 v154, -4, v154
	s_or_b32 s2, s2, s58
	v_and_or_b32 v156, v155, 15, s0
	v_add_u32_e32 v154, s2, v154
	v_ashrrev_i32_e32 v157, 31, v156
	v_ashrrev_i32_e32 v155, 31, v154
	v_lshlrev_b64 v[158:159], 12, v[156:157]
	v_lshl_add_u64 v[158:159], s[26:27], 0, v[158:159]
	v_lshlrev_b64 v[154:155], 2, v[154:155]
	v_lshl_add_u64 v[158:159], v[158:159], 0, v[154:155]
	flat_store_dwordx4 v[158:159], v[124:127]
	flat_store_dwordx4 v[158:159], v[120:123] offset:64
	flat_store_dwordx4 v[158:159], v[108:111] offset:512
	flat_store_dwordx4 v[158:159], v[100:103] offset:576
	s_mov_b64 s[0:1], 0x80000
	s_mov_b32 s10, s16
	v_or_b32_e32 v100, 16, v156
	v_ashrrev_i32_e32 v101, 31, v100
	v_lshlrev_b64 v[100:101], 12, v[100:101]
	v_lshl_add_u64 v[100:101], s[26:27], 0, v[100:101]
	v_lshl_add_u64 v[100:101], v[100:101], 0, v[154:155]
	flat_store_dwordx4 v[100:101], v[116:119]
	flat_store_dwordx4 v[100:101], v[112:115] offset:64
	flat_store_dwordx4 v[100:101], v[92:95] offset:512
	flat_store_dwordx4 v[100:101], v[84:87] offset:576
	s_mov_b32 s12, s40
	s_mov_b32 s14, s44
	v_or_b32_e32 v84, 32, v156
	v_ashrrev_i32_e32 v85, 31, v84
	v_lshlrev_b64 v[84:85], 12, v[84:85]
	v_lshl_add_u64 v[84:85], s[26:27], 0, v[84:85]
	v_lshl_add_u64 v[84:85], v[84:85], 0, v[154:155]
	flat_store_dwordx4 v[84:85], v[104:107]
	flat_store_dwordx4 v[84:85], v[96:99] offset:64
	flat_store_dwordx4 v[84:85], v[76:79] offset:512
	flat_store_dwordx4 v[84:85], v[72:75] offset:576
	s_mov_b64 s[66:67], s[64:65]
	s_nop 0
	v_or_b32_e32 v72, 48, v156
	v_ashrrev_i32_e32 v73, 31, v72
	v_lshlrev_b64 v[72:73], 12, v[72:73]
	v_lshl_add_u64 v[72:73], s[26:27], 0, v[72:73]
	v_lshl_add_u64 v[72:73], v[72:73], 0, v[154:155]
	flat_store_dwordx4 v[72:73], v[88:91]
	flat_store_dwordx4 v[72:73], v[80:83] offset:64
	flat_store_dwordx4 v[72:73], v[68:71] offset:512
	flat_store_dwordx4 v[72:73], v[64:67] offset:576
	s_nop 1
	v_lshl_add_u64 v[64:65], v[158:159], 0, s[0:1]
	s_mov_b32 s0, 0x80000
	v_add_co_u32_e32 v66, vcc, s0, v158
	s_mov_b64 s[0:1], 0x90000
	s_nop 0
	v_addc_co_u32_e32 v67, vcc, 0, v159, vcc
	flat_store_dwordx4 v[66:67], v[60:63]
	flat_store_dwordx4 v[64:65], v[56:59] offset:64
	flat_store_dwordx4 v[64:65], v[44:47] offset:512
	flat_store_dwordx4 v[64:65], v[40:43] offset:576
	s_nop 1
	v_lshl_add_u64 v[40:41], v[158:159], 0, s[0:1]
	s_mov_b32 s0, 0x90000
	v_add_co_u32_e32 v42, vcc, s0, v158
	s_mov_b64 s[0:1], 0xa0000
	s_nop 0
	v_addc_co_u32_e32 v43, vcc, 0, v159, vcc
	flat_store_dwordx4 v[42:43], v[52:55]
	flat_store_dwordx4 v[40:41], v[48:51] offset:64
	flat_store_dwordx4 v[40:41], v[28:31] offset:512
	flat_store_dwordx4 v[40:41], v[24:27] offset:576
	s_nop 1
	v_lshl_add_u64 v[24:25], v[158:159], 0, s[0:1]
	s_mov_b32 s0, 0xa0000
	v_add_co_u32_e32 v26, vcc, s0, v158
	s_mov_b64 s[0:1], 0xb0000
	s_nop 0
	v_addc_co_u32_e32 v27, vcc, 0, v159, vcc
	flat_store_dwordx4 v[26:27], v[36:39]
	flat_store_dwordx4 v[24:25], v[32:35] offset:64
	flat_store_dwordx4 v[24:25], v[12:15] offset:512
	flat_store_dwordx4 v[24:25], v[8:11] offset:576
	s_nop 1
	v_add_co_u32_e32 v10, vcc, 0xb0000, v158
	v_lshl_add_u64 v[8:9], v[158:159], 0, s[0:1]
	s_nop 0
	v_addc_co_u32_e32 v11, vcc, 0, v159, vcc
	s_and_b64 vcc, exec, s[6:7]
	s_mov_b64 s[0:1], s[8:9]
	flat_store_dwordx4 v[10:11], v[20:23]
	flat_store_dwordx4 v[8:9], v[16:19] offset:64
	flat_store_dwordx4 v[8:9], v[4:7] offset:512
	flat_store_dwordx4 v[8:9], v[0:3] offset:576
	s_cbranch_vccz .LBB0_160
	s_waitcnt vmcnt(0)
	s_cmpk_gt_u32 s51, 0xff
	s_cbranch_scc1 .LBB0_173
	s_barrier

.LBB0_203:
	s_add_u32 s2, s44, s13
	s_addc_u32 s15, s45, 0
	s_add_u32 s17, s2, 0x100
	s_addc_u32 s21, s15, 0
	s_and_b64 s[18:19], s[0:1], exec
	s_cselect_b32 s81, s9, s21
	s_cselect_b32 s80, s8, s17
	s_add_u32 s13, s64, s13
	s_addc_u32 s17, s65, 0
	s_add_u32 s13, s13, 0x100
	s_addc_u32 s17, s17, 0
	s_add_i32 s21, 0, 0x10000
	s_and_b64 s[0:1], s[0:1], exec
	s_cselect_b32 s89, s11, s17
	s_cselect_b32 s88, s10, s13
	s_add_u32 s96, s2, 0x10080
	s_addc_u32 s97, s15, 0
	s_add_i32 s43, s21, s52
	s_add_i32 m0, s41, 0xc000
	s_add_i32 s47, s41, 0xe000
	s_add_i32 s42, 0, 0x14000
	s_add_i32 s31, s43, 0x2000
	s_add_u32 s76, s88, 0x40000
	v_add_u32_e32 v138, s21, v136
	s_addc_u32 s77, s89, 0
	s_add_i32 s19, s42, s52
	ds_read_b128 v[154:157], v138
	ds_read_b128 v[158:161], v138 offset:1024
	ds_read_b128 v[162:165], v138 offset:2048
	ds_read_b128 v[166:169], v138 offset:3072
	s_add_i32 s18, s19, 0x2000
	s_add_i32 s17, 0, 0x18000
	s_add_u32 s68, s80, 0x10000
	s_addc_u32 s69, s81, 0
	s_add_i32 s15, s17, s52
	s_add_i32 s13, 0, 0x1c000
	s_add_i32 s2, s15, 0x2000
	s_add_u32 s0, s88, 0x40080
	s_addc_u32 s1, s89, 0
	s_add_i32 s30, s13, s52
	s_add_i32 s21, s30, 0x2000
	ds_read_b128 v[170:173], v137
	ds_read_b128 v[174:177], v137 offset:1024
	ds_read_b128 v[178:181], v137 offset:2048
	ds_read_b128 v[182:185], v137 offset:3072
	ds_read_b128 v[186:189], v137 offset:4096
	ds_read_b128 v[190:193], v137 offset:5120
	ds_read_b128 v[194:197], v137 offset:6144
	global_load_lds_dwordx4 v128, s[96:97]
	s_mov_b32 m0, s47
	ds_read_b128 v[198:201], v137 offset:7168
	global_load_lds_dwordx4 v132, s[96:97]
	s_waitcnt lgkmcnt(8)
	s_barrier
	s_waitcnt lgkmcnt(0)
	s_setprio 1
	v_mfma_f32_16x16x32_bf16 v[124:127], v[154:157], v[170:173], v[124:127]
	v_mfma_f32_16x16x32_bf16 v[120:123], v[162:165], v[170:173], v[120:123]
	v_mfma_f32_16x16x32_bf16 v[112:115], v[154:157], v[178:181], v[112:115]
	v_mfma_f32_16x16x32_bf16 v[104:107], v[162:165], v[178:181], v[104:107]
	v_mfma_f32_16x16x32_bf16 v[96:99], v[154:157], v[186:189], v[96:99]
	v_mfma_f32_16x16x32_bf16 v[88:91], v[162:165], v[186:189], v[88:91]
	v_mfma_f32_16x16x32_bf16 v[80:83], v[154:157], v[194:197], v[80:83]
	v_mfma_f32_16x16x32_bf16 v[72:75], v[162:165], v[194:197], v[72:75]
	v_mfma_f32_16x16x32_bf16 v[124:127], v[158:161], v[174:177], v[124:127]
	v_mfma_f32_16x16x32_bf16 v[120:123], v[166:169], v[174:177], v[120:123]
	v_mfma_f32_16x16x32_bf16 v[112:115], v[158:161], v[182:185], v[112:115]
	v_mfma_f32_16x16x32_bf16 v[104:107], v[166:169], v[182:185], v[104:107]
	v_mfma_f32_16x16x32_bf16 v[96:99], v[158:161], v[190:193], v[96:99]
	v_mfma_f32_16x16x32_bf16 v[88:91], v[166:169], v[190:193], v[88:91]
	v_mfma_f32_16x16x32_bf16 v[80:83], v[158:161], v[198:201], v[80:83]
	v_mfma_f32_16x16x32_bf16 v[72:75], v[166:169], v[198:201], v[72:75]
	s_setprio 0
	s_barrier
	v_add_u32_e32 v138, s42, v136
	s_mov_b32 m0, s43
	ds_read_b128 v[202:205], v138
	ds_read_b128 v[206:209], v138 offset:1024
	ds_read_b128 v[228:231], v138 offset:2048
	global_load_lds_dwordx4 v130, s[88:89]
	s_mov_b32 m0, s31
	ds_read_b128 v[232:235], v138 offset:3072
	global_load_lds_dwordx4 v134, s[88:89]
	s_barrier
	s_waitcnt lgkmcnt(0)
	s_setprio 1
	v_mfma_f32_16x16x32_bf16 v[116:119], v[202:205], v[170:173], v[116:119]
	v_mfma_f32_16x16x32_bf16 v[108:111], v[228:231], v[170:173], v[108:111]
	v_mfma_f32_16x16x32_bf16 v[100:103], v[202:205], v[178:181], v[100:103]
	v_mfma_f32_16x16x32_bf16 v[92:95], v[228:231], v[178:181], v[92:95]
	v_mfma_f32_16x16x32_bf16 v[84:87], v[202:205], v[186:189], v[84:87]
	v_mfma_f32_16x16x32_bf16 v[76:79], v[228:231], v[186:189], v[76:79]
	v_mfma_f32_16x16x32_bf16 v[68:71], v[202:205], v[194:197], v[68:71]
	v_mfma_f32_16x16x32_bf16 v[64:67], v[228:231], v[194:197], v[64:67]
	v_mfma_f32_16x16x32_bf16 v[116:119], v[206:209], v[174:177], v[116:119]
	v_mfma_f32_16x16x32_bf16 v[108:111], v[232:235], v[174:177], v[108:111]
	v_mfma_f32_16x16x32_bf16 v[100:103], v[206:209], v[182:185], v[100:103]
	v_mfma_f32_16x16x32_bf16 v[92:95], v[232:235], v[182:185], v[92:95]
	v_mfma_f32_16x16x32_bf16 v[84:87], v[206:209], v[190:193], v[84:87]
	v_mfma_f32_16x16x32_bf16 v[76:79], v[232:235], v[190:193], v[76:79]
	v_mfma_f32_16x16x32_bf16 v[68:71], v[206:209], v[198:201], v[68:71]
	v_mfma_f32_16x16x32_bf16 v[64:67], v[232:235], v[198:201], v[64:67]
	s_setprio 0
	s_mov_b32 m0, s41
	s_barrier
	ds_read_b128 v[170:173], v137 offset:16384
	ds_read_b128 v[174:177], v137 offset:17408
	ds_read_b128 v[178:181], v137 offset:18432
	ds_read_b128 v[182:185], v137 offset:19456
	ds_read_b128 v[186:189], v137 offset:20480
	ds_read_b128 v[190:193], v137 offset:21504
	ds_read_b128 v[194:197], v137 offset:22528
	global_load_lds_dwordx4 v128, s[80:81]
	s_mov_b32 m0, s57
	ds_read_b128 v[198:201], v137 offset:23552
	global_load_lds_dwordx4 v132, s[80:81]
	s_barrier
	s_waitcnt lgkmcnt(0)
	s_setprio 1
	v_mfma_f32_16x16x32_bf16 v[60:63], v[154:157], v[170:173], v[60:63]
	v_mfma_f32_16x16x32_bf16 v[56:59], v[162:165], v[170:173], v[56:59]
	v_mfma_f32_16x16x32_bf16 v[48:51], v[154:157], v[178:181], v[48:51]
	v_mfma_f32_16x16x32_bf16 v[40:43], v[162:165], v[178:181], v[40:43]
	v_mfma_f32_16x16x32_bf16 v[32:35], v[154:157], v[186:189], v[32:35]
	v_mfma_f32_16x16x32_bf16 v[24:27], v[162:165], v[186:189], v[24:27]
	v_mfma_f32_16x16x32_bf16 v[16:19], v[154:157], v[194:197], v[16:19]
	v_mfma_f32_16x16x32_bf16 v[8:11], v[162:165], v[194:197], v[8:11]
	v_mfma_f32_16x16x32_bf16 v[60:63], v[158:161], v[174:177], v[60:63]
	v_mfma_f32_16x16x32_bf16 v[56:59], v[166:169], v[174:177], v[56:59]
	v_mfma_f32_16x16x32_bf16 v[48:51], v[158:161], v[182:185], v[48:51]
	v_mfma_f32_16x16x32_bf16 v[40:43], v[166:169], v[182:185], v[40:43]
	v_mfma_f32_16x16x32_bf16 v[32:35], v[158:161], v[190:193], v[32:35]
	v_mfma_f32_16x16x32_bf16 v[24:27], v[166:169], v[190:193], v[24:27]
	v_mfma_f32_16x16x32_bf16 v[16:19], v[158:161], v[198:201], v[16:19]
	v_mfma_f32_16x16x32_bf16 v[8:11], v[166:169], v[198:201], v[8:11]
	s_setprio 0
	s_barrier
	s_mov_b32 m0, s19
	s_nop 0
	global_load_lds_dwordx4 v130, s[76:77]
	s_mov_b32 m0, s18
	s_nop 0
	global_load_lds_dwordx4 v134, s[76:77]
	s_waitcnt vmcnt(6)
	s_barrier
	s_setprio 1
	v_mfma_f32_16x16x32_bf16 v[52:55], v[202:205], v[170:173], v[52:55]
	v_mfma_f32_16x16x32_bf16 v[44:47], v[228:231], v[170:173], v[44:47]
	v_mfma_f32_16x16x32_bf16 v[36:39], v[202:205], v[178:181], v[36:39]
	v_mfma_f32_16x16x32_bf16 v[28:31], v[228:231], v[178:181], v[28:31]
	v_mfma_f32_16x16x32_bf16 v[20:23], v[202:205], v[186:189], v[20:23]
	v_mfma_f32_16x16x32_bf16 v[12:15], v[228:231], v[186:189], v[12:15]
	v_mfma_f32_16x16x32_bf16 v[4:7], v[202:205], v[194:197], v[4:7]
	v_mfma_f32_16x16x32_bf16 v[0:3], v[228:231], v[194:197], v[0:3]
	v_mfma_f32_16x16x32_bf16 v[52:55], v[206:209], v[174:177], v[52:55]
	v_mfma_f32_16x16x32_bf16 v[44:47], v[232:235], v[174:177], v[44:47]
	v_mfma_f32_16x16x32_bf16 v[36:39], v[206:209], v[182:185], v[36:39]
	v_mfma_f32_16x16x32_bf16 v[28:31], v[232:235], v[182:185], v[28:31]
	v_mfma_f32_16x16x32_bf16 v[20:23], v[206:209], v[190:193], v[20:23]
	v_mfma_f32_16x16x32_bf16 v[12:15], v[232:235], v[190:193], v[12:15]
	v_mfma_f32_16x16x32_bf16 v[4:7], v[206:209], v[198:201], v[4:7]
	v_mfma_f32_16x16x32_bf16 v[0:3], v[232:235], v[198:201], v[0:3]
	s_setprio 0
	v_add_u32_e32 v140, s17, v136
	s_barrier
	ds_read_b128 v[154:157], v140
	ds_read_b128 v[158:161], v140 offset:1024
	ds_read_b128 v[162:165], v140 offset:2048
	ds_read_b128 v[166:169], v140 offset:3072
	s_mov_b32 m0, s58
	ds_read_b128 v[170:173], v137 offset:32768
	ds_read_b128 v[174:177], v137 offset:33792
	ds_read_b128 v[178:181], v137 offset:34816
	ds_read_b128 v[182:185], v137 offset:35840
	ds_read_b128 v[186:189], v137 offset:36864
	ds_read_b128 v[190:193], v137 offset:37888
	ds_read_b128 v[194:197], v137 offset:38912
	global_load_lds_dwordx4 v128, s[68:69]
	s_mov_b32 m0, s59
	ds_read_b128 v[198:201], v137 offset:39936
	global_load_lds_dwordx4 v132, s[68:69]
	s_waitcnt lgkmcnt(8)
	s_barrier
	s_waitcnt lgkmcnt(0)
	s_setprio 1
	v_mfma_f32_16x16x32_bf16 v[124:127], v[154:157], v[170:173], v[124:127]
	v_mfma_f32_16x16x32_bf16 v[120:123], v[162:165], v[170:173], v[120:123]
	v_mfma_f32_16x16x32_bf16 v[112:115], v[154:157], v[178:181], v[112:115]
	v_mfma_f32_16x16x32_bf16 v[104:107], v[162:165], v[178:181], v[104:107]
	v_mfma_f32_16x16x32_bf16 v[96:99], v[154:157], v[186:189], v[96:99]
	v_mfma_f32_16x16x32_bf16 v[88:91], v[162:165], v[186:189], v[88:91]
	v_mfma_f32_16x16x32_bf16 v[80:83], v[154:157], v[194:197], v[80:83]
	v_mfma_f32_16x16x32_bf16 v[72:75], v[162:165], v[194:197], v[72:75]
	v_mfma_f32_16x16x32_bf16 v[124:127], v[158:161], v[174:177], v[124:127]
	v_mfma_f32_16x16x32_bf16 v[120:123], v[166:169], v[174:177], v[120:123]
	v_mfma_f32_16x16x32_bf16 v[112:115], v[158:161], v[182:185], v[112:115]
	v_mfma_f32_16x16x32_bf16 v[104:107], v[166:169], v[182:185], v[104:107]
	v_mfma_f32_16x16x32_bf16 v[96:99], v[158:161], v[190:193], v[96:99]
	v_mfma_f32_16x16x32_bf16 v[88:91], v[166:169], v[190:193], v[88:91]
	v_mfma_f32_16x16x32_bf16 v[80:83], v[158:161], v[198:201], v[80:83]
	v_mfma_f32_16x16x32_bf16 v[72:75], v[166:169], v[198:201], v[72:75]
	s_setprio 0
	s_barrier
	s_mov_b32 m0, s15
	v_add_u32_e32 v140, s13, v136
	ds_read_b128 v[202:205], v140
	ds_read_b128 v[206:209], v140 offset:1024
	ds_read_b128 v[228:231], v140 offset:2048
	ds_read_b128 v[232:235], v140 offset:3072
	s_add_u32 s100, s88, 0x80
	s_addc_u32 s101, s89, 0
	global_load_lds_dwordx4 v130, s[100:101]
	s_mov_b32 m0, s2
	s_nop 0
	global_load_lds_dwordx4 v134, s[100:101]
	s_barrier
	s_waitcnt lgkmcnt(0)
	s_setprio 1
	v_mfma_f32_16x16x32_bf16 v[116:119], v[202:205], v[170:173], v[116:119]
	v_mfma_f32_16x16x32_bf16 v[108:111], v[228:231], v[170:173], v[108:111]
	v_mfma_f32_16x16x32_bf16 v[100:103], v[202:205], v[178:181], v[100:103]
	v_mfma_f32_16x16x32_bf16 v[92:95], v[228:231], v[178:181], v[92:95]
	v_mfma_f32_16x16x32_bf16 v[84:87], v[202:205], v[186:189], v[84:87]
	v_mfma_f32_16x16x32_bf16 v[76:79], v[228:231], v[186:189], v[76:79]
	v_mfma_f32_16x16x32_bf16 v[68:71], v[202:205], v[194:197], v[68:71]
	v_mfma_f32_16x16x32_bf16 v[64:67], v[228:231], v[194:197], v[64:67]
	v_mfma_f32_16x16x32_bf16 v[116:119], v[206:209], v[174:177], v[116:119]
	v_mfma_f32_16x16x32_bf16 v[108:111], v[232:235], v[174:177], v[108:111]
	v_mfma_f32_16x16x32_bf16 v[100:103], v[206:209], v[182:185], v[100:103]
	v_mfma_f32_16x16x32_bf16 v[92:95], v[232:235], v[182:185], v[92:95]
	v_mfma_f32_16x16x32_bf16 v[84:87], v[206:209], v[190:193], v[84:87]
	v_mfma_f32_16x16x32_bf16 v[76:79], v[232:235], v[190:193], v[76:79]
	v_mfma_f32_16x16x32_bf16 v[68:71], v[206:209], v[198:201], v[68:71]
	v_mfma_f32_16x16x32_bf16 v[64:67], v[232:235], v[198:201], v[64:67]
	s_setprio 0
	s_mov_b32 m0, s73
	s_barrier
	ds_read_b128 v[170:173], v137 offset:49152
	ds_read_b128 v[174:177], v137 offset:50176
	ds_read_b128 v[178:181], v137 offset:51200
	ds_read_b128 v[182:185], v137 offset:52224
	ds_read_b128 v[186:189], v137 offset:53248
	ds_read_b128 v[190:193], v137 offset:54272
	ds_read_b128 v[194:197], v137 offset:55296
	ds_read_b128 v[198:201], v137 offset:56320
	s_add_u32 s100, s80, 0x80
	s_addc_u32 s101, s81, 0
	global_load_lds_dwordx4 v128, s[100:101]
	s_mov_b32 m0, s74
	s_nop 0
	global_load_lds_dwordx4 v132, s[100:101]
	s_barrier
	s_waitcnt lgkmcnt(0)
	s_setprio 1
	v_mfma_f32_16x16x32_bf16 v[60:63], v[154:157], v[170:173], v[60:63]
	v_mfma_f32_16x16x32_bf16 v[56:59], v[162:165], v[170:173], v[56:59]
	v_mfma_f32_16x16x32_bf16 v[48:51], v[154:157], v[178:181], v[48:51]
	v_mfma_f32_16x16x32_bf16 v[40:43], v[162:165], v[178:181], v[40:43]
	v_mfma_f32_16x16x32_bf16 v[32:35], v[154:157], v[186:189], v[32:35]
	v_mfma_f32_16x16x32_bf16 v[24:27], v[162:165], v[186:189], v[24:27]
	v_mfma_f32_16x16x32_bf16 v[16:19], v[154:157], v[194:197], v[16:19]
	v_mfma_f32_16x16x32_bf16 v[8:11], v[162:165], v[194:197], v[8:11]
	v_mfma_f32_16x16x32_bf16 v[60:63], v[158:161], v[174:177], v[60:63]
	v_mfma_f32_16x16x32_bf16 v[56:59], v[166:169], v[174:177], v[56:59]
	v_mfma_f32_16x16x32_bf16 v[48:51], v[158:161], v[182:185], v[48:51]
	v_mfma_f32_16x16x32_bf16 v[40:43], v[166:169], v[182:185], v[40:43]
	v_mfma_f32_16x16x32_bf16 v[32:35], v[158:161], v[190:193], v[32:35]
	v_mfma_f32_16x16x32_bf16 v[24:27], v[166:169], v[190:193], v[24:27]
	v_mfma_f32_16x16x32_bf16 v[16:19], v[158:161], v[198:201], v[16:19]
	v_mfma_f32_16x16x32_bf16 v[8:11], v[166:169], v[198:201], v[8:11]
	s_setprio 0
	s_barrier
	s_mov_b32 m0, s30
	s_nop 0
	global_load_lds_dwordx4 v130, s[0:1]
	s_mov_b32 m0, s21
	s_nop 0
	global_load_lds_dwordx4 v134, s[0:1]
	s_waitcnt vmcnt(6)
	s_barrier
	s_setprio 1
	v_mfma_f32_16x16x32_bf16 v[52:55], v[202:205], v[170:173], v[52:55]
	v_mfma_f32_16x16x32_bf16 v[44:47], v[228:231], v[170:173], v[44:47]
	v_mfma_f32_16x16x32_bf16 v[36:39], v[202:205], v[178:181], v[36:39]
	v_mfma_f32_16x16x32_bf16 v[28:31], v[228:231], v[178:181], v[28:31]
	v_mfma_f32_16x16x32_bf16 v[20:23], v[202:205], v[186:189], v[20:23]
	v_mfma_f32_16x16x32_bf16 v[12:15], v[228:231], v[186:189], v[12:15]
	v_mfma_f32_16x16x32_bf16 v[4:7], v[202:205], v[194:197], v[4:7]
	v_mfma_f32_16x16x32_bf16 v[0:3], v[228:231], v[194:197], v[0:3]
	v_mfma_f32_16x16x32_bf16 v[52:55], v[206:209], v[174:177], v[52:55]
	v_mfma_f32_16x16x32_bf16 v[44:47], v[232:235], v[174:177], v[44:47]
	v_mfma_f32_16x16x32_bf16 v[36:39], v[206:209], v[182:185], v[36:39]
	v_mfma_f32_16x16x32_bf16 v[28:31], v[232:235], v[182:185], v[28:31]
	v_mfma_f32_16x16x32_bf16 v[20:23], v[206:209], v[190:193], v[20:23]
	v_mfma_f32_16x16x32_bf16 v[12:15], v[232:235], v[190:193], v[12:15]
	v_mfma_f32_16x16x32_bf16 v[4:7], v[206:209], v[198:201], v[4:7]
	v_mfma_f32_16x16x32_bf16 v[0:3], v[232:235], v[198:201], v[0:3]
	s_setprio 0
	s_movk_i32 s13, 0x100
	s_andn2_b64 vcc, exec, s[66:67]
	s_mov_b64 s[0:1], -1
	s_mov_b64 s[66:67], 0
	s_barrier
	s_cbranch_vccz .LBB0_203
	v_mbcnt_lo_u32_b32 v138, -1, 0
	v_mbcnt_hi_u32_b32 v138, -1, v138
	s_lshl_b32 s0, s40, 8
	v_ashrrev_i32_e32 v139, 1, v138
	s_or_b32 s0, s0, s72
	v_and_b32_e32 v139, -8, v139
	v_add_u32_e32 v139, s0, v139
	s_lshl_b32 s1, s20, 8
	v_and_or_b32 v138, v138, 15, s71
	s_and_b32 s1, s1, 0x300
	v_cvt_pk_bf16_f32 v124, v124, v125
	v_cvt_pk_bf16_f32 v125, v126, v127
	v_cvt_pk_bf16_f32 v126, v120, v121
	v_ashrrev_i32_e32 v120, 1, v139
	v_add_u32_e32 v138, s1, v138
	v_cvt_pk_bf16_f32 v127, v122, v123
	v_and_b32_e32 v122, 0xfffffc00, v120
	v_add_u32_e32 v120, v122, v138
	s_ashr_i32 s0, s20, 2
	v_ashrrev_i32_e32 v121, 31, v120
	s_ashr_i32 s1, s0, 31
	v_lshlrev_b64 v[120:121], 13, v[120:121]
	s_lshl_b64 s[0:1], s[0:1], 12
	v_and_b32_e32 v140, 0x7f8, v139
	v_lshl_add_u64 v[120:121], s[38:39], 0, v[120:121]
	v_lshl_add_u64 v[120:121], v[120:121], 0, s[0:1]
	v_lshlrev_b32_e32 v140, 1, v140
	v_lshl_add_u64 v[120:121], v[120:121], 0, v[140:141]
	flat_store_dwordx4 v[120:121], v[124:127]
	v_add_u32_e32 v120, 0x80, v139
	v_cvt_pk_bf16_f32 v116, v116, v117
	v_cvt_pk_bf16_f32 v117, v118, v119
	v_cvt_pk_bf16_f32 v118, v108, v109
	v_ashrrev_i32_e32 v108, 1, v120
	v_and_b32_e32 v121, 0x7f8, v120
	v_and_b32_e32 v120, 0xfffffc00, v108
	v_add_u32_e32 v108, v120, v138
	v_ashrrev_i32_e32 v109, 31, v108
	v_lshlrev_b64 v[108:109], 13, v[108:109]
	v_lshl_add_u64 v[108:109], s[38:39], 0, v[108:109]
	v_cvt_pk_bf16_f32 v119, v110, v111
	v_lshl_add_u64 v[110:111], v[108:109], 0, s[0:1]
	v_lshlrev_b32_e32 v108, 1, v121
	v_mov_b32_e32 v109, v141
	v_lshl_add_u64 v[110:111], v[110:111], 0, v[108:109]
	flat_store_dwordx4 v[110:111], v[116:119]
	v_cvt_pk_bf16_f32 v110, v112, v113
	v_cvt_pk_bf16_f32 v112, v104, v105
	v_cvt_pk_bf16_f32 v100, v100, v101
	v_cvt_pk_bf16_f32 v101, v102, v103
	v_cvt_pk_bf16_f32 v102, v92, v93
	s_nop 1
	v_or_b32_e32 v116, 16, v138
	v_add_u32_e32 v104, v122, v116
	v_add_u32_e32 v92, v120, v116
	v_ashrrev_i32_e32 v105, 31, v104
	v_ashrrev_i32_e32 v93, 31, v92
	v_lshlrev_b64 v[104:105], 13, v[104:105]
	v_lshlrev_b64 v[92:93], 13, v[92:93]
	v_lshl_add_u64 v[104:105], s[38:39], 0, v[104:105]
	v_lshl_add_u64 v[92:93], s[38:39], 0, v[92:93]
	v_lshl_add_u64 v[104:105], v[104:105], 0, s[0:1]
	v_lshl_add_u64 v[92:93], v[92:93], 0, s[0:1]
	v_lshl_add_u64 v[104:105], v[104:105], 0, v[140:141]
	v_lshl_add_u64 v[92:93], v[92:93], 0, v[108:109]
	v_cvt_pk_bf16_f32 v111, v114, v115
	v_cvt_pk_bf16_f32 v113, v106, v107
	flat_store_dwordx4 v[104:105], v[110:113]
	v_cvt_pk_bf16_f32 v103, v94, v95
	flat_store_dwordx4 v[92:93], v[100:103]
	v_cvt_pk_bf16_f32 v94, v88, v89
	v_cvt_pk_bf16_f32 v84, v84, v85
	v_cvt_pk_bf16_f32 v85, v86, v87
	v_cvt_pk_bf16_f32 v86, v76, v77
	v_cvt_pk_bf16_f32 v92, v96, v97
	s_nop 1
	v_or_b32_e32 v100, 32, v138
	v_add_u32_e32 v88, v122, v100
	v_add_u32_e32 v76, v120, v100
	v_ashrrev_i32_e32 v89, 31, v88
	v_ashrrev_i32_e32 v77, 31, v76
	v_lshlrev_b64 v[88:89], 13, v[88:89]
	v_lshlrev_b64 v[76:77], 13, v[76:77]
	v_lshl_add_u64 v[88:89], s[38:39], 0, v[88:89]
	v_lshl_add_u64 v[76:77], s[38:39], 0, v[76:77]
	v_lshl_add_u64 v[88:89], v[88:89], 0, s[0:1]
	v_lshl_add_u64 v[76:77], v[76:77], 0, s[0:1]
	v_lshl_add_u64 v[88:89], v[88:89], 0, v[140:141]
	v_lshl_add_u64 v[76:77], v[76:77], 0, v[108:109]
	v_cvt_pk_bf16_f32 v93, v98, v99
	v_cvt_pk_bf16_f32 v95, v90, v91
	flat_store_dwordx4 v[88:89], v[92:95]
	v_cvt_pk_bf16_f32 v87, v78, v79
	flat_store_dwordx4 v[76:77], v[84:87]
	v_cvt_pk_bf16_f32 v78, v72, v73
	v_cvt_pk_bf16_f32 v68, v68, v69
	v_cvt_pk_bf16_f32 v69, v70, v71
	v_cvt_pk_bf16_f32 v70, v64, v65
	v_cvt_pk_bf16_f32 v76, v80, v81
	s_nop 1
	v_or_b32_e32 v84, 48, v138
	v_add_u32_e32 v72, v122, v84
	v_add_u32_e32 v64, v120, v84
	v_ashrrev_i32_e32 v73, 31, v72
	v_ashrrev_i32_e32 v65, 31, v64
	v_lshlrev_b64 v[72:73], 13, v[72:73]
	v_lshlrev_b64 v[64:65], 13, v[64:65]
	v_lshl_add_u64 v[72:73], s[38:39], 0, v[72:73]
	v_lshl_add_u64 v[64:65], s[38:39], 0, v[64:65]
	v_lshl_add_u64 v[72:73], v[72:73], 0, s[0:1]
	v_lshl_add_u64 v[64:65], v[64:65], 0, s[0:1]
	v_lshl_add_u64 v[72:73], v[72:73], 0, v[140:141]
	v_lshl_add_u64 v[64:65], v[64:65], 0, v[108:109]
	v_cvt_pk_bf16_f32 v77, v82, v83
	v_cvt_pk_bf16_f32 v79, v74, v75
	flat_store_dwordx4 v[72:73], v[76:79]
	v_cvt_pk_bf16_f32 v71, v66, v67
	flat_store_dwordx4 v[64:65], v[68:71]
	v_add_u32_e32 v64, 0x80, v138
	v_cvt_pk_bf16_f32 v60, v60, v61
	v_cvt_pk_bf16_f32 v61, v62, v63
	v_cvt_pk_bf16_f32 v62, v56, v57
	v_add_u32_e32 v56, v122, v64
	v_cvt_pk_bf16_f32 v52, v52, v53
	v_cvt_pk_bf16_f32 v53, v54, v55
	v_cvt_pk_bf16_f32 v54, v44, v45
	v_add_u32_e32 v44, v120, v64
	v_ashrrev_i32_e32 v57, 31, v56
	v_ashrrev_i32_e32 v45, 31, v44
	v_lshlrev_b64 v[56:57], 13, v[56:57]
	v_lshlrev_b64 v[44:45], 13, v[44:45]
	v_lshl_add_u64 v[56:57], s[38:39], 0, v[56:57]
	v_lshl_add_u64 v[44:45], s[38:39], 0, v[44:45]
	v_lshl_add_u64 v[56:57], v[56:57], 0, s[0:1]
	v_lshl_add_u64 v[44:45], v[44:45], 0, s[0:1]
	v_lshl_add_u64 v[56:57], v[56:57], 0, v[140:141]
	v_lshl_add_u64 v[44:45], v[44:45], 0, v[108:109]
	v_cvt_pk_bf16_f32 v63, v58, v59
	flat_store_dwordx4 v[56:57], v[60:63]
	v_cvt_pk_bf16_f32 v55, v46, v47
	flat_store_dwordx4 v[44:45], v[52:55]
	v_cvt_pk_bf16_f32 v46, v40, v41
	v_cvt_pk_bf16_f32 v36, v36, v37
	v_cvt_pk_bf16_f32 v37, v38, v39
	v_cvt_pk_bf16_f32 v38, v28, v29
	v_cvt_pk_bf16_f32 v44, v48, v49
	s_nop 1
	v_add_u32_e32 v52, 0x90, v138
	v_add_u32_e32 v40, v122, v52
	v_add_u32_e32 v28, v120, v52
	v_ashrrev_i32_e32 v41, 31, v40
	v_ashrrev_i32_e32 v29, 31, v28
	v_lshlrev_b64 v[40:41], 13, v[40:41]
	v_lshlrev_b64 v[28:29], 13, v[28:29]
	v_lshl_add_u64 v[40:41], s[38:39], 0, v[40:41]
	v_lshl_add_u64 v[28:29], s[38:39], 0, v[28:29]
	v_lshl_add_u64 v[40:41], v[40:41], 0, s[0:1]
	v_lshl_add_u64 v[28:29], v[28:29], 0, s[0:1]
	v_lshl_add_u64 v[40:41], v[40:41], 0, v[140:141]
	v_lshl_add_u64 v[28:29], v[28:29], 0, v[108:109]
	v_cvt_pk_bf16_f32 v45, v50, v51
	v_cvt_pk_bf16_f32 v47, v42, v43
	flat_store_dwordx4 v[40:41], v[44:47]
	v_cvt_pk_bf16_f32 v39, v30, v31
	flat_store_dwordx4 v[28:29], v[36:39]
	v_cvt_pk_bf16_f32 v30, v24, v25
	v_cvt_pk_bf16_f32 v20, v20, v21
	v_cvt_pk_bf16_f32 v21, v22, v23
	v_cvt_pk_bf16_f32 v22, v12, v13
	v_cvt_pk_bf16_f32 v28, v32, v33
	s_nop 1
	v_add_u32_e32 v36, 0xa0, v138
	v_add_u32_e32 v24, v122, v36
	v_add_u32_e32 v12, v120, v36
	v_ashrrev_i32_e32 v25, 31, v24
	v_ashrrev_i32_e32 v13, 31, v12
	v_lshlrev_b64 v[24:25], 13, v[24:25]
	v_lshlrev_b64 v[12:13], 13, v[12:13]
	v_lshl_add_u64 v[24:25], s[38:39], 0, v[24:25]
	v_lshl_add_u64 v[12:13], s[38:39], 0, v[12:13]
	v_lshl_add_u64 v[24:25], v[24:25], 0, s[0:1]
	v_lshl_add_u64 v[12:13], v[12:13], 0, s[0:1]
	v_lshl_add_u64 v[24:25], v[24:25], 0, v[140:141]
	v_lshl_add_u64 v[12:13], v[12:13], 0, v[108:109]
	v_cvt_pk_bf16_f32 v29, v34, v35
	v_cvt_pk_bf16_f32 v31, v26, v27
	flat_store_dwordx4 v[24:25], v[28:31]
	v_cvt_pk_bf16_f32 v23, v14, v15
	flat_store_dwordx4 v[12:13], v[20:23]
	v_cvt_pk_bf16_f32 v14, v8, v9
	v_cvt_pk_bf16_f32 v4, v4, v5
	v_cvt_pk_bf16_f32 v5, v6, v7
	v_cvt_pk_bf16_f32 v6, v0, v1
	s_and_b64 vcc, exec, s[6:7]
	s_nop 0
	v_add_u32_e32 v20, 0xb0, v138
	v_add_u32_e32 v8, v122, v20
	v_add_u32_e32 v0, v120, v20
	v_ashrrev_i32_e32 v9, 31, v8
	v_ashrrev_i32_e32 v1, 31, v0
	v_lshlrev_b64 v[8:9], 13, v[8:9]
	v_lshlrev_b64 v[0:1], 13, v[0:1]
	v_lshl_add_u64 v[8:9], s[38:39], 0, v[8:9]
	v_lshl_add_u64 v[0:1], s[38:39], 0, v[0:1]
	v_lshl_add_u64 v[8:9], v[8:9], 0, s[0:1]
	v_lshl_add_u64 v[0:1], v[0:1], 0, s[0:1]
	v_lshl_add_u64 v[8:9], v[8:9], 0, v[140:141]
	v_lshl_add_u64 v[0:1], v[0:1], 0, v[108:109]
	s_mov_b32 s20, s12
	s_mov_b32 s40, s14
	s_mov_b64 s[64:65], s[10:11]
	s_mov_b64 s[44:45], s[8:9]
	v_readlane_b32 s89, v252, 11
	s_mov_b32 s81, 0x10000
	s_mov_b32 s88, 0x8000
	v_readlane_b32 s77, v252, 31
	v_cvt_pk_bf16_f32 v12, v16, v17
	v_cvt_pk_bf16_f32 v13, v18, v19
	v_cvt_pk_bf16_f32 v15, v10, v11
	flat_store_dwordx4 v[8:9], v[12:15]
	v_cvt_pk_bf16_f32 v7, v2, v3
	flat_store_dwordx4 v[0:1], v[4:7]
	s_cbranch_vccz .LBB0_192
	s_waitcnt vmcnt(0)
	s_cmpk_gt_u32 s49, 0xff
	s_cbranch_scc1 .LBB0_207
	s_barrier

.LBB0_275:
	s_add_u32 s0, s12, 0x100
	s_addc_u32 s1, s13, 0
	s_add_i32 s2, 0, 0x10000
	v_add_u32_e32 v138, s2, v154
	ds_read_b128 v[156:159], v138
	ds_read_b128 v[160:163], v138 offset:1024
	ds_read_b128 v[164:167], v138 offset:2048
	ds_read_b128 v[168:171], v138 offset:3072
	s_cmp_eq_u32 s65, 40
	s_cselect_b32 s15, s5, s1
	s_cselect_b32 s14, s4, s0
	s_cselect_b32 s11, s9, s64
	s_cselect_b32 s10, s8, s59
	s_add_i32 m0, s40, 0xc000
	ds_read_b128 v[172:175], v155
	ds_read_b128 v[176:179], v155 offset:1024
	ds_read_b128 v[180:183], v155 offset:2048
	ds_read_b128 v[184:187], v155 offset:3072
	ds_read_b128 v[188:191], v155 offset:4096
	ds_read_b128 v[192:195], v155 offset:5120
	ds_read_b128 v[196:199], v155 offset:6144
	global_load_lds_dwordx4 v136, s[12:13]
	s_add_i32 m0, s40, 0xe000
	ds_read_b128 v[200:203], v155 offset:7168
	global_load_lds_dwordx4 v134, s[12:13]
	s_waitcnt lgkmcnt(8)
	s_barrier
	s_waitcnt lgkmcnt(0)
	s_setprio 1
	v_mfma_f32_16x16x32_bf16 v[124:127], v[156:159], v[172:175], v[124:127]
	v_mfma_f32_16x16x32_bf16 v[120:123], v[164:167], v[172:175], v[120:123]
	v_mfma_f32_16x16x32_bf16 v[116:119], v[156:159], v[180:183], v[116:119]
	v_mfma_f32_16x16x32_bf16 v[108:111], v[164:167], v[180:183], v[108:111]
	v_mfma_f32_16x16x32_bf16 v[100:103], v[156:159], v[188:191], v[100:103]
	v_mfma_f32_16x16x32_bf16 v[92:95], v[164:167], v[188:191], v[92:95]
	v_mfma_f32_16x16x32_bf16 v[84:87], v[156:159], v[196:199], v[84:87]
	v_mfma_f32_16x16x32_bf16 v[76:79], v[164:167], v[196:199], v[76:79]
	v_mfma_f32_16x16x32_bf16 v[124:127], v[160:163], v[176:179], v[124:127]
	v_mfma_f32_16x16x32_bf16 v[120:123], v[168:171], v[176:179], v[120:123]
	v_mfma_f32_16x16x32_bf16 v[116:119], v[160:163], v[184:187], v[116:119]
	v_mfma_f32_16x16x32_bf16 v[108:111], v[168:171], v[184:187], v[108:111]
	v_mfma_f32_16x16x32_bf16 v[100:103], v[160:163], v[192:195], v[100:103]
	v_mfma_f32_16x16x32_bf16 v[92:95], v[168:171], v[192:195], v[92:95]
	v_mfma_f32_16x16x32_bf16 v[84:87], v[160:163], v[200:203], v[84:87]
	v_mfma_f32_16x16x32_bf16 v[76:79], v[168:171], v[200:203], v[76:79]
	s_setprio 0
	s_barrier
	s_add_i32 s18, 0, 0x14000
	v_add_u32_e32 v138, s18, v154
	s_add_i32 s2, s2, s39
	ds_read_b128 v[204:207], v138
	ds_read_b128 v[208:211], v138 offset:1024
	ds_read_b128 v[228:231], v138 offset:2048
	s_mov_b32 m0, s2
	ds_read_b128 v[232:235], v138 offset:3072
	global_load_lds_dwordx4 v140, s[10:11]
	s_add_i32 m0, s2, 0x2000
	s_nop 0
	global_load_lds_dwordx4 v132, s[10:11]
	s_barrier
	s_waitcnt lgkmcnt(0)
	s_setprio 1
	v_mfma_f32_16x16x32_bf16 v[112:115], v[204:207], v[172:175], v[112:115]
	v_mfma_f32_16x16x32_bf16 v[104:107], v[228:231], v[172:175], v[104:107]
	v_mfma_f32_16x16x32_bf16 v[96:99], v[204:207], v[180:183], v[96:99]
	v_mfma_f32_16x16x32_bf16 v[88:91], v[228:231], v[180:183], v[88:91]
	v_mfma_f32_16x16x32_bf16 v[80:83], v[204:207], v[188:191], v[80:83]
	v_mfma_f32_16x16x32_bf16 v[72:75], v[228:231], v[188:191], v[72:75]
	v_mfma_f32_16x16x32_bf16 v[68:71], v[204:207], v[196:199], v[68:71]
	v_mfma_f32_16x16x32_bf16 v[64:67], v[228:231], v[196:199], v[64:67]
	v_mfma_f32_16x16x32_bf16 v[112:115], v[208:211], v[176:179], v[112:115]
	v_mfma_f32_16x16x32_bf16 v[104:107], v[232:235], v[176:179], v[104:107]
	v_mfma_f32_16x16x32_bf16 v[96:99], v[208:211], v[184:187], v[96:99]
	v_mfma_f32_16x16x32_bf16 v[88:91], v[232:235], v[184:187], v[88:91]
	v_mfma_f32_16x16x32_bf16 v[80:83], v[208:211], v[192:195], v[80:83]
	v_mfma_f32_16x16x32_bf16 v[72:75], v[232:235], v[192:195], v[72:75]
	v_mfma_f32_16x16x32_bf16 v[68:71], v[208:211], v[200:203], v[68:71]
	v_mfma_f32_16x16x32_bf16 v[64:67], v[232:235], v[200:203], v[64:67]
	s_setprio 0
	s_mov_b32 m0, s40
	s_barrier
	ds_read_b128 v[172:175], v155 offset:16384
	ds_read_b128 v[176:179], v155 offset:17408
	ds_read_b128 v[180:183], v155 offset:18432
	ds_read_b128 v[184:187], v155 offset:19456
	ds_read_b128 v[188:191], v155 offset:20480
	ds_read_b128 v[192:195], v155 offset:21504
	ds_read_b128 v[196:199], v155 offset:22528
	global_load_lds_dwordx4 v128, s[14:15]
	s_mov_b32 m0, s41
	ds_read_b128 v[200:203], v155 offset:23552
	global_load_lds_dwordx4 v130, s[14:15]
	s_barrier
	s_waitcnt lgkmcnt(0)
	s_setprio 1
	v_mfma_f32_16x16x32_bf16 v[60:63], v[156:159], v[172:175], v[60:63]
	v_mfma_f32_16x16x32_bf16 v[56:59], v[164:167], v[172:175], v[56:59]
	v_mfma_f32_16x16x32_bf16 v[52:55], v[156:159], v[180:183], v[52:55]
	v_mfma_f32_16x16x32_bf16 v[44:47], v[164:167], v[180:183], v[44:47]
	v_mfma_f32_16x16x32_bf16 v[36:39], v[156:159], v[188:191], v[36:39]
	v_mfma_f32_16x16x32_bf16 v[28:31], v[164:167], v[188:191], v[28:31]
	v_mfma_f32_16x16x32_bf16 v[20:23], v[156:159], v[196:199], v[20:23]
	v_mfma_f32_16x16x32_bf16 v[12:15], v[164:167], v[196:199], v[12:15]
	v_mfma_f32_16x16x32_bf16 v[60:63], v[160:163], v[176:179], v[60:63]
	v_mfma_f32_16x16x32_bf16 v[56:59], v[168:171], v[176:179], v[56:59]
	v_mfma_f32_16x16x32_bf16 v[52:55], v[160:163], v[184:187], v[52:55]
	v_mfma_f32_16x16x32_bf16 v[44:47], v[168:171], v[184:187], v[44:47]
	v_mfma_f32_16x16x32_bf16 v[36:39], v[160:163], v[192:195], v[36:39]
	v_mfma_f32_16x16x32_bf16 v[28:31], v[168:171], v[192:195], v[28:31]
	v_mfma_f32_16x16x32_bf16 v[20:23], v[160:163], v[200:203], v[20:23]
	v_mfma_f32_16x16x32_bf16 v[12:15], v[168:171], v[200:203], v[12:15]
	s_setprio 0
	s_barrier
	s_add_u32 s12, s10, 0xb0000
	s_addc_u32 s13, s11, 0
	s_add_i32 s2, s18, s39
	s_mov_b32 m0, s2
	s_nop 0
	global_load_lds_dwordx4 v140, s[12:13]
	s_add_i32 m0, s2, 0x2000
	s_nop 0
	global_load_lds_dwordx4 v132, s[12:13]
	s_waitcnt vmcnt(6)
	s_barrier
	s_setprio 1
	v_mfma_f32_16x16x32_bf16 v[48:51], v[204:207], v[172:175], v[48:51]
	v_mfma_f32_16x16x32_bf16 v[40:43], v[228:231], v[172:175], v[40:43]
	v_mfma_f32_16x16x32_bf16 v[32:35], v[204:207], v[180:183], v[32:35]
	v_mfma_f32_16x16x32_bf16 v[24:27], v[228:231], v[180:183], v[24:27]
	v_mfma_f32_16x16x32_bf16 v[16:19], v[204:207], v[188:191], v[16:19]
	v_mfma_f32_16x16x32_bf16 v[8:11], v[228:231], v[188:191], v[8:11]
	v_mfma_f32_16x16x32_bf16 v[4:7], v[204:207], v[196:199], v[4:7]
	v_mfma_f32_16x16x32_bf16 v[0:3], v[228:231], v[196:199], v[0:3]
	v_mfma_f32_16x16x32_bf16 v[48:51], v[208:211], v[176:179], v[48:51]
	v_mfma_f32_16x16x32_bf16 v[40:43], v[232:235], v[176:179], v[40:43]
	v_mfma_f32_16x16x32_bf16 v[32:35], v[208:211], v[184:187], v[32:35]
	v_mfma_f32_16x16x32_bf16 v[24:27], v[232:235], v[184:187], v[24:27]
	v_mfma_f32_16x16x32_bf16 v[16:19], v[208:211], v[192:195], v[16:19]
	v_mfma_f32_16x16x32_bf16 v[8:11], v[232:235], v[192:195], v[8:11]
	v_mfma_f32_16x16x32_bf16 v[4:7], v[208:211], v[200:203], v[4:7]
	v_mfma_f32_16x16x32_bf16 v[0:3], v[232:235], v[200:203], v[0:3]
	s_setprio 0
	s_add_i32 s2, 0, 0x18000
	v_add_u32_e32 v168, s2, v154
	s_barrier
	ds_read_b128 v[156:159], v168
	ds_read_b128 v[160:163], v168 offset:1024
	ds_read_b128 v[164:167], v168 offset:2048
	ds_read_b128 v[168:171], v168 offset:3072
	s_add_u32 s12, s14, 0xb0000
	s_addc_u32 s13, s15, 0
	s_mov_b32 m0, s44
	ds_read_b128 v[172:175], v155 offset:32768
	ds_read_b128 v[176:179], v155 offset:33792
	ds_read_b128 v[180:183], v155 offset:34816
	ds_read_b128 v[184:187], v155 offset:35840
	ds_read_b128 v[188:191], v155 offset:36864
	ds_read_b128 v[192:195], v155 offset:37888
	ds_read_b128 v[196:199], v155 offset:38912
	global_load_lds_dwordx4 v128, s[12:13]
	s_mov_b32 m0, s45
	ds_read_b128 v[200:203], v155 offset:39936
	global_load_lds_dwordx4 v130, s[12:13]
	s_waitcnt lgkmcnt(8)
	s_barrier
	s_waitcnt lgkmcnt(0)
	s_setprio 1
	v_mfma_f32_16x16x32_bf16 v[124:127], v[156:159], v[172:175], v[124:127]
	v_mfma_f32_16x16x32_bf16 v[120:123], v[164:167], v[172:175], v[120:123]
	v_mfma_f32_16x16x32_bf16 v[116:119], v[156:159], v[180:183], v[116:119]
	v_mfma_f32_16x16x32_bf16 v[108:111], v[164:167], v[180:183], v[108:111]
	v_mfma_f32_16x16x32_bf16 v[100:103], v[156:159], v[188:191], v[100:103]
	v_mfma_f32_16x16x32_bf16 v[92:95], v[164:167], v[188:191], v[92:95]
	v_mfma_f32_16x16x32_bf16 v[84:87], v[156:159], v[196:199], v[84:87]
	v_mfma_f32_16x16x32_bf16 v[76:79], v[164:167], v[196:199], v[76:79]
	v_mfma_f32_16x16x32_bf16 v[124:127], v[160:163], v[176:179], v[124:127]
	v_mfma_f32_16x16x32_bf16 v[120:123], v[168:171], v[176:179], v[120:123]
	v_mfma_f32_16x16x32_bf16 v[116:119], v[160:163], v[184:187], v[116:119]
	v_mfma_f32_16x16x32_bf16 v[108:111], v[168:171], v[184:187], v[108:111]
	v_mfma_f32_16x16x32_bf16 v[100:103], v[160:163], v[192:195], v[100:103]
	v_mfma_f32_16x16x32_bf16 v[92:95], v[168:171], v[192:195], v[92:95]
	v_mfma_f32_16x16x32_bf16 v[84:87], v[160:163], v[200:203], v[84:87]
	v_mfma_f32_16x16x32_bf16 v[76:79], v[168:171], v[200:203], v[76:79]
	s_setprio 0
	s_barrier
	s_add_i32 s12, 0, 0x1c000
	s_add_i32 s2, s2, s39
	v_add_u32_e32 v232, s12, v154
	s_mov_b32 m0, s2
	ds_read_b128 v[204:207], v232
	ds_read_b128 v[208:211], v232 offset:1024
	ds_read_b128 v[228:231], v232 offset:2048
	ds_read_b128 v[232:235], v232 offset:3072
	s_add_u32 s100, s10, 0x80
	s_addc_u32 s101, s11, 0
	global_load_lds_dwordx4 v140, s[100:101]
	s_add_i32 m0, s2, 0x2000
	s_nop 0
	global_load_lds_dwordx4 v132, s[100:101]
	s_barrier
	s_waitcnt lgkmcnt(0)
	s_setprio 1
	v_mfma_f32_16x16x32_bf16 v[112:115], v[204:207], v[172:175], v[112:115]
	v_mfma_f32_16x16x32_bf16 v[104:107], v[228:231], v[172:175], v[104:107]
	v_mfma_f32_16x16x32_bf16 v[96:99], v[204:207], v[180:183], v[96:99]
	v_mfma_f32_16x16x32_bf16 v[88:91], v[228:231], v[180:183], v[88:91]
	v_mfma_f32_16x16x32_bf16 v[80:83], v[204:207], v[188:191], v[80:83]
	v_mfma_f32_16x16x32_bf16 v[72:75], v[228:231], v[188:191], v[72:75]
	v_mfma_f32_16x16x32_bf16 v[68:71], v[204:207], v[196:199], v[68:71]
	v_mfma_f32_16x16x32_bf16 v[64:67], v[228:231], v[196:199], v[64:67]
	v_mfma_f32_16x16x32_bf16 v[112:115], v[208:211], v[176:179], v[112:115]
	v_mfma_f32_16x16x32_bf16 v[104:107], v[232:235], v[176:179], v[104:107]
	v_mfma_f32_16x16x32_bf16 v[96:99], v[208:211], v[184:187], v[96:99]
	v_mfma_f32_16x16x32_bf16 v[88:91], v[232:235], v[184:187], v[88:91]
	v_mfma_f32_16x16x32_bf16 v[80:83], v[208:211], v[192:195], v[80:83]
	v_mfma_f32_16x16x32_bf16 v[72:75], v[232:235], v[192:195], v[72:75]
	v_mfma_f32_16x16x32_bf16 v[68:71], v[208:211], v[200:203], v[68:71]
	v_mfma_f32_16x16x32_bf16 v[64:67], v[232:235], v[200:203], v[64:67]
	s_setprio 0
	s_mov_b32 m0, s49
	s_barrier
	ds_read_b128 v[172:175], v155 offset:49152
	ds_read_b128 v[176:179], v155 offset:50176
	ds_read_b128 v[180:183], v155 offset:51200
	ds_read_b128 v[184:187], v155 offset:52224
	ds_read_b128 v[188:191], v155 offset:53248
	ds_read_b128 v[192:195], v155 offset:54272
	ds_read_b128 v[196:199], v155 offset:55296
	ds_read_b128 v[200:203], v155 offset:56320
	s_add_u32 s100, s14, 0x80
	s_addc_u32 s101, s15, 0
	global_load_lds_dwordx4 v128, s[100:101]
	s_mov_b32 m0, s20
	s_nop 0
	global_load_lds_dwordx4 v130, s[100:101]
	s_barrier
	s_waitcnt lgkmcnt(0)
	s_setprio 1
	v_mfma_f32_16x16x32_bf16 v[60:63], v[156:159], v[172:175], v[60:63]
	v_mfma_f32_16x16x32_bf16 v[56:59], v[164:167], v[172:175], v[56:59]
	v_mfma_f32_16x16x32_bf16 v[52:55], v[156:159], v[180:183], v[52:55]
	v_mfma_f32_16x16x32_bf16 v[44:47], v[164:167], v[180:183], v[44:47]
	v_mfma_f32_16x16x32_bf16 v[36:39], v[156:159], v[188:191], v[36:39]
	v_mfma_f32_16x16x32_bf16 v[28:31], v[164:167], v[188:191], v[28:31]
	v_mfma_f32_16x16x32_bf16 v[20:23], v[156:159], v[196:199], v[20:23]
	v_mfma_f32_16x16x32_bf16 v[12:15], v[164:167], v[196:199], v[12:15]
	v_mfma_f32_16x16x32_bf16 v[60:63], v[160:163], v[176:179], v[60:63]
	v_mfma_f32_16x16x32_bf16 v[56:59], v[168:171], v[176:179], v[56:59]
	v_mfma_f32_16x16x32_bf16 v[52:55], v[160:163], v[184:187], v[52:55]
	v_mfma_f32_16x16x32_bf16 v[44:47], v[168:171], v[184:187], v[44:47]
	v_mfma_f32_16x16x32_bf16 v[36:39], v[160:163], v[192:195], v[36:39]
	v_mfma_f32_16x16x32_bf16 v[28:31], v[168:171], v[192:195], v[28:31]
	v_mfma_f32_16x16x32_bf16 v[20:23], v[160:163], v[200:203], v[20:23]
	v_mfma_f32_16x16x32_bf16 v[12:15], v[168:171], v[200:203], v[12:15]
	s_setprio 0
	s_barrier
	s_add_u32 s10, s10, 0xb0080
	s_addc_u32 s11, s11, 0
	s_add_i32 s2, s12, s39
	s_mov_b32 m0, s2
	s_nop 0
	global_load_lds_dwordx4 v140, s[10:11]
	s_add_i32 m0, s2, 0x2000
	s_nop 0
	global_load_lds_dwordx4 v132, s[10:11]
	s_waitcnt vmcnt(6)
	s_barrier
	s_setprio 1
	v_mfma_f32_16x16x32_bf16 v[48:51], v[204:207], v[172:175], v[48:51]
	v_mfma_f32_16x16x32_bf16 v[40:43], v[228:231], v[172:175], v[40:43]
	v_mfma_f32_16x16x32_bf16 v[32:35], v[204:207], v[180:183], v[32:35]
	v_mfma_f32_16x16x32_bf16 v[24:27], v[228:231], v[180:183], v[24:27]
	v_mfma_f32_16x16x32_bf16 v[16:19], v[204:207], v[188:191], v[16:19]
	v_mfma_f32_16x16x32_bf16 v[8:11], v[228:231], v[188:191], v[8:11]
	v_mfma_f32_16x16x32_bf16 v[4:7], v[204:207], v[196:199], v[4:7]
	v_mfma_f32_16x16x32_bf16 v[0:3], v[228:231], v[196:199], v[0:3]
	v_mfma_f32_16x16x32_bf16 v[48:51], v[208:211], v[176:179], v[48:51]
	v_mfma_f32_16x16x32_bf16 v[40:43], v[232:235], v[176:179], v[40:43]
	v_mfma_f32_16x16x32_bf16 v[32:35], v[208:211], v[184:187], v[32:35]
	v_mfma_f32_16x16x32_bf16 v[24:27], v[232:235], v[184:187], v[24:27]
	v_mfma_f32_16x16x32_bf16 v[16:19], v[208:211], v[192:195], v[16:19]
	v_mfma_f32_16x16x32_bf16 v[8:11], v[232:235], v[192:195], v[8:11]
	v_mfma_f32_16x16x32_bf16 v[4:7], v[208:211], v[200:203], v[4:7]
	v_mfma_f32_16x16x32_bf16 v[0:3], v[232:235], v[200:203], v[0:3]
	s_setprio 0
	s_add_i32 s65, s65, 2
	s_add_u32 s59, s59, 0x100
	s_addc_u32 s64, s64, 0
	s_cmp_gt_u32 s65, 41
	s_mov_b64 s[12:13], s[0:1]
	s_barrier
	s_cbranch_scc0 .LBB0_275
	s_lshl_b32 s0, s57, 8
	v_mbcnt_lo_u32_b32 v139, -1, 0
	v_mbcnt_hi_u32_b32 v139, -1, v139
	s_lshl_b32 s1, s58, 8
	v_ashrrev_i32_e32 v138, 1, v139
	s_add_i32 s0, s0, s46
	v_and_b32_e32 v138, -8, v138
	s_or_b32 s1, s1, s48
	v_and_or_b32 v156, v139, 15, s0
	v_add_u32_e32 v138, s1, v138
	v_ashrrev_i32_e32 v157, 31, v156
	v_ashrrev_i32_e32 v139, 31, v138
	v_lshlrev_b64 v[158:159], 11, v[156:157]
	v_lshl_add_u64 v[158:159], s[24:25], 0, v[158:159]
	v_lshlrev_b64 v[160:161], 1, v[138:139]
	v_lshl_add_u64 v[138:139], v[158:159], 0, v[160:161]
	v_cvt_pk_bf16_f32 v60, v60, v61
	v_cvt_pk_bf16_f32 v61, v62, v63
	v_cvt_pk_bf16_f32 v62, v56, v57
	v_add_co_u32_e32 v56, vcc, s19, v138
	v_cvt_pk_bf16_f32 v112, v112, v113
	v_cvt_pk_bf16_f32 v113, v114, v115
	v_cvt_pk_bf16_f32 v114, v104, v105
	v_or_b32_e32 v104, 16, v156
	s_nop 0
	v_addc_co_u32_e32 v57, vcc, 0, v139, vcc
	v_cvt_pk_bf16_f32 v48, v48, v49
	v_cvt_pk_bf16_f32 v49, v50, v51
	v_cvt_pk_bf16_f32 v51, v42, v43
	v_cvt_pk_bf16_f32 v42, v44, v45
	v_add_co_u32_e32 v44, vcc, s30, v138
	v_ashrrev_i32_e32 v105, 31, v104
	v_cvt_pk_bf16_f32 v96, v96, v97
	v_cvt_pk_bf16_f32 v97, v98, v99
	v_cvt_pk_bf16_f32 v98, v88, v89
	v_or_b32_e32 v88, 32, v156
	v_addc_co_u32_e32 v45, vcc, 0, v139, vcc
	v_lshlrev_b64 v[104:105], 11, v[104:105]
	v_ashrrev_i32_e32 v89, 31, v88
	v_cvt_pk_bf16_f32 v80, v80, v81
	v_cvt_pk_bf16_f32 v81, v82, v83
	v_cvt_pk_bf16_f32 v82, v72, v73
	v_or_b32_e32 v72, 48, v156
	s_mov_b64 s[0:1], 0x40000
	v_cvt_pk_bf16_f32 v32, v32, v33
	v_cvt_pk_bf16_f32 v33, v34, v35
	v_cvt_pk_bf16_f32 v35, v26, v27
	v_cvt_pk_bf16_f32 v26, v28, v29
	v_add_co_u32_e32 v28, vcc, s31, v138
	v_lshl_add_u64 v[104:105], s[24:25], 0, v[104:105]
	v_lshlrev_b64 v[88:89], 11, v[88:89]
	v_ashrrev_i32_e32 v73, 31, v72
	v_cvt_pk_bf16_f32 v68, v68, v69
	v_cvt_pk_bf16_f32 v69, v70, v71
	v_cvt_pk_bf16_f32 v70, v64, v65
	v_lshl_add_u64 v[64:65], v[138:139], 0, s[0:1]
	s_mov_b64 s[0:1], 0x48000
	v_addc_co_u32_e32 v29, vcc, 0, v139, vcc
	v_cvt_pk_bf16_f32 v115, v106, v107
	flat_store_dwordx4 v[138:139], v[112:115] offset:256
	v_lshl_add_u64 v[88:89], s[24:25], 0, v[88:89]
	v_lshlrev_b64 v[72:73], 11, v[72:73]
	v_lshl_add_u64 v[112:113], v[104:105], 0, v[160:161]
	v_cvt_pk_bf16_f32 v50, v40, v41
	flat_store_dwordx4 v[64:65], v[48:51] offset:256
	v_cvt_pk_bf16_f32 v16, v16, v17
	v_cvt_pk_bf16_f32 v17, v18, v19
	v_cvt_pk_bf16_f32 v19, v10, v11
	v_cvt_pk_bf16_f32 v10, v12, v13
	v_add_co_u32_e32 v12, vcc, s42, v138
	s_nop 0
	v_lshl_add_u64 v[48:49], v[138:139], 0, s[0:1]
	s_mov_b64 s[0:1], 0x50000
	v_cvt_pk_bf16_f32 v99, v90, v91
	flat_store_dwordx4 v[112:113], v[96:99] offset:256
	v_lshl_add_u64 v[72:73], s[24:25], 0, v[72:73]
	v_cvt_pk_bf16_f32 v34, v24, v25
	flat_store_dwordx4 v[48:49], v[32:35] offset:256
	v_lshl_add_u64 v[96:97], v[88:89], 0, v[160:161]
	v_addc_co_u32_e32 v13, vcc, 0, v139, vcc
	v_lshl_add_u64 v[32:33], v[138:139], 0, s[0:1]
	s_mov_b64 s[0:1], 0x58000
	v_cvt_pk_bf16_f32 v83, v74, v75
	flat_store_dwordx4 v[96:97], v[80:83] offset:256
	v_cvt_pk_bf16_f32 v18, v8, v9
	flat_store_dwordx4 v[32:33], v[16:19] offset:256
	s_and_b64 vcc, exec, s[6:7]
	v_lshl_add_u64 v[80:81], v[72:73], 0, v[160:161]
	v_lshl_add_u64 v[16:17], v[138:139], 0, s[0:1]
	s_mov_b32 s58, s52
	s_mov_b32 s57, s51
	s_mov_b64 s[0:1], s[8:9]
	s_mov_b64 s[12:13], s[4:5]
	v_cvt_pk_bf16_f32 v124, v124, v125
	v_cvt_pk_bf16_f32 v125, v126, v127
	v_cvt_pk_bf16_f32 v126, v120, v121
	v_cvt_pk_bf16_f32 v127, v122, v123
	flat_store_dwordx4 v[138:139], v[124:127]
	v_cvt_pk_bf16_f32 v104, v116, v117
	v_cvt_pk_bf16_f32 v105, v118, v119
	v_cvt_pk_bf16_f32 v106, v108, v109
	v_cvt_pk_bf16_f32 v107, v110, v111
	flat_store_dwordx4 v[112:113], v[104:107]
	v_cvt_pk_bf16_f32 v88, v100, v101
	v_cvt_pk_bf16_f32 v89, v102, v103
	v_cvt_pk_bf16_f32 v90, v92, v93
	v_cvt_pk_bf16_f32 v91, v94, v95
	flat_store_dwordx4 v[96:97], v[88:91]
	v_cvt_pk_bf16_f32 v72, v84, v85
	v_cvt_pk_bf16_f32 v73, v86, v87
	v_cvt_pk_bf16_f32 v74, v76, v77
	v_cvt_pk_bf16_f32 v75, v78, v79
	flat_store_dwordx4 v[80:81], v[72:75]
	v_cvt_pk_bf16_f32 v71, v66, v67
	flat_store_dwordx4 v[80:81], v[68:71] offset:256
	v_cvt_pk_bf16_f32 v63, v58, v59
	flat_store_dwordx4 v[56:57], v[60:63]
	v_cvt_pk_bf16_f32 v40, v52, v53
	v_cvt_pk_bf16_f32 v41, v54, v55
	v_cvt_pk_bf16_f32 v43, v46, v47
	flat_store_dwordx4 v[44:45], v[40:43]
	v_cvt_pk_bf16_f32 v24, v36, v37
	v_cvt_pk_bf16_f32 v25, v38, v39
	v_cvt_pk_bf16_f32 v27, v30, v31
	flat_store_dwordx4 v[28:29], v[24:27]
	v_cvt_pk_bf16_f32 v8, v20, v21
	v_cvt_pk_bf16_f32 v9, v22, v23
	v_cvt_pk_bf16_f32 v11, v14, v15
	flat_store_dwordx4 v[12:13], v[8:11]
	v_cvt_pk_bf16_f32 v4, v4, v5
	v_cvt_pk_bf16_f32 v5, v6, v7
	v_cvt_pk_bf16_f32 v6, v0, v1
	v_cvt_pk_bf16_f32 v7, v2, v3
	flat_store_dwordx4 v[16:17], v[4:7] offset:256
	s_cbranch_vccz .LBB0_264
	s_waitcnt vmcnt(0)
	s_cmpk_gt_u32 s17, 0xff
	s_cbranch_scc1 .LBB0_279
	s_barrier

.LBB0_289:
	s_add_u32 s0, s16, 0xfffc0080
	s_addc_u32 s1, s17, -1
	s_add_i32 s2, 0, 0x10000
	v_add_u32_e32 v138, s2, v154
	ds_read_b128 v[156:159], v138
	ds_read_b128 v[160:163], v138 offset:1024
	ds_read_b128 v[164:167], v138 offset:2048
	ds_read_b128 v[168:171], v138 offset:3072
	s_cmp_eq_u32 s21, 12
	s_cselect_b32 s37, s11, s1
	s_cselect_b32 s36, s10, s0
	s_cselect_b32 s1, s13, s9
	s_cselect_b32 s0, s12, s5
	s_add_i32 m0, s15, 0xc000
	ds_read_b128 v[172:175], v155
	ds_read_b128 v[176:179], v155 offset:1024
	ds_read_b128 v[180:183], v155 offset:2048
	ds_read_b128 v[184:187], v155 offset:3072
	ds_read_b128 v[188:191], v155 offset:4096
	ds_read_b128 v[192:195], v155 offset:5120
	ds_read_b128 v[196:199], v155 offset:6144
	global_load_lds_dwordx4 v136, s[16:17]
	s_add_i32 m0, s15, 0xe000
	ds_read_b128 v[200:203], v155 offset:7168
	global_load_lds_dwordx4 v134, s[16:17]
	s_waitcnt lgkmcnt(8)
	s_barrier
	s_waitcnt lgkmcnt(0)
	s_setprio 1
	v_mfma_f32_16x16x32_bf16 v[124:127], v[156:159], v[172:175], v[124:127]
	v_mfma_f32_16x16x32_bf16 v[120:123], v[164:167], v[172:175], v[120:123]
	v_mfma_f32_16x16x32_bf16 v[108:111], v[156:159], v[180:183], v[108:111]
	v_mfma_f32_16x16x32_bf16 v[104:107], v[164:167], v[180:183], v[104:107]
	v_mfma_f32_16x16x32_bf16 v[92:95], v[156:159], v[188:191], v[92:95]
	v_mfma_f32_16x16x32_bf16 v[88:91], v[164:167], v[188:191], v[88:91]
	v_mfma_f32_16x16x32_bf16 v[76:79], v[156:159], v[196:199], v[76:79]
	v_mfma_f32_16x16x32_bf16 v[72:75], v[164:167], v[196:199], v[72:75]
	v_mfma_f32_16x16x32_bf16 v[124:127], v[160:163], v[176:179], v[124:127]
	v_mfma_f32_16x16x32_bf16 v[120:123], v[168:171], v[176:179], v[120:123]
	v_mfma_f32_16x16x32_bf16 v[108:111], v[160:163], v[184:187], v[108:111]
	v_mfma_f32_16x16x32_bf16 v[104:107], v[168:171], v[184:187], v[104:107]
	v_mfma_f32_16x16x32_bf16 v[92:95], v[160:163], v[192:195], v[92:95]
	v_mfma_f32_16x16x32_bf16 v[88:91], v[168:171], v[192:195], v[88:91]
	v_mfma_f32_16x16x32_bf16 v[76:79], v[160:163], v[200:203], v[76:79]
	v_mfma_f32_16x16x32_bf16 v[72:75], v[168:171], v[200:203], v[72:75]
	s_setprio 0
	s_barrier
	s_add_i32 s30, 0, 0x14000
	v_add_u32_e32 v138, s30, v154
	s_add_i32 s2, s2, s44
	ds_read_b128 v[204:207], v138
	ds_read_b128 v[208:211], v138 offset:1024
	ds_read_b128 v[228:231], v138 offset:2048
	s_mov_b32 m0, s2
	ds_read_b128 v[232:235], v138 offset:3072
	global_load_lds_dwordx4 v140, s[0:1]
	s_add_i32 m0, s2, 0x2000
	s_nop 0
	global_load_lds_dwordx4 v128, s[0:1]
	s_barrier
	s_waitcnt lgkmcnt(0)
	s_setprio 1
	v_mfma_f32_16x16x32_bf16 v[116:119], v[204:207], v[172:175], v[116:119]
	v_mfma_f32_16x16x32_bf16 v[112:115], v[228:231], v[172:175], v[112:115]
	v_mfma_f32_16x16x32_bf16 v[100:103], v[204:207], v[180:183], v[100:103]
	v_mfma_f32_16x16x32_bf16 v[96:99], v[228:231], v[180:183], v[96:99]
	v_mfma_f32_16x16x32_bf16 v[84:87], v[204:207], v[188:191], v[84:87]
	v_mfma_f32_16x16x32_bf16 v[80:83], v[228:231], v[188:191], v[80:83]
	v_mfma_f32_16x16x32_bf16 v[68:71], v[204:207], v[196:199], v[68:71]
	v_mfma_f32_16x16x32_bf16 v[64:67], v[228:231], v[196:199], v[64:67]
	v_mfma_f32_16x16x32_bf16 v[116:119], v[208:211], v[176:179], v[116:119]
	v_mfma_f32_16x16x32_bf16 v[112:115], v[232:235], v[176:179], v[112:115]
	v_mfma_f32_16x16x32_bf16 v[100:103], v[208:211], v[184:187], v[100:103]
	v_mfma_f32_16x16x32_bf16 v[96:99], v[232:235], v[184:187], v[96:99]
	v_mfma_f32_16x16x32_bf16 v[84:87], v[208:211], v[192:195], v[84:87]
	v_mfma_f32_16x16x32_bf16 v[80:83], v[232:235], v[192:195], v[80:83]
	v_mfma_f32_16x16x32_bf16 v[68:71], v[208:211], v[200:203], v[68:71]
	v_mfma_f32_16x16x32_bf16 v[64:67], v[232:235], v[200:203], v[64:67]
	s_setprio 0
	s_mov_b32 m0, s15
	s_barrier
	ds_read_b128 v[172:175], v155 offset:16384
	ds_read_b128 v[176:179], v155 offset:17408
	ds_read_b128 v[180:183], v155 offset:18432
	ds_read_b128 v[184:187], v155 offset:19456
	ds_read_b128 v[188:191], v155 offset:20480
	ds_read_b128 v[192:195], v155 offset:21504
	ds_read_b128 v[196:199], v155 offset:22528
	global_load_lds_dwordx4 v132, s[36:37]
	s_mov_b32 m0, s45
	ds_read_b128 v[200:203], v155 offset:23552
	global_load_lds_dwordx4 v130, s[36:37]
	s_barrier
	s_waitcnt lgkmcnt(0)
	s_setprio 1
	v_mfma_f32_16x16x32_bf16 v[60:63], v[156:159], v[172:175], v[60:63]
	v_mfma_f32_16x16x32_bf16 v[56:59], v[164:167], v[172:175], v[56:59]
	v_mfma_f32_16x16x32_bf16 v[44:47], v[156:159], v[180:183], v[44:47]
	v_mfma_f32_16x16x32_bf16 v[40:43], v[164:167], v[180:183], v[40:43]
	v_mfma_f32_16x16x32_bf16 v[28:31], v[156:159], v[188:191], v[28:31]
	v_mfma_f32_16x16x32_bf16 v[24:27], v[164:167], v[188:191], v[24:27]
	v_mfma_f32_16x16x32_bf16 v[12:15], v[156:159], v[196:199], v[12:15]
	v_mfma_f32_16x16x32_bf16 v[8:11], v[164:167], v[196:199], v[8:11]
	v_mfma_f32_16x16x32_bf16 v[60:63], v[160:163], v[176:179], v[60:63]
	v_mfma_f32_16x16x32_bf16 v[56:59], v[168:171], v[176:179], v[56:59]
	v_mfma_f32_16x16x32_bf16 v[44:47], v[160:163], v[184:187], v[44:47]
	v_mfma_f32_16x16x32_bf16 v[40:43], v[168:171], v[184:187], v[40:43]
	v_mfma_f32_16x16x32_bf16 v[28:31], v[160:163], v[192:195], v[28:31]
	v_mfma_f32_16x16x32_bf16 v[24:27], v[168:171], v[192:195], v[24:27]
	v_mfma_f32_16x16x32_bf16 v[12:15], v[160:163], v[200:203], v[12:15]
	v_mfma_f32_16x16x32_bf16 v[8:11], v[168:171], v[200:203], v[8:11]
	s_setprio 0
	s_barrier
	s_add_u32 s18, s0, 0x40000
	s_addc_u32 s19, s1, 0
	s_add_i32 s2, s30, s44
	s_mov_b32 m0, s2
	s_nop 0
	global_load_lds_dwordx4 v140, s[18:19]
	s_add_i32 m0, s2, 0x2000
	s_nop 0
	global_load_lds_dwordx4 v128, s[18:19]
	s_waitcnt vmcnt(6)
	s_barrier
	s_setprio 1
	v_mfma_f32_16x16x32_bf16 v[52:55], v[204:207], v[172:175], v[52:55]
	v_mfma_f32_16x16x32_bf16 v[48:51], v[228:231], v[172:175], v[48:51]
	v_mfma_f32_16x16x32_bf16 v[36:39], v[204:207], v[180:183], v[36:39]
	v_mfma_f32_16x16x32_bf16 v[32:35], v[228:231], v[180:183], v[32:35]
	v_mfma_f32_16x16x32_bf16 v[20:23], v[204:207], v[188:191], v[20:23]
	v_mfma_f32_16x16x32_bf16 v[16:19], v[228:231], v[188:191], v[16:19]
	v_mfma_f32_16x16x32_bf16 v[4:7], v[204:207], v[196:199], v[4:7]
	v_mfma_f32_16x16x32_bf16 v[0:3], v[228:231], v[196:199], v[0:3]
	v_mfma_f32_16x16x32_bf16 v[52:55], v[208:211], v[176:179], v[52:55]
	v_mfma_f32_16x16x32_bf16 v[48:51], v[232:235], v[176:179], v[48:51]
	v_mfma_f32_16x16x32_bf16 v[36:39], v[208:211], v[184:187], v[36:39]
	v_mfma_f32_16x16x32_bf16 v[32:35], v[232:235], v[184:187], v[32:35]
	v_mfma_f32_16x16x32_bf16 v[20:23], v[208:211], v[192:195], v[20:23]
	v_mfma_f32_16x16x32_bf16 v[16:19], v[232:235], v[192:195], v[16:19]
	v_mfma_f32_16x16x32_bf16 v[4:7], v[208:211], v[200:203], v[4:7]
	v_mfma_f32_16x16x32_bf16 v[0:3], v[232:235], v[200:203], v[0:3]
	s_setprio 0
	s_add_i32 s2, 0, 0x18000
	v_add_u32_e32 v168, s2, v154
	s_barrier
	ds_read_b128 v[156:159], v168
	ds_read_b128 v[160:163], v168 offset:1024
	ds_read_b128 v[164:167], v168 offset:2048
	ds_read_b128 v[168:171], v168 offset:3072
	s_add_u32 s18, s36, 0x40000
	s_addc_u32 s19, s37, 0
	s_mov_b32 m0, s46
	ds_read_b128 v[172:175], v155 offset:32768
	ds_read_b128 v[176:179], v155 offset:33792
	ds_read_b128 v[180:183], v155 offset:34816
	ds_read_b128 v[184:187], v155 offset:35840
	ds_read_b128 v[188:191], v155 offset:36864
	ds_read_b128 v[192:195], v155 offset:37888
	ds_read_b128 v[196:199], v155 offset:38912
	global_load_lds_dwordx4 v132, s[18:19]
	s_mov_b32 m0, s48
	ds_read_b128 v[200:203], v155 offset:39936
	global_load_lds_dwordx4 v130, s[18:19]
	s_waitcnt lgkmcnt(8)
	s_barrier
	s_waitcnt lgkmcnt(0)
	s_setprio 1
	v_mfma_f32_16x16x32_bf16 v[124:127], v[156:159], v[172:175], v[124:127]
	v_mfma_f32_16x16x32_bf16 v[120:123], v[164:167], v[172:175], v[120:123]
	v_mfma_f32_16x16x32_bf16 v[108:111], v[156:159], v[180:183], v[108:111]
	v_mfma_f32_16x16x32_bf16 v[104:107], v[164:167], v[180:183], v[104:107]
	v_mfma_f32_16x16x32_bf16 v[92:95], v[156:159], v[188:191], v[92:95]
	v_mfma_f32_16x16x32_bf16 v[88:91], v[164:167], v[188:191], v[88:91]
	v_mfma_f32_16x16x32_bf16 v[76:79], v[156:159], v[196:199], v[76:79]
	v_mfma_f32_16x16x32_bf16 v[72:75], v[164:167], v[196:199], v[72:75]
	v_mfma_f32_16x16x32_bf16 v[124:127], v[160:163], v[176:179], v[124:127]
	v_mfma_f32_16x16x32_bf16 v[120:123], v[168:171], v[176:179], v[120:123]
	v_mfma_f32_16x16x32_bf16 v[108:111], v[160:163], v[184:187], v[108:111]
	v_mfma_f32_16x16x32_bf16 v[104:107], v[168:171], v[184:187], v[104:107]
	v_mfma_f32_16x16x32_bf16 v[92:95], v[160:163], v[192:195], v[92:95]
	v_mfma_f32_16x16x32_bf16 v[88:91], v[168:171], v[192:195], v[88:91]
	v_mfma_f32_16x16x32_bf16 v[76:79], v[160:163], v[200:203], v[76:79]
	v_mfma_f32_16x16x32_bf16 v[72:75], v[168:171], v[200:203], v[72:75]
	s_setprio 0
	s_barrier
	s_add_i32 s18, 0, 0x1c000
	s_add_i32 s2, s2, s44
	v_add_u32_e32 v232, s18, v154
	s_mov_b32 m0, s2
	ds_read_b128 v[204:207], v232
	ds_read_b128 v[208:211], v232 offset:1024
	ds_read_b128 v[228:231], v232 offset:2048
	ds_read_b128 v[232:235], v232 offset:3072
	s_add_u32 s100, s0, 0x80
	s_addc_u32 s101, s1, 0
	global_load_lds_dwordx4 v140, s[100:101]
	s_add_i32 m0, s2, 0x2000
	s_nop 0
	global_load_lds_dwordx4 v128, s[100:101]
	s_barrier
	s_waitcnt lgkmcnt(0)
	s_setprio 1
	v_mfma_f32_16x16x32_bf16 v[116:119], v[204:207], v[172:175], v[116:119]
	v_mfma_f32_16x16x32_bf16 v[112:115], v[228:231], v[172:175], v[112:115]
	v_mfma_f32_16x16x32_bf16 v[100:103], v[204:207], v[180:183], v[100:103]
	v_mfma_f32_16x16x32_bf16 v[96:99], v[228:231], v[180:183], v[96:99]
	v_mfma_f32_16x16x32_bf16 v[84:87], v[204:207], v[188:191], v[84:87]
	v_mfma_f32_16x16x32_bf16 v[80:83], v[228:231], v[188:191], v[80:83]
	v_mfma_f32_16x16x32_bf16 v[68:71], v[204:207], v[196:199], v[68:71]
	v_mfma_f32_16x16x32_bf16 v[64:67], v[228:231], v[196:199], v[64:67]
	v_mfma_f32_16x16x32_bf16 v[116:119], v[208:211], v[176:179], v[116:119]
	v_mfma_f32_16x16x32_bf16 v[112:115], v[232:235], v[176:179], v[112:115]
	v_mfma_f32_16x16x32_bf16 v[100:103], v[208:211], v[184:187], v[100:103]
	v_mfma_f32_16x16x32_bf16 v[96:99], v[232:235], v[184:187], v[96:99]
	v_mfma_f32_16x16x32_bf16 v[84:87], v[208:211], v[192:195], v[84:87]
	v_mfma_f32_16x16x32_bf16 v[80:83], v[232:235], v[192:195], v[80:83]
	v_mfma_f32_16x16x32_bf16 v[68:71], v[208:211], v[200:203], v[68:71]
	v_mfma_f32_16x16x32_bf16 v[64:67], v[232:235], v[200:203], v[64:67]
	s_setprio 0
	s_mov_b32 m0, s57
	s_barrier
	ds_read_b128 v[172:175], v155 offset:49152
	ds_read_b128 v[176:179], v155 offset:50176
	ds_read_b128 v[180:183], v155 offset:51200
	ds_read_b128 v[184:187], v155 offset:52224
	ds_read_b128 v[188:191], v155 offset:53248
	ds_read_b128 v[192:195], v155 offset:54272
	ds_read_b128 v[196:199], v155 offset:55296
	ds_read_b128 v[200:203], v155 offset:56320
	s_add_u32 s100, s36, 0x80
	s_addc_u32 s101, s37, 0
	global_load_lds_dwordx4 v132, s[100:101]
	s_mov_b32 m0, s58
	s_nop 0
	global_load_lds_dwordx4 v130, s[100:101]
	s_barrier
	s_waitcnt lgkmcnt(0)
	s_setprio 1
	v_mfma_f32_16x16x32_bf16 v[60:63], v[156:159], v[172:175], v[60:63]
	v_mfma_f32_16x16x32_bf16 v[56:59], v[164:167], v[172:175], v[56:59]
	v_mfma_f32_16x16x32_bf16 v[44:47], v[156:159], v[180:183], v[44:47]
	v_mfma_f32_16x16x32_bf16 v[40:43], v[164:167], v[180:183], v[40:43]
	v_mfma_f32_16x16x32_bf16 v[28:31], v[156:159], v[188:191], v[28:31]
	v_mfma_f32_16x16x32_bf16 v[24:27], v[164:167], v[188:191], v[24:27]
	v_mfma_f32_16x16x32_bf16 v[12:15], v[156:159], v[196:199], v[12:15]
	v_mfma_f32_16x16x32_bf16 v[8:11], v[164:167], v[196:199], v[8:11]
	v_mfma_f32_16x16x32_bf16 v[60:63], v[160:163], v[176:179], v[60:63]
	v_mfma_f32_16x16x32_bf16 v[56:59], v[168:171], v[176:179], v[56:59]
	v_mfma_f32_16x16x32_bf16 v[44:47], v[160:163], v[184:187], v[44:47]
	v_mfma_f32_16x16x32_bf16 v[40:43], v[168:171], v[184:187], v[40:43]
	v_mfma_f32_16x16x32_bf16 v[28:31], v[160:163], v[192:195], v[28:31]
	v_mfma_f32_16x16x32_bf16 v[24:27], v[168:171], v[192:195], v[24:27]
	v_mfma_f32_16x16x32_bf16 v[12:15], v[160:163], v[200:203], v[12:15]
	v_mfma_f32_16x16x32_bf16 v[8:11], v[168:171], v[200:203], v[8:11]
	s_setprio 0
	s_barrier
	s_add_u32 s0, s0, 0x40080
	s_addc_u32 s1, s1, 0
	s_add_i32 s2, s18, s44
	s_mov_b32 m0, s2
	s_nop 0
	global_load_lds_dwordx4 v140, s[0:1]
	s_add_i32 m0, s2, 0x2000
	s_nop 0
	global_load_lds_dwordx4 v128, s[0:1]
	s_waitcnt vmcnt(6)
	s_barrier
	s_setprio 1
	v_mfma_f32_16x16x32_bf16 v[52:55], v[204:207], v[172:175], v[52:55]
	v_mfma_f32_16x16x32_bf16 v[48:51], v[228:231], v[172:175], v[48:51]
	v_mfma_f32_16x16x32_bf16 v[36:39], v[204:207], v[180:183], v[36:39]
	v_mfma_f32_16x16x32_bf16 v[32:35], v[228:231], v[180:183], v[32:35]
	v_mfma_f32_16x16x32_bf16 v[20:23], v[204:207], v[188:191], v[20:23]
	v_mfma_f32_16x16x32_bf16 v[16:19], v[228:231], v[188:191], v[16:19]
	v_mfma_f32_16x16x32_bf16 v[4:7], v[204:207], v[196:199], v[4:7]
	v_mfma_f32_16x16x32_bf16 v[0:3], v[228:231], v[196:199], v[0:3]
	v_mfma_f32_16x16x32_bf16 v[52:55], v[208:211], v[176:179], v[52:55]
	v_mfma_f32_16x16x32_bf16 v[48:51], v[232:235], v[176:179], v[48:51]
	v_mfma_f32_16x16x32_bf16 v[36:39], v[208:211], v[184:187], v[36:39]
	v_mfma_f32_16x16x32_bf16 v[32:35], v[232:235], v[184:187], v[32:35]
	v_mfma_f32_16x16x32_bf16 v[20:23], v[208:211], v[192:195], v[20:23]
	v_mfma_f32_16x16x32_bf16 v[16:19], v[232:235], v[192:195], v[16:19]
	v_mfma_f32_16x16x32_bf16 v[4:7], v[208:211], v[200:203], v[4:7]
	v_mfma_f32_16x16x32_bf16 v[0:3], v[232:235], v[200:203], v[0:3]
	s_setprio 0
	s_add_i32 s21, s21, 2
	s_add_u32 s5, s5, 0x100
	s_addc_u32 s9, s9, 0
	s_add_u32 s16, s16, 0x100
	s_addc_u32 s17, s17, 0
	s_cmp_gt_u32 s21, 13
	s_barrier
	s_cbranch_scc0 .LBB0_289
	v_mul_f32_e32 v161, 0xbfb8aa3b, v124
	v_exp_f32_e32 v161, v161
	v_mul_f32_e32 v162, 0xbfb8aa3b, v125
	v_exp_f32_e32 v162, v162
	v_mul_f32_e32 v163, 0xbfb8aa3b, v126
	v_exp_f32_e32 v163, v163
	v_mul_f32_e32 v164, 0xbfb8aa3b, v127
	v_exp_f32_e32 v164, v164
	v_mul_f32_e32 v165, 0xbfb8aa3b, v120
	v_exp_f32_e32 v165, v165
	v_mul_f32_e32 v166, 0xbfb8aa3b, v121
	v_add_f32_e32 v161, 1.0, v161
	v_exp_f32_e32 v166, v166
	v_mul_f32_e32 v167, 0xbfb8aa3b, v122
	v_rcp_f32_e32 v161, v161
	v_add_f32_e32 v162, 1.0, v162
	v_exp_f32_e32 v167, v167
	v_mul_f32_e32 v168, 0xbfb8aa3b, v123
	v_rcp_f32_e32 v162, v162
	v_add_f32_e32 v163, 1.0, v163
	v_exp_f32_e32 v168, v168
	v_rcp_f32_e32 v163, v163
	v_add_f32_e32 v164, 1.0, v164
	v_rcp_f32_e32 v164, v164
	v_add_f32_e32 v165, 1.0, v165
	v_rcp_f32_e32 v165, v165
	v_add_f32_e32 v166, 1.0, v166
	v_mul_f32_e32 v124, v124, v161
	v_rcp_f32_e32 v166, v166
	v_add_f32_e32 v167, 1.0, v167
	v_mul_f32_e32 v116, v124, v116
	v_mul_f32_e32 v124, v125, v162
	s_lshl_b32 s0, s14, 8
	v_rcp_f32_e32 v167, v167
	v_add_f32_e32 v168, 1.0, v168
	v_mul_f32_e32 v117, v124, v117
	v_mul_f32_e32 v124, v126, v163
	v_mbcnt_lo_u32_b32 v138, -1, 0
	v_mbcnt_hi_u32_b32 v138, -1, v138
	s_add_i32 s0, s0, s51
	v_rcp_f32_e32 v168, v168
	v_mul_f32_e32 v124, v124, v118
	v_mul_f32_e32 v118, v127, v164
	v_and_or_b32 v160, v138, 15, s0
	s_lshl_b32 s0, s20, 7
	v_ashrrev_i32_e32 v138, 1, v138
	v_mul_f32_e32 v125, v118, v119
	v_mul_f32_e32 v118, v120, v165
	s_or_b32 s0, s0, s52
	v_and_b32_e32 v138, -8, v138
	v_mul_f32_e32 v120, v118, v112
	v_mul_f32_e32 v112, v121, v166
	v_add_u32_e32 v156, s0, v138
	v_mul_f32_e32 v121, v112, v113
	v_mul_f32_e32 v112, v122, v167
	v_ashrrev_i32_e32 v157, 31, v156
	v_mov_b64_e32 v[138:139], s[34:35]
	v_mul_f32_e32 v122, v112, v114
	v_mul_f32_e32 v112, v123, v168
	v_mad_i64_i32 v[158:159], s[0:1], v160, s33, v[138:139]
	v_mul_f32_e32 v123, v112, v115
	v_lshlrev_b64 v[112:113], 1, v[156:157]
	v_lshl_add_u64 v[118:119], v[158:159], 0, v[112:113]
	v_cvt_pk_bf16_f32 v114, v116, v117
	v_cvt_pk_bf16_f32 v116, v120, v121
	v_cvt_pk_bf16_f32 v115, v124, v125
	v_cvt_pk_bf16_f32 v117, v122, v123
	flat_store_dwordx4 v[118:119], v[114:117]
	v_mul_f32_e32 v118, 0xbfb8aa3b, v110
	v_exp_f32_e32 v118, v118
	v_mul_f32_e32 v116, 0xbfb8aa3b, v108
	v_exp_f32_e32 v116, v116
	v_mul_f32_e32 v117, 0xbfb8aa3b, v109
	v_exp_f32_e32 v117, v117
	v_mul_f32_e32 v119, 0xbfb8aa3b, v111
	v_exp_f32_e32 v119, v119
	v_mul_f32_e32 v120, 0xbfb8aa3b, v104
	v_exp_f32_e32 v120, v120
	v_mul_f32_e32 v121, 0xbfb8aa3b, v105
	v_add_f32_e32 v116, 1.0, v116
	v_exp_f32_e32 v121, v121
	v_mul_f32_e32 v122, 0xbfb8aa3b, v106
	v_rcp_f32_e32 v116, v116
	v_add_f32_e32 v117, 1.0, v117
	v_exp_f32_e32 v122, v122
	v_mul_f32_e32 v123, 0xbfb8aa3b, v107
	v_rcp_f32_e32 v117, v117
	v_add_f32_e32 v118, 1.0, v118
	v_exp_f32_e32 v123, v123
	v_rcp_f32_e32 v118, v118
	v_add_f32_e32 v119, 1.0, v119
	v_rcp_f32_e32 v119, v119
	v_add_f32_e32 v120, 1.0, v120
	v_rcp_f32_e32 v120, v120
	v_add_f32_e32 v121, 1.0, v121
	v_mul_f32_e32 v108, v108, v116
	v_rcp_f32_e32 v121, v121
	v_add_f32_e32 v122, 1.0, v122
	v_mul_f32_e32 v108, v108, v100
	v_mul_f32_e32 v100, v109, v117
	v_rcp_f32_e32 v122, v122
	v_add_f32_e32 v123, 1.0, v123
	v_mul_f32_e32 v109, v100, v101
	v_mul_f32_e32 v100, v110, v118
	v_rcp_f32_e32 v123, v123
	v_mul_f32_e32 v102, v100, v102
	v_mul_f32_e32 v100, v111, v119
	v_mul_f32_e32 v103, v100, v103
	v_mul_f32_e32 v100, v104, v120
	v_mul_f32_e32 v104, v100, v96
	v_mul_f32_e32 v96, v105, v121
	v_or_b32_e32 v114, 16, v160
	v_mul_f32_e32 v105, v96, v97
	v_mul_f32_e32 v96, v106, v122
	v_mad_i64_i32 v[114:115], s[0:1], v114, s33, v[138:139]
	v_mul_f32_e32 v106, v96, v98
	v_mul_f32_e32 v96, v107, v123
	v_mul_f32_e32 v99, v96, v99
	v_lshl_add_u64 v[100:101], v[114:115], 0, v[112:113]
	v_cvt_pk_bf16_f32 v98, v104, v105
	v_cvt_pk_bf16_f32 v96, v108, v109
	v_cvt_pk_bf16_f32 v97, v102, v103
	v_cvt_pk_bf16_f32 v99, v106, v99
	flat_store_dwordx4 v[100:101], v[96:99]
	v_mul_f32_e32 v100, 0xbfb8aa3b, v94
	v_exp_f32_e32 v100, v100
	v_mul_f32_e32 v98, 0xbfb8aa3b, v92
	v_exp_f32_e32 v98, v98
	v_mul_f32_e32 v99, 0xbfb8aa3b, v93
	v_exp_f32_e32 v99, v99
	v_mul_f32_e32 v101, 0xbfb8aa3b, v95
	v_exp_f32_e32 v101, v101
	v_mul_f32_e32 v102, 0xbfb8aa3b, v88
	v_exp_f32_e32 v102, v102
	v_mul_f32_e32 v103, 0xbfb8aa3b, v89
	v_add_f32_e32 v98, 1.0, v98
	v_exp_f32_e32 v103, v103
	v_mul_f32_e32 v104, 0xbfb8aa3b, v90
	v_rcp_f32_e32 v98, v98
	v_add_f32_e32 v99, 1.0, v99
	v_exp_f32_e32 v104, v104
	v_mul_f32_e32 v105, 0xbfb8aa3b, v91
	v_rcp_f32_e32 v99, v99
	v_add_f32_e32 v100, 1.0, v100
	v_exp_f32_e32 v105, v105
	v_rcp_f32_e32 v100, v100
	v_add_f32_e32 v101, 1.0, v101
	v_rcp_f32_e32 v101, v101
	v_add_f32_e32 v102, 1.0, v102
	v_rcp_f32_e32 v102, v102
	v_add_f32_e32 v103, 1.0, v103
	v_mul_f32_e32 v92, v92, v98
	v_rcp_f32_e32 v103, v103
	v_add_f32_e32 v104, 1.0, v104
	v_mul_f32_e32 v92, v92, v84
	v_mul_f32_e32 v84, v93, v99
	v_rcp_f32_e32 v104, v104
	v_add_f32_e32 v105, 1.0, v105
	v_mul_f32_e32 v93, v84, v85
	v_mul_f32_e32 v84, v94, v100
	v_rcp_f32_e32 v105, v105
	v_mul_f32_e32 v86, v84, v86
	v_mul_f32_e32 v84, v95, v101
	v_mul_f32_e32 v87, v84, v87
	v_mul_f32_e32 v84, v88, v102
	v_mul_f32_e32 v88, v84, v80
	v_mul_f32_e32 v80, v89, v103
	v_or_b32_e32 v96, 32, v160
	v_mul_f32_e32 v89, v80, v81
	v_mul_f32_e32 v80, v90, v104
	v_mad_i64_i32 v[96:97], s[0:1], v96, s33, v[138:139]
	v_mul_f32_e32 v90, v80, v82
	v_mul_f32_e32 v80, v91, v105
	v_mul_f32_e32 v83, v80, v83
	v_lshl_add_u64 v[84:85], v[96:97], 0, v[112:113]
	v_cvt_pk_bf16_f32 v82, v88, v89
	v_cvt_pk_bf16_f32 v80, v92, v93
	v_cvt_pk_bf16_f32 v81, v86, v87
	v_cvt_pk_bf16_f32 v83, v90, v83
	flat_store_dwordx4 v[84:85], v[80:83]
	v_mul_f32_e32 v84, 0xbfb8aa3b, v78
	v_exp_f32_e32 v84, v84
	v_mul_f32_e32 v82, 0xbfb8aa3b, v76
	v_exp_f32_e32 v82, v82
	v_mul_f32_e32 v83, 0xbfb8aa3b, v77
	v_exp_f32_e32 v83, v83
	v_mul_f32_e32 v85, 0xbfb8aa3b, v79
	v_exp_f32_e32 v85, v85
	v_mul_f32_e32 v86, 0xbfb8aa3b, v72
	v_exp_f32_e32 v86, v86
	v_mul_f32_e32 v87, 0xbfb8aa3b, v73
	v_add_f32_e32 v82, 1.0, v82
	v_exp_f32_e32 v87, v87
	v_mul_f32_e32 v88, 0xbfb8aa3b, v74
	v_rcp_f32_e32 v82, v82
	v_add_f32_e32 v83, 1.0, v83
	v_exp_f32_e32 v88, v88
	v_mul_f32_e32 v89, 0xbfb8aa3b, v75
	v_rcp_f32_e32 v83, v83
	v_add_f32_e32 v84, 1.0, v84
	v_exp_f32_e32 v89, v89
	v_rcp_f32_e32 v84, v84
	v_add_f32_e32 v85, 1.0, v85
	v_rcp_f32_e32 v85, v85
	v_add_f32_e32 v86, 1.0, v86
	v_rcp_f32_e32 v86, v86
	v_add_f32_e32 v87, 1.0, v87
	v_mul_f32_e32 v76, v76, v82
	v_rcp_f32_e32 v87, v87
	v_add_f32_e32 v88, 1.0, v88
	v_mul_f32_e32 v76, v76, v68
	v_mul_f32_e32 v68, v77, v83
	v_rcp_f32_e32 v88, v88
	v_add_f32_e32 v89, 1.0, v89
	v_mul_f32_e32 v77, v68, v69
	v_mul_f32_e32 v68, v78, v84
	v_rcp_f32_e32 v89, v89
	v_mul_f32_e32 v70, v68, v70
	v_mul_f32_e32 v68, v79, v85
	v_mul_f32_e32 v71, v68, v71
	v_mul_f32_e32 v68, v72, v86
	v_mul_f32_e32 v72, v68, v64
	v_mul_f32_e32 v64, v73, v87
	v_or_b32_e32 v80, 48, v160
	v_mul_f32_e32 v73, v64, v65
	v_mul_f32_e32 v64, v74, v88
	v_mad_i64_i32 v[80:81], s[0:1], v80, s33, v[138:139]
	v_mul_f32_e32 v74, v64, v66
	v_mul_f32_e32 v64, v75, v89
	v_mul_f32_e32 v67, v64, v67
	v_lshl_add_u64 v[68:69], v[80:81], 0, v[112:113]
	v_cvt_pk_bf16_f32 v66, v72, v73
	v_cvt_pk_bf16_f32 v64, v76, v77
	v_cvt_pk_bf16_f32 v65, v70, v71
	v_cvt_pk_bf16_f32 v67, v74, v67
	flat_store_dwordx4 v[68:69], v[64:67]
	v_mul_f32_e32 v68, 0xbfb8aa3b, v62
	v_exp_f32_e32 v68, v68
	v_mul_f32_e32 v66, 0xbfb8aa3b, v60
	v_exp_f32_e32 v66, v66
	v_mul_f32_e32 v67, 0xbfb8aa3b, v61
	v_exp_f32_e32 v67, v67
	v_mul_f32_e32 v69, 0xbfb8aa3b, v63
	v_exp_f32_e32 v69, v69
	v_mul_f32_e32 v70, 0xbfb8aa3b, v56
	v_exp_f32_e32 v70, v70
	v_mul_f32_e32 v71, 0xbfb8aa3b, v57
	v_add_f32_e32 v66, 1.0, v66
	v_exp_f32_e32 v71, v71
	v_mul_f32_e32 v72, 0xbfb8aa3b, v58
	v_rcp_f32_e32 v66, v66
	v_add_f32_e32 v67, 1.0, v67
	v_exp_f32_e32 v72, v72
	v_mul_f32_e32 v73, 0xbfb8aa3b, v59
	v_rcp_f32_e32 v67, v67
	v_add_f32_e32 v68, 1.0, v68
	v_exp_f32_e32 v73, v73
	v_rcp_f32_e32 v68, v68
	v_add_f32_e32 v69, 1.0, v69
	v_rcp_f32_e32 v69, v69
	v_add_f32_e32 v70, 1.0, v70
	v_rcp_f32_e32 v70, v70
	v_add_f32_e32 v71, 1.0, v71
	v_mul_f32_e32 v60, v60, v66
	v_rcp_f32_e32 v71, v71
	v_add_f32_e32 v72, 1.0, v72
	v_mul_f32_e32 v60, v60, v52
	v_mul_f32_e32 v52, v61, v67
	v_rcp_f32_e32 v72, v72
	v_add_f32_e32 v73, 1.0, v73
	v_mul_f32_e32 v61, v52, v53
	v_mul_f32_e32 v52, v62, v68
	v_rcp_f32_e32 v73, v73
	v_mul_f32_e32 v54, v52, v54
	v_mul_f32_e32 v52, v63, v69
	v_mul_f32_e32 v55, v52, v55
	v_mul_f32_e32 v52, v56, v70
	v_mul_f32_e32 v56, v52, v48
	v_mul_f32_e32 v48, v57, v71
	v_add_u32_e32 v64, 0x80, v160
	v_mul_f32_e32 v57, v48, v49
	v_mul_f32_e32 v48, v58, v72
	v_mad_i64_i32 v[64:65], s[0:1], v64, s33, v[138:139]
	v_mul_f32_e32 v58, v48, v50
	v_mul_f32_e32 v48, v59, v73
	v_mul_f32_e32 v51, v48, v51
	v_lshl_add_u64 v[52:53], v[64:65], 0, v[112:113]
	v_cvt_pk_bf16_f32 v50, v56, v57
	v_cvt_pk_bf16_f32 v48, v60, v61
	v_cvt_pk_bf16_f32 v49, v54, v55
	v_cvt_pk_bf16_f32 v51, v58, v51
	flat_store_dwordx4 v[52:53], v[48:51]
	v_mul_f32_e32 v52, 0xbfb8aa3b, v46
	v_exp_f32_e32 v52, v52
	v_mul_f32_e32 v50, 0xbfb8aa3b, v44
	v_exp_f32_e32 v50, v50
	v_mul_f32_e32 v51, 0xbfb8aa3b, v45
	v_exp_f32_e32 v51, v51
	v_mul_f32_e32 v53, 0xbfb8aa3b, v47
	v_exp_f32_e32 v53, v53
	v_mul_f32_e32 v54, 0xbfb8aa3b, v40
	v_exp_f32_e32 v54, v54
	v_mul_f32_e32 v55, 0xbfb8aa3b, v41
	v_add_f32_e32 v50, 1.0, v50
	v_exp_f32_e32 v55, v55
	v_mul_f32_e32 v56, 0xbfb8aa3b, v42
	v_rcp_f32_e32 v50, v50
	v_add_f32_e32 v51, 1.0, v51
	v_exp_f32_e32 v56, v56
	v_mul_f32_e32 v57, 0xbfb8aa3b, v43
	v_rcp_f32_e32 v51, v51
	v_add_f32_e32 v52, 1.0, v52
	v_exp_f32_e32 v57, v57
	v_rcp_f32_e32 v52, v52
	v_add_f32_e32 v53, 1.0, v53
	v_rcp_f32_e32 v53, v53
	v_add_f32_e32 v54, 1.0, v54
	v_rcp_f32_e32 v54, v54
	v_add_f32_e32 v55, 1.0, v55
	v_mul_f32_e32 v44, v44, v50
	v_rcp_f32_e32 v55, v55
	v_add_f32_e32 v56, 1.0, v56
	v_mul_f32_e32 v44, v44, v36
	v_mul_f32_e32 v36, v45, v51
	v_rcp_f32_e32 v56, v56
	v_add_f32_e32 v57, 1.0, v57
	v_mul_f32_e32 v45, v36, v37
	v_mul_f32_e32 v36, v46, v52
	v_rcp_f32_e32 v57, v57
	v_mul_f32_e32 v38, v36, v38
	v_mul_f32_e32 v36, v47, v53
	v_mul_f32_e32 v39, v36, v39
	v_mul_f32_e32 v36, v40, v54
	v_mul_f32_e32 v40, v36, v32
	v_mul_f32_e32 v32, v41, v55
	v_add_u32_e32 v48, 0x90, v160
	v_mul_f32_e32 v41, v32, v33
	v_mul_f32_e32 v32, v42, v56
	v_mad_i64_i32 v[48:49], s[0:1], v48, s33, v[138:139]
	v_mul_f32_e32 v42, v32, v34
	v_mul_f32_e32 v32, v43, v57
	v_mul_f32_e32 v35, v32, v35
	v_lshl_add_u64 v[36:37], v[48:49], 0, v[112:113]
	v_cvt_pk_bf16_f32 v34, v40, v41
	v_cvt_pk_bf16_f32 v32, v44, v45
	v_cvt_pk_bf16_f32 v33, v38, v39
	v_cvt_pk_bf16_f32 v35, v42, v35
	flat_store_dwordx4 v[36:37], v[32:35]
	v_mul_f32_e32 v36, 0xbfb8aa3b, v30
	v_exp_f32_e32 v36, v36
	v_mul_f32_e32 v34, 0xbfb8aa3b, v28
	v_exp_f32_e32 v34, v34
	v_mul_f32_e32 v35, 0xbfb8aa3b, v29
	v_exp_f32_e32 v35, v35
	v_mul_f32_e32 v37, 0xbfb8aa3b, v31
	v_exp_f32_e32 v37, v37
	v_mul_f32_e32 v38, 0xbfb8aa3b, v24
	v_exp_f32_e32 v38, v38
	v_mul_f32_e32 v39, 0xbfb8aa3b, v25
	v_add_f32_e32 v34, 1.0, v34
	v_exp_f32_e32 v39, v39
	v_mul_f32_e32 v40, 0xbfb8aa3b, v26
	v_rcp_f32_e32 v34, v34
	v_add_f32_e32 v35, 1.0, v35
	v_exp_f32_e32 v40, v40
	v_mul_f32_e32 v41, 0xbfb8aa3b, v27
	v_rcp_f32_e32 v35, v35
	v_add_f32_e32 v36, 1.0, v36
	v_exp_f32_e32 v41, v41
	v_rcp_f32_e32 v36, v36
	v_add_f32_e32 v37, 1.0, v37
	v_rcp_f32_e32 v37, v37
	v_add_f32_e32 v38, 1.0, v38
	v_rcp_f32_e32 v38, v38
	v_add_f32_e32 v39, 1.0, v39
	v_mul_f32_e32 v28, v28, v34
	v_rcp_f32_e32 v39, v39
	v_add_f32_e32 v40, 1.0, v40
	v_mul_f32_e32 v28, v28, v20
	v_mul_f32_e32 v20, v29, v35
	v_rcp_f32_e32 v40, v40
	v_add_f32_e32 v41, 1.0, v41
	v_mul_f32_e32 v29, v20, v21
	v_mul_f32_e32 v20, v30, v36
	v_rcp_f32_e32 v41, v41
	v_mul_f32_e32 v22, v20, v22
	v_mul_f32_e32 v20, v31, v37
	v_mul_f32_e32 v23, v20, v23
	v_mul_f32_e32 v20, v24, v38
	v_mul_f32_e32 v24, v20, v16
	v_mul_f32_e32 v16, v25, v39
	v_add_u32_e32 v32, 0xa0, v160
	v_mul_f32_e32 v25, v16, v17
	v_mul_f32_e32 v16, v26, v40
	v_mad_i64_i32 v[32:33], s[0:1], v32, s33, v[138:139]
	v_mul_f32_e32 v26, v16, v18
	v_mul_f32_e32 v16, v27, v41
	v_mul_f32_e32 v19, v16, v19
	v_lshl_add_u64 v[20:21], v[32:33], 0, v[112:113]
	v_cvt_pk_bf16_f32 v18, v24, v25
	v_cvt_pk_bf16_f32 v16, v28, v29
	v_cvt_pk_bf16_f32 v17, v22, v23
	v_cvt_pk_bf16_f32 v19, v26, v19
	flat_store_dwordx4 v[20:21], v[16:19]
	v_mul_f32_e32 v20, 0xbfb8aa3b, v14
	v_exp_f32_e32 v20, v20
	v_mul_f32_e32 v18, 0xbfb8aa3b, v12
	v_exp_f32_e32 v18, v18
	v_mul_f32_e32 v19, 0xbfb8aa3b, v13
	v_exp_f32_e32 v19, v19
	v_mul_f32_e32 v21, 0xbfb8aa3b, v15
	v_exp_f32_e32 v21, v21
	v_mul_f32_e32 v22, 0xbfb8aa3b, v8
	v_exp_f32_e32 v22, v22
	v_mul_f32_e32 v23, 0xbfb8aa3b, v9
	v_add_f32_e32 v18, 1.0, v18
	v_exp_f32_e32 v23, v23
	v_mul_f32_e32 v24, 0xbfb8aa3b, v10
	v_rcp_f32_e32 v18, v18
	v_add_f32_e32 v19, 1.0, v19
	v_exp_f32_e32 v24, v24
	v_mul_f32_e32 v25, 0xbfb8aa3b, v11
	v_rcp_f32_e32 v19, v19
	v_add_f32_e32 v20, 1.0, v20
	v_exp_f32_e32 v25, v25
	v_rcp_f32_e32 v20, v20
	v_add_f32_e32 v21, 1.0, v21
	v_rcp_f32_e32 v21, v21
	v_add_f32_e32 v22, 1.0, v22
	v_rcp_f32_e32 v22, v22
	v_add_f32_e32 v23, 1.0, v23
	v_mul_f32_e32 v12, v12, v18
	v_rcp_f32_e32 v23, v23
	v_add_f32_e32 v24, 1.0, v24
	v_mul_f32_e32 v12, v12, v4
	v_mul_f32_e32 v4, v13, v19
	v_rcp_f32_e32 v24, v24
	v_add_f32_e32 v25, 1.0, v25
	v_mul_f32_e32 v13, v4, v5
	v_mul_f32_e32 v4, v14, v20
	v_rcp_f32_e32 v25, v25
	v_mul_f32_e32 v6, v4, v6
	v_mul_f32_e32 v4, v15, v21
	v_mul_f32_e32 v7, v4, v7
	v_mul_f32_e32 v4, v8, v22
	v_mul_f32_e32 v8, v4, v0
	v_mul_f32_e32 v0, v9, v23
	v_add_u32_e32 v16, 0xb0, v160
	v_mul_f32_e32 v9, v0, v1
	v_mul_f32_e32 v0, v10, v24
	v_mad_i64_i32 v[16:17], s[0:1], v16, s33, v[138:139]
	v_mul_f32_e32 v10, v0, v2
	v_mul_f32_e32 v0, v11, v25
	v_mul_f32_e32 v3, v0, v3
	v_lshl_add_u64 v[4:5], v[16:17], 0, v[112:113]
	s_and_b64 vcc, exec, s[6:7]
	s_mov_b32 s20, s8
	s_mov_b32 s14, s4
	s_mov_b64 s[16:17], s[12:13]
	s_mov_b64 s[0:1], s[10:11]
	v_cvt_pk_bf16_f32 v0, v12, v13
	v_cvt_pk_bf16_f32 v1, v6, v7
	v_cvt_pk_bf16_f32 v2, v8, v9
	v_cvt_pk_bf16_f32 v3, v10, v3
	flat_store_dwordx4 v[4:5], v[0:3]
	s_cbranch_vccz .LBB0_286
	s_waitcnt vmcnt(0)
	s_cmpk_gt_u32 s39, 0xff
	v_readlane_b32 s51, v252, 10
	s_cbranch_scc1 .LBB0_293
	s_barrier

.LBB0_321:
	s_add_u32 s0, s16, 0xfffc0080
	s_addc_u32 s1, s17, -1
	s_add_i32 s2, 0, 0x10000
	v_add_u32_e32 v138, s2, v154
	ds_read_b128 v[156:159], v138
	ds_read_b128 v[160:163], v138 offset:1024
	ds_read_b128 v[164:167], v138 offset:2048
	ds_read_b128 v[168:171], v138 offset:3072
	s_cmp_eq_u32 s59, 12
	s_cselect_b32 s41, s11, s1
	s_cselect_b32 s40, s10, s0
	s_cselect_b32 s1, s13, s9
	s_cselect_b32 s0, s12, s5
	s_add_i32 m0, s15, 0xc000
	ds_read_b128 v[172:175], v155
	ds_read_b128 v[176:179], v155 offset:1024
	ds_read_b128 v[180:183], v155 offset:2048
	ds_read_b128 v[184:187], v155 offset:3072
	ds_read_b128 v[188:191], v155 offset:4096
	ds_read_b128 v[192:195], v155 offset:5120
	ds_read_b128 v[196:199], v155 offset:6144
	global_load_lds_dwordx4 v136, s[16:17]
	s_add_i32 m0, s15, 0xe000
	ds_read_b128 v[200:203], v155 offset:7168
	global_load_lds_dwordx4 v134, s[16:17]
	s_waitcnt lgkmcnt(8)
	s_barrier
	s_waitcnt lgkmcnt(0)
	s_setprio 1
	v_mfma_f32_16x16x32_bf16 v[124:127], v[156:159], v[172:175], v[124:127]
	v_mfma_f32_16x16x32_bf16 v[120:123], v[164:167], v[172:175], v[120:123]
	v_mfma_f32_16x16x32_bf16 v[116:119], v[156:159], v[180:183], v[116:119]
	v_mfma_f32_16x16x32_bf16 v[108:111], v[164:167], v[180:183], v[108:111]
	v_mfma_f32_16x16x32_bf16 v[100:103], v[156:159], v[188:191], v[100:103]
	v_mfma_f32_16x16x32_bf16 v[92:95], v[164:167], v[188:191], v[92:95]
	v_mfma_f32_16x16x32_bf16 v[84:87], v[156:159], v[196:199], v[84:87]
	v_mfma_f32_16x16x32_bf16 v[76:79], v[164:167], v[196:199], v[76:79]
	v_mfma_f32_16x16x32_bf16 v[124:127], v[160:163], v[176:179], v[124:127]
	v_mfma_f32_16x16x32_bf16 v[120:123], v[168:171], v[176:179], v[120:123]
	v_mfma_f32_16x16x32_bf16 v[116:119], v[160:163], v[184:187], v[116:119]
	v_mfma_f32_16x16x32_bf16 v[108:111], v[168:171], v[184:187], v[108:111]
	v_mfma_f32_16x16x32_bf16 v[100:103], v[160:163], v[192:195], v[100:103]
	v_mfma_f32_16x16x32_bf16 v[92:95], v[168:171], v[192:195], v[92:95]
	v_mfma_f32_16x16x32_bf16 v[84:87], v[160:163], v[200:203], v[84:87]
	v_mfma_f32_16x16x32_bf16 v[76:79], v[168:171], v[200:203], v[76:79]
	s_setprio 0
	s_barrier
	s_add_i32 s30, 0, 0x14000
	v_add_u32_e32 v138, s30, v154
	s_add_i32 s2, s2, s45
	ds_read_b128 v[204:207], v138
	ds_read_b128 v[208:211], v138 offset:1024
	ds_read_b128 v[228:231], v138 offset:2048
	s_mov_b32 m0, s2
	ds_read_b128 v[232:235], v138 offset:3072
	global_load_lds_dwordx4 v140, s[0:1]
	s_add_i32 m0, s2, 0x2000
	s_nop 0
	global_load_lds_dwordx4 v132, s[0:1]
	s_barrier
	s_waitcnt lgkmcnt(0)
	s_setprio 1
	v_mfma_f32_16x16x32_bf16 v[112:115], v[204:207], v[172:175], v[112:115]
	v_mfma_f32_16x16x32_bf16 v[104:107], v[228:231], v[172:175], v[104:107]
	v_mfma_f32_16x16x32_bf16 v[96:99], v[204:207], v[180:183], v[96:99]
	v_mfma_f32_16x16x32_bf16 v[88:91], v[228:231], v[180:183], v[88:91]
	v_mfma_f32_16x16x32_bf16 v[80:83], v[204:207], v[188:191], v[80:83]
	v_mfma_f32_16x16x32_bf16 v[72:75], v[228:231], v[188:191], v[72:75]
	v_mfma_f32_16x16x32_bf16 v[68:71], v[204:207], v[196:199], v[68:71]
	v_mfma_f32_16x16x32_bf16 v[64:67], v[228:231], v[196:199], v[64:67]
	v_mfma_f32_16x16x32_bf16 v[112:115], v[208:211], v[176:179], v[112:115]
	v_mfma_f32_16x16x32_bf16 v[104:107], v[232:235], v[176:179], v[104:107]
	v_mfma_f32_16x16x32_bf16 v[96:99], v[208:211], v[184:187], v[96:99]
	v_mfma_f32_16x16x32_bf16 v[88:91], v[232:235], v[184:187], v[88:91]
	v_mfma_f32_16x16x32_bf16 v[80:83], v[208:211], v[192:195], v[80:83]
	v_mfma_f32_16x16x32_bf16 v[72:75], v[232:235], v[192:195], v[72:75]
	v_mfma_f32_16x16x32_bf16 v[68:71], v[208:211], v[200:203], v[68:71]
	v_mfma_f32_16x16x32_bf16 v[64:67], v[232:235], v[200:203], v[64:67]
	s_setprio 0
	s_mov_b32 m0, s15
	s_barrier
	ds_read_b128 v[172:175], v155 offset:16384
	ds_read_b128 v[176:179], v155 offset:17408
	ds_read_b128 v[180:183], v155 offset:18432
	ds_read_b128 v[184:187], v155 offset:19456
	ds_read_b128 v[188:191], v155 offset:20480
	ds_read_b128 v[192:195], v155 offset:21504
	ds_read_b128 v[196:199], v155 offset:22528
	global_load_lds_dwordx4 v128, s[40:41]
	s_mov_b32 m0, s46
	ds_read_b128 v[200:203], v155 offset:23552
	global_load_lds_dwordx4 v130, s[40:41]
	s_barrier
	s_waitcnt lgkmcnt(0)
	s_setprio 1
	v_mfma_f32_16x16x32_bf16 v[60:63], v[156:159], v[172:175], v[60:63]
	v_mfma_f32_16x16x32_bf16 v[56:59], v[164:167], v[172:175], v[56:59]
	v_mfma_f32_16x16x32_bf16 v[52:55], v[156:159], v[180:183], v[52:55]
	v_mfma_f32_16x16x32_bf16 v[44:47], v[164:167], v[180:183], v[44:47]
	v_mfma_f32_16x16x32_bf16 v[36:39], v[156:159], v[188:191], v[36:39]
	v_mfma_f32_16x16x32_bf16 v[28:31], v[164:167], v[188:191], v[28:31]
	v_mfma_f32_16x16x32_bf16 v[20:23], v[156:159], v[196:199], v[20:23]
	v_mfma_f32_16x16x32_bf16 v[12:15], v[164:167], v[196:199], v[12:15]
	v_mfma_f32_16x16x32_bf16 v[60:63], v[160:163], v[176:179], v[60:63]
	v_mfma_f32_16x16x32_bf16 v[56:59], v[168:171], v[176:179], v[56:59]
	v_mfma_f32_16x16x32_bf16 v[52:55], v[160:163], v[184:187], v[52:55]
	v_mfma_f32_16x16x32_bf16 v[44:47], v[168:171], v[184:187], v[44:47]
	v_mfma_f32_16x16x32_bf16 v[36:39], v[160:163], v[192:195], v[36:39]
	v_mfma_f32_16x16x32_bf16 v[28:31], v[168:171], v[192:195], v[28:31]
	v_mfma_f32_16x16x32_bf16 v[20:23], v[160:163], v[200:203], v[20:23]
	v_mfma_f32_16x16x32_bf16 v[12:15], v[168:171], v[200:203], v[12:15]
	s_setprio 0
	s_barrier
	s_add_u32 s18, s0, 0x40000
	s_addc_u32 s19, s1, 0
	s_add_i32 s2, s30, s45
	s_mov_b32 m0, s2
	s_nop 0
	global_load_lds_dwordx4 v140, s[18:19]
	s_add_i32 m0, s2, 0x2000
	s_nop 0
	global_load_lds_dwordx4 v132, s[18:19]
	s_waitcnt vmcnt(6)
	s_barrier
	s_setprio 1
	v_mfma_f32_16x16x32_bf16 v[48:51], v[204:207], v[172:175], v[48:51]
	v_mfma_f32_16x16x32_bf16 v[40:43], v[228:231], v[172:175], v[40:43]
	v_mfma_f32_16x16x32_bf16 v[32:35], v[204:207], v[180:183], v[32:35]
	v_mfma_f32_16x16x32_bf16 v[24:27], v[228:231], v[180:183], v[24:27]
	v_mfma_f32_16x16x32_bf16 v[16:19], v[204:207], v[188:191], v[16:19]
	v_mfma_f32_16x16x32_bf16 v[8:11], v[228:231], v[188:191], v[8:11]
	v_mfma_f32_16x16x32_bf16 v[4:7], v[204:207], v[196:199], v[4:7]
	v_mfma_f32_16x16x32_bf16 v[0:3], v[228:231], v[196:199], v[0:3]
	v_mfma_f32_16x16x32_bf16 v[48:51], v[208:211], v[176:179], v[48:51]
	v_mfma_f32_16x16x32_bf16 v[40:43], v[232:235], v[176:179], v[40:43]
	v_mfma_f32_16x16x32_bf16 v[32:35], v[208:211], v[184:187], v[32:35]
	v_mfma_f32_16x16x32_bf16 v[24:27], v[232:235], v[184:187], v[24:27]
	v_mfma_f32_16x16x32_bf16 v[16:19], v[208:211], v[192:195], v[16:19]
	v_mfma_f32_16x16x32_bf16 v[8:11], v[232:235], v[192:195], v[8:11]
	v_mfma_f32_16x16x32_bf16 v[4:7], v[208:211], v[200:203], v[4:7]
	v_mfma_f32_16x16x32_bf16 v[0:3], v[232:235], v[200:203], v[0:3]
	s_setprio 0
	s_add_i32 s2, 0, 0x18000
	v_add_u32_e32 v168, s2, v154
	s_barrier
	ds_read_b128 v[156:159], v168
	ds_read_b128 v[160:163], v168 offset:1024
	ds_read_b128 v[164:167], v168 offset:2048
	ds_read_b128 v[168:171], v168 offset:3072
	s_add_u32 s18, s40, 0x40000
	s_addc_u32 s19, s41, 0
	s_mov_b32 m0, s48
	ds_read_b128 v[172:175], v155 offset:32768
	ds_read_b128 v[176:179], v155 offset:33792
	ds_read_b128 v[180:183], v155 offset:34816
	ds_read_b128 v[184:187], v155 offset:35840
	ds_read_b128 v[188:191], v155 offset:36864
	ds_read_b128 v[192:195], v155 offset:37888
	ds_read_b128 v[196:199], v155 offset:38912
	global_load_lds_dwordx4 v128, s[18:19]
	s_mov_b32 m0, s49
	ds_read_b128 v[200:203], v155 offset:39936
	global_load_lds_dwordx4 v130, s[18:19]
	s_waitcnt lgkmcnt(8)
	s_barrier
	s_waitcnt lgkmcnt(0)
	s_setprio 1
	v_mfma_f32_16x16x32_bf16 v[124:127], v[156:159], v[172:175], v[124:127]
	v_mfma_f32_16x16x32_bf16 v[120:123], v[164:167], v[172:175], v[120:123]
	v_mfma_f32_16x16x32_bf16 v[116:119], v[156:159], v[180:183], v[116:119]
	v_mfma_f32_16x16x32_bf16 v[108:111], v[164:167], v[180:183], v[108:111]
	v_mfma_f32_16x16x32_bf16 v[100:103], v[156:159], v[188:191], v[100:103]
	v_mfma_f32_16x16x32_bf16 v[92:95], v[164:167], v[188:191], v[92:95]
	v_mfma_f32_16x16x32_bf16 v[84:87], v[156:159], v[196:199], v[84:87]
	v_mfma_f32_16x16x32_bf16 v[76:79], v[164:167], v[196:199], v[76:79]
	v_mfma_f32_16x16x32_bf16 v[124:127], v[160:163], v[176:179], v[124:127]
	v_mfma_f32_16x16x32_bf16 v[120:123], v[168:171], v[176:179], v[120:123]
	v_mfma_f32_16x16x32_bf16 v[116:119], v[160:163], v[184:187], v[116:119]
	v_mfma_f32_16x16x32_bf16 v[108:111], v[168:171], v[184:187], v[108:111]
	v_mfma_f32_16x16x32_bf16 v[100:103], v[160:163], v[192:195], v[100:103]
	v_mfma_f32_16x16x32_bf16 v[92:95], v[168:171], v[192:195], v[92:95]
	v_mfma_f32_16x16x32_bf16 v[84:87], v[160:163], v[200:203], v[84:87]
	v_mfma_f32_16x16x32_bf16 v[76:79], v[168:171], v[200:203], v[76:79]
	s_setprio 0
	s_barrier
	s_add_i32 s18, 0, 0x1c000
	s_add_i32 s2, s2, s45
	v_add_u32_e32 v232, s18, v154
	s_mov_b32 m0, s2
	ds_read_b128 v[204:207], v232
	ds_read_b128 v[208:211], v232 offset:1024
	ds_read_b128 v[228:231], v232 offset:2048
	ds_read_b128 v[232:235], v232 offset:3072
	s_add_u32 s100, s0, 0x80
	s_addc_u32 s101, s1, 0
	global_load_lds_dwordx4 v140, s[100:101]
	s_add_i32 m0, s2, 0x2000
	s_nop 0
	global_load_lds_dwordx4 v132, s[100:101]
	s_barrier
	s_waitcnt lgkmcnt(0)
	s_setprio 1
	v_mfma_f32_16x16x32_bf16 v[112:115], v[204:207], v[172:175], v[112:115]
	v_mfma_f32_16x16x32_bf16 v[104:107], v[228:231], v[172:175], v[104:107]
	v_mfma_f32_16x16x32_bf16 v[96:99], v[204:207], v[180:183], v[96:99]
	v_mfma_f32_16x16x32_bf16 v[88:91], v[228:231], v[180:183], v[88:91]
	v_mfma_f32_16x16x32_bf16 v[80:83], v[204:207], v[188:191], v[80:83]
	v_mfma_f32_16x16x32_bf16 v[72:75], v[228:231], v[188:191], v[72:75]
	v_mfma_f32_16x16x32_bf16 v[68:71], v[204:207], v[196:199], v[68:71]
	v_mfma_f32_16x16x32_bf16 v[64:67], v[228:231], v[196:199], v[64:67]
	v_mfma_f32_16x16x32_bf16 v[112:115], v[208:211], v[176:179], v[112:115]
	v_mfma_f32_16x16x32_bf16 v[104:107], v[232:235], v[176:179], v[104:107]
	v_mfma_f32_16x16x32_bf16 v[96:99], v[208:211], v[184:187], v[96:99]
	v_mfma_f32_16x16x32_bf16 v[88:91], v[232:235], v[184:187], v[88:91]
	v_mfma_f32_16x16x32_bf16 v[80:83], v[208:211], v[192:195], v[80:83]
	v_mfma_f32_16x16x32_bf16 v[72:75], v[232:235], v[192:195], v[72:75]
	v_mfma_f32_16x16x32_bf16 v[68:71], v[208:211], v[200:203], v[68:71]
	v_mfma_f32_16x16x32_bf16 v[64:67], v[232:235], v[200:203], v[64:67]
	s_setprio 0
	s_mov_b32 m0, s57
	s_barrier
	ds_read_b128 v[172:175], v155 offset:49152
	ds_read_b128 v[176:179], v155 offset:50176
	ds_read_b128 v[180:183], v155 offset:51200
	ds_read_b128 v[184:187], v155 offset:52224
	ds_read_b128 v[188:191], v155 offset:53248
	ds_read_b128 v[192:195], v155 offset:54272
	ds_read_b128 v[196:199], v155 offset:55296
	ds_read_b128 v[200:203], v155 offset:56320
	s_add_u32 s100, s40, 0x80
	s_addc_u32 s101, s41, 0
	global_load_lds_dwordx4 v128, s[100:101]
	s_mov_b32 m0, s58
	s_nop 0
	global_load_lds_dwordx4 v130, s[100:101]
	s_barrier
	s_waitcnt lgkmcnt(0)
	s_setprio 1
	v_mfma_f32_16x16x32_bf16 v[60:63], v[156:159], v[172:175], v[60:63]
	v_mfma_f32_16x16x32_bf16 v[56:59], v[164:167], v[172:175], v[56:59]
	v_mfma_f32_16x16x32_bf16 v[52:55], v[156:159], v[180:183], v[52:55]
	v_mfma_f32_16x16x32_bf16 v[44:47], v[164:167], v[180:183], v[44:47]
	v_mfma_f32_16x16x32_bf16 v[36:39], v[156:159], v[188:191], v[36:39]
	v_mfma_f32_16x16x32_bf16 v[28:31], v[164:167], v[188:191], v[28:31]
	v_mfma_f32_16x16x32_bf16 v[20:23], v[156:159], v[196:199], v[20:23]
	v_mfma_f32_16x16x32_bf16 v[12:15], v[164:167], v[196:199], v[12:15]
	v_mfma_f32_16x16x32_bf16 v[60:63], v[160:163], v[176:179], v[60:63]
	v_mfma_f32_16x16x32_bf16 v[56:59], v[168:171], v[176:179], v[56:59]
	v_mfma_f32_16x16x32_bf16 v[52:55], v[160:163], v[184:187], v[52:55]
	v_mfma_f32_16x16x32_bf16 v[44:47], v[168:171], v[184:187], v[44:47]
	v_mfma_f32_16x16x32_bf16 v[36:39], v[160:163], v[192:195], v[36:39]
	v_mfma_f32_16x16x32_bf16 v[28:31], v[168:171], v[192:195], v[28:31]
	v_mfma_f32_16x16x32_bf16 v[20:23], v[160:163], v[200:203], v[20:23]
	v_mfma_f32_16x16x32_bf16 v[12:15], v[168:171], v[200:203], v[12:15]
	s_setprio 0
	s_barrier
	s_add_u32 s0, s0, 0x40080
	s_addc_u32 s1, s1, 0
	s_add_i32 s2, s18, s45
	s_mov_b32 m0, s2
	s_nop 0
	global_load_lds_dwordx4 v140, s[0:1]
	s_add_i32 m0, s2, 0x2000
	s_nop 0
	global_load_lds_dwordx4 v132, s[0:1]
	s_waitcnt vmcnt(6)
	s_barrier
	s_setprio 1
	v_mfma_f32_16x16x32_bf16 v[48:51], v[204:207], v[172:175], v[48:51]
	v_mfma_f32_16x16x32_bf16 v[40:43], v[228:231], v[172:175], v[40:43]
	v_mfma_f32_16x16x32_bf16 v[32:35], v[204:207], v[180:183], v[32:35]
	v_mfma_f32_16x16x32_bf16 v[24:27], v[228:231], v[180:183], v[24:27]
	v_mfma_f32_16x16x32_bf16 v[16:19], v[204:207], v[188:191], v[16:19]
	v_mfma_f32_16x16x32_bf16 v[8:11], v[228:231], v[188:191], v[8:11]
	v_mfma_f32_16x16x32_bf16 v[4:7], v[204:207], v[196:199], v[4:7]
	v_mfma_f32_16x16x32_bf16 v[0:3], v[228:231], v[196:199], v[0:3]
	v_mfma_f32_16x16x32_bf16 v[48:51], v[208:211], v[176:179], v[48:51]
	v_mfma_f32_16x16x32_bf16 v[40:43], v[232:235], v[176:179], v[40:43]
	v_mfma_f32_16x16x32_bf16 v[32:35], v[208:211], v[184:187], v[32:35]
	v_mfma_f32_16x16x32_bf16 v[24:27], v[232:235], v[184:187], v[24:27]
	v_mfma_f32_16x16x32_bf16 v[16:19], v[208:211], v[192:195], v[16:19]
	v_mfma_f32_16x16x32_bf16 v[8:11], v[232:235], v[192:195], v[8:11]
	v_mfma_f32_16x16x32_bf16 v[4:7], v[208:211], v[200:203], v[4:7]
	v_mfma_f32_16x16x32_bf16 v[0:3], v[232:235], v[200:203], v[0:3]
	s_setprio 0
	s_add_i32 s59, s59, 2
	s_add_u32 s5, s5, 0x100
	s_addc_u32 s9, s9, 0
	s_add_u32 s16, s16, 0x100
	s_addc_u32 s17, s17, 0
	s_cmp_gt_u32 s59, 13
	s_barrier
	s_cbranch_scc0 .LBB0_321
	s_lshl_b32 s0, s14, 8
	v_mbcnt_lo_u32_b32 v139, -1, 0
	v_mbcnt_hi_u32_b32 v139, -1, v139
	s_lshl_b32 s1, s21, 8
	v_ashrrev_i32_e32 v138, 1, v139
	s_add_i32 s0, s0, s51
	v_and_b32_e32 v138, -8, v138
	s_or_b32 s1, s1, s52
	v_and_or_b32 v156, v139, 15, s0
	v_add_u32_e32 v138, s1, v138
	v_ashrrev_i32_e32 v157, 31, v156
	v_ashrrev_i32_e32 v139, 31, v138
	v_lshlrev_b64 v[158:159], 11, v[156:157]
	v_lshl_add_u64 v[158:159], s[26:27], 0, v[158:159]
	v_lshlrev_b64 v[160:161], 1, v[138:139]
	v_lshl_add_u64 v[138:139], v[158:159], 0, v[160:161]
	v_cvt_pk_bf16_f32 v60, v60, v61
	v_cvt_pk_bf16_f32 v61, v62, v63
	v_cvt_pk_bf16_f32 v62, v56, v57
	v_add_co_u32_e32 v56, vcc, s31, v138
	v_cvt_pk_bf16_f32 v112, v112, v113
	v_cvt_pk_bf16_f32 v113, v114, v115
	v_cvt_pk_bf16_f32 v114, v104, v105
	v_or_b32_e32 v104, 16, v156
	s_nop 0
	v_addc_co_u32_e32 v57, vcc, 0, v139, vcc
	v_cvt_pk_bf16_f32 v48, v48, v49
	v_cvt_pk_bf16_f32 v49, v50, v51
	v_cvt_pk_bf16_f32 v51, v42, v43
	v_cvt_pk_bf16_f32 v42, v44, v45
	v_add_co_u32_e32 v44, vcc, s42, v138
	v_ashrrev_i32_e32 v105, 31, v104
	v_cvt_pk_bf16_f32 v96, v96, v97
	v_cvt_pk_bf16_f32 v97, v98, v99
	v_cvt_pk_bf16_f32 v98, v88, v89
	v_or_b32_e32 v88, 32, v156
	v_addc_co_u32_e32 v45, vcc, 0, v139, vcc
	v_lshlrev_b64 v[104:105], 11, v[104:105]
	v_ashrrev_i32_e32 v89, 31, v88
	v_cvt_pk_bf16_f32 v80, v80, v81
	v_cvt_pk_bf16_f32 v81, v82, v83
	v_cvt_pk_bf16_f32 v82, v72, v73
	v_or_b32_e32 v72, 48, v156
	s_mov_b64 s[0:1], 0x40000
	v_cvt_pk_bf16_f32 v32, v32, v33
	v_cvt_pk_bf16_f32 v33, v34, v35
	v_cvt_pk_bf16_f32 v35, v26, v27
	v_cvt_pk_bf16_f32 v26, v28, v29
	v_add_co_u32_e32 v28, vcc, s43, v138
	v_lshl_add_u64 v[104:105], s[26:27], 0, v[104:105]
	v_lshlrev_b64 v[88:89], 11, v[88:89]
	v_ashrrev_i32_e32 v73, 31, v72
	v_cvt_pk_bf16_f32 v68, v68, v69
	v_cvt_pk_bf16_f32 v69, v70, v71
	v_cvt_pk_bf16_f32 v70, v64, v65
	v_lshl_add_u64 v[64:65], v[138:139], 0, s[0:1]
	s_mov_b64 s[0:1], 0x48000
	v_addc_co_u32_e32 v29, vcc, 0, v139, vcc
	v_cvt_pk_bf16_f32 v115, v106, v107
	flat_store_dwordx4 v[138:139], v[112:115] offset:256
	v_lshl_add_u64 v[88:89], s[26:27], 0, v[88:89]
	v_lshlrev_b64 v[72:73], 11, v[72:73]
	v_lshl_add_u64 v[112:113], v[104:105], 0, v[160:161]
	v_cvt_pk_bf16_f32 v50, v40, v41
	flat_store_dwordx4 v[64:65], v[48:51] offset:256
	v_cvt_pk_bf16_f32 v16, v16, v17
	v_cvt_pk_bf16_f32 v17, v18, v19
	v_cvt_pk_bf16_f32 v19, v10, v11
	v_cvt_pk_bf16_f32 v10, v12, v13
	v_add_co_u32_e32 v12, vcc, s47, v138
	s_nop 0
	v_lshl_add_u64 v[48:49], v[138:139], 0, s[0:1]
	s_mov_b64 s[0:1], 0x50000
	v_cvt_pk_bf16_f32 v99, v90, v91
	flat_store_dwordx4 v[112:113], v[96:99] offset:256
	v_lshl_add_u64 v[72:73], s[26:27], 0, v[72:73]
	v_cvt_pk_bf16_f32 v34, v24, v25
	flat_store_dwordx4 v[48:49], v[32:35] offset:256
	v_lshl_add_u64 v[96:97], v[88:89], 0, v[160:161]
	v_addc_co_u32_e32 v13, vcc, 0, v139, vcc
	v_lshl_add_u64 v[32:33], v[138:139], 0, s[0:1]
	s_mov_b64 s[0:1], 0x58000
	v_cvt_pk_bf16_f32 v83, v74, v75
	flat_store_dwordx4 v[96:97], v[80:83] offset:256
	v_cvt_pk_bf16_f32 v18, v8, v9
	flat_store_dwordx4 v[32:33], v[16:19] offset:256
	s_and_b64 vcc, exec, s[6:7]
	v_lshl_add_u64 v[80:81], v[72:73], 0, v[160:161]
	v_lshl_add_u64 v[16:17], v[138:139], 0, s[0:1]
	s_mov_b32 s21, s8
	s_mov_b32 s14, s4
	s_mov_b64 s[16:17], s[12:13]
	s_mov_b64 s[0:1], s[10:11]
	v_cvt_pk_bf16_f32 v124, v124, v125
	v_cvt_pk_bf16_f32 v125, v126, v127
	v_cvt_pk_bf16_f32 v126, v120, v121
	v_cvt_pk_bf16_f32 v127, v122, v123
	flat_store_dwordx4 v[138:139], v[124:127]
	v_cvt_pk_bf16_f32 v104, v116, v117
	v_cvt_pk_bf16_f32 v105, v118, v119
	v_cvt_pk_bf16_f32 v106, v108, v109
	v_cvt_pk_bf16_f32 v107, v110, v111
	flat_store_dwordx4 v[112:113], v[104:107]
	v_cvt_pk_bf16_f32 v88, v100, v101
	v_cvt_pk_bf16_f32 v89, v102, v103
	v_cvt_pk_bf16_f32 v90, v92, v93
	v_cvt_pk_bf16_f32 v91, v94, v95
	flat_store_dwordx4 v[96:97], v[88:91]
	v_cvt_pk_bf16_f32 v72, v84, v85
	v_cvt_pk_bf16_f32 v73, v86, v87
	v_cvt_pk_bf16_f32 v74, v76, v77
	v_cvt_pk_bf16_f32 v75, v78, v79
	flat_store_dwordx4 v[80:81], v[72:75]
	v_cvt_pk_bf16_f32 v71, v66, v67
	flat_store_dwordx4 v[80:81], v[68:71] offset:256
	v_cvt_pk_bf16_f32 v63, v58, v59
	flat_store_dwordx4 v[56:57], v[60:63]
	v_cvt_pk_bf16_f32 v40, v52, v53
	v_cvt_pk_bf16_f32 v41, v54, v55
	v_cvt_pk_bf16_f32 v43, v46, v47
	flat_store_dwordx4 v[44:45], v[40:43]
	v_cvt_pk_bf16_f32 v24, v36, v37
	v_cvt_pk_bf16_f32 v25, v38, v39
	v_cvt_pk_bf16_f32 v27, v30, v31
	flat_store_dwordx4 v[28:29], v[24:27]
	v_cvt_pk_bf16_f32 v8, v20, v21
	v_cvt_pk_bf16_f32 v9, v22, v23
	v_cvt_pk_bf16_f32 v11, v14, v15
	flat_store_dwordx4 v[12:13], v[8:11]
	v_cvt_pk_bf16_f32 v4, v4, v5
	v_cvt_pk_bf16_f32 v5, v6, v7
	v_cvt_pk_bf16_f32 v6, v0, v1
	v_cvt_pk_bf16_f32 v7, v2, v3
	flat_store_dwordx4 v[16:17], v[4:7] offset:256
	s_cbranch_vccz .LBB0_314
	s_waitcnt vmcnt(0)
	s_cmpk_gt_u32 s37, 0xff
	s_cbranch_scc1 .LBB0_325
	s_barrier

.LBB0_373:
	s_lshl_b32 s0, s0, 15
	v_add_u32_e32 v178, s0, v139
	v_add_u32_e32 v210, s0, v154
	ds_read_b128 v[118:121], v178 offset:16384
	ds_read_b128 v[122:125], v178 offset:16896
	ds_read_b128 v[158:161], v178 offset:17408
	ds_read_b128 v[162:165], v178 offset:17920
	ds_read_b128 v[166:169], v178 offset:18432
	ds_read_b128 v[170:173], v178 offset:18944
	ds_read_b128 v[174:177], v178 offset:19456
	ds_read_b128 v[178:181], v178 offset:19968
	ds_read_b128 v[182:185], v210 offset:16384
	ds_read_b128 v[186:189], v210 offset:16896
	ds_read_b128 v[190:193], v210 offset:17408
	ds_read_b128 v[194:197], v210 offset:17920
	ds_read_b128 v[198:201], v210 offset:18432
	ds_read_b128 v[202:205], v210 offset:18944
	ds_read_b128 v[206:209], v210 offset:19456
	ds_read_b128 v[228:231], v210 offset:19968
	s_waitcnt lgkmcnt(0)
	v_mfma_f32_16x16x32_bf16 v[56:59], v[118:121], v[84:87], v[56:59]
	v_mfma_f32_16x16x32_bf16 v[48:51], v[118:121], v[88:91], v[48:51]
	v_mfma_f32_16x16x32_bf16 v[60:63], v[122:125], v[84:87], v[60:63]
	v_mfma_f32_16x16x32_bf16 v[44:47], v[122:125], v[88:91], v[44:47]
	v_mfma_f32_16x16x32_bf16 v[64:67], v[158:161], v[84:87], v[64:67]
	v_mfma_f32_16x16x32_bf16 v[40:43], v[158:161], v[88:91], v[40:43]
	v_mfma_f32_16x16x32_bf16 v[68:71], v[162:165], v[84:87], v[68:71]
	v_mfma_f32_16x16x32_bf16 v[36:39], v[162:165], v[88:91], v[36:39]
	v_mfma_f32_16x16x32_bf16 v[72:75], v[166:169], v[84:87], v[72:75]
	v_mfma_f32_16x16x32_bf16 v[32:35], v[166:169], v[88:91], v[32:35]
	v_mfma_f32_16x16x32_bf16 v[76:79], v[170:173], v[84:87], v[76:79]
	v_mfma_f32_16x16x32_bf16 v[24:27], v[170:173], v[88:91], v[24:27]
	v_mfma_f32_16x16x32_bf16 v[80:83], v[174:177], v[84:87], v[80:83]
	v_mfma_f32_16x16x32_bf16 v[20:23], v[174:177], v[88:91], v[20:23]
	v_mfma_f32_16x16x32_bf16 v[28:31], v[178:181], v[84:87], v[28:31]
	v_mfma_f32_16x16x32_bf16 v[16:19], v[178:181], v[88:91], v[16:19]
	v_mfma_f32_16x16x32_bf16 v[56:59], v[182:185], v[92:95], v[56:59]
	v_mfma_f32_16x16x32_bf16 v[48:51], v[182:185], v[96:99], v[48:51]
	v_mfma_f32_16x16x32_bf16 v[60:63], v[186:189], v[92:95], v[60:63]
	v_mfma_f32_16x16x32_bf16 v[44:47], v[186:189], v[96:99], v[44:47]
	v_mfma_f32_16x16x32_bf16 v[64:67], v[190:193], v[92:95], v[64:67]
	v_mfma_f32_16x16x32_bf16 v[40:43], v[190:193], v[96:99], v[40:43]
	v_mfma_f32_16x16x32_bf16 v[68:71], v[194:197], v[92:95], v[68:71]
	v_mfma_f32_16x16x32_bf16 v[36:39], v[194:197], v[96:99], v[36:39]
	v_mfma_f32_16x16x32_bf16 v[72:75], v[198:201], v[92:95], v[72:75]
	v_mfma_f32_16x16x32_bf16 v[32:35], v[198:201], v[96:99], v[32:35]
	v_mfma_f32_16x16x32_bf16 v[76:79], v[202:205], v[92:95], v[76:79]
	v_mfma_f32_16x16x32_bf16 v[24:27], v[202:205], v[96:99], v[24:27]
	v_mfma_f32_16x16x32_bf16 v[80:83], v[206:209], v[92:95], v[80:83]
	v_mfma_f32_16x16x32_bf16 v[20:23], v[206:209], v[96:99], v[20:23]
	v_mfma_f32_16x16x32_bf16 v[28:31], v[228:231], v[92:95], v[28:31]
	v_mfma_f32_16x16x32_bf16 v[16:19], v[228:231], v[96:99], v[16:19]
	s_cmp_gt_i32 s15, s20
	s_cselect_b64 s[0:1], -1, 0
	s_cbranch_scc1 .LBB0_370
.LBB0_374:
	s_lshl_b32 s2, s14, 15
	v_add_u32_e32 v170, s2, v135
	v_add_u32_e32 v178, s2, v136
	v_add_u32_e32 v186, s2, v137
	v_add_u32_e32 v194, s2, v138
	ds_read_b128 v[84:87], v170
	ds_read_b128 v[88:91], v170 offset:1024
	ds_read_b128 v[92:95], v178
	ds_read_b128 v[96:99], v178 offset:1024
	ds_read_b128 v[118:121], v186
	ds_read_b128 v[122:125], v186 offset:1024
	ds_read_b128 v[158:161], v194
	ds_read_b128 v[162:165], v194 offset:1024
	ds_read_b128 v[166:169], v170 offset:2048
	ds_read_b128 v[170:173], v170 offset:3072
	ds_read_b128 v[174:177], v178 offset:2048
	ds_read_b128 v[178:181], v178 offset:3072
	ds_read_b128 v[182:185], v186 offset:2048
	ds_read_b128 v[186:189], v186 offset:3072
	ds_read_b128 v[190:193], v194 offset:2048
	ds_read_b128 v[194:197], v194 offset:3072
	s_waitcnt lgkmcnt(0)
	v_mfma_f32_16x16x32_bf16 v[84:87], v[84:87], v[0:3], v[52:55]
	v_mfma_f32_16x16x32_bf16 v[118:121], v[118:121], v[8:11], v[52:55]
	v_mfma_f32_16x16x32_bf16 v[88:91], v[88:91], v[0:3], v[52:55]
	v_mfma_f32_16x16x32_bf16 v[122:125], v[122:125], v[8:11], v[52:55]
	v_mfma_f32_16x16x32_bf16 v[166:169], v[166:169], v[0:3], v[52:55]
	v_mfma_f32_16x16x32_bf16 v[182:185], v[182:185], v[8:11], v[52:55]
	v_mfma_f32_16x16x32_bf16 v[170:173], v[170:173], v[0:3], v[52:55]
	v_mfma_f32_16x16x32_bf16 v[186:189], v[186:189], v[8:11], v[52:55]
	v_mfma_f32_16x16x32_bf16 v[84:87], v[92:95], v[4:7], v[84:87]
	v_mfma_f32_16x16x32_bf16 v[92:95], v[158:161], v[12:15], v[118:121]
	v_mfma_f32_16x16x32_bf16 v[88:91], v[96:99], v[4:7], v[88:91]
	v_mfma_f32_16x16x32_bf16 v[96:99], v[162:165], v[12:15], v[122:125]
	v_mfma_f32_16x16x32_bf16 v[118:121], v[174:177], v[4:7], v[166:169]
	v_mfma_f32_16x16x32_bf16 v[122:125], v[190:193], v[12:15], v[182:185]
	v_mfma_f32_16x16x32_bf16 v[158:161], v[178:181], v[4:7], v[170:173]
	v_mfma_f32_16x16x32_bf16 v[162:165], v[194:197], v[12:15], v[186:189]
	v_add_f32_e32 v170, 0x42100000, v117
	v_fma_f32 v84, -v157, |v170|, v84
	v_add_f32_e32 v168, -1.0, v170
	v_fma_f32 v92, -v157, |v170|, v92
	v_exp_f32_e32 v166, v84
	v_fma_f32 v84, -v157, |v168|, v85
	v_exp_f32_e32 v167, v92
	v_exp_f32_e32 v92, v84
	v_fma_f32 v84, -v157, |v168|, v93
	v_exp_f32_e32 v93, v84
	v_add_f32_e32 v84, -2.0, v170
	v_fma_f32 v85, -v157, |v84|, v86
	v_fma_f32 v84, -v157, |v84|, v94
	v_exp_f32_e32 v169, v84
	v_add_f32_e32 v84, 0xc0400000, v170
	v_exp_f32_e32 v168, v85
	v_fma_f32 v85, -v157, |v84|, v87
	v_fma_f32 v84, -v157, |v84|, v95
	v_exp_f32_e32 v95, v84
	v_add_f32_e32 v84, 0x42000000, v117
	v_exp_f32_e32 v94, v85
	v_fma_f32 v85, -v157, |v84|, v88
	v_exp_f32_e32 v170, v85
	v_fma_f32 v85, -v157, |v84|, v96
	v_exp_f32_e32 v171, v85
	v_add_f32_e32 v85, -1.0, v84
	v_fma_f32 v86, -v157, |v85|, v89
	v_fma_f32 v85, -v157, |v85|, v97
	v_exp_f32_e32 v97, v85
	v_add_f32_e32 v85, -2.0, v84
	v_exp_f32_e32 v96, v86
	v_fma_f32 v86, -v157, |v85|, v90
	v_fma_f32 v85, -v157, |v85|, v98
	v_add_f32_e32 v84, 0xc0400000, v84
	v_exp_f32_e32 v173, v85
	v_fma_f32 v85, -v157, |v84|, v91
	v_fma_f32 v84, -v157, |v84|, v99
	v_exp_f32_e32 v90, v85
	v_exp_f32_e32 v91, v84
	v_add_f32_e32 v84, v114, v166
	v_add_f32_e32 v85, v115, v167
	v_exp_f32_e32 v172, v86
	v_add_f32_e32 v84, v84, v92
	v_add_f32_e32 v85, v85, v93
	v_add_f32_e32 v84, v84, v168
	v_add_f32_e32 v85, v85, v169
	v_cvt_pk_bf16_f32 v88, v167, v93
	v_cvt_pk_bf16_f32 v86, v170, v96
	v_cvt_pk_bf16_f32 v87, v172, v90
	v_add_f32_e32 v84, v84, v94
	v_add_f32_e32 v85, v85, v95
	v_add_f32_e32 v84, v84, v170
	v_add_f32_e32 v85, v85, v171
	v_add_f32_e32 v84, v84, v96
	v_add_f32_e32 v85, v85, v97
	v_add_f32_e32 v84, v84, v172
	v_add_f32_e32 v85, v85, v173
	v_add_f32_e32 v98, v84, v90
	v_add_f32_e32 v99, v85, v91
	v_cvt_pk_bf16_f32 v84, v166, v92
	v_cvt_pk_bf16_f32 v90, v171, v97
	v_cvt_pk_bf16_f32 v85, v168, v94
	v_cvt_pk_bf16_f32 v89, v169, v95
	v_add_f32_e32 v92, 4.0, v117
	v_fma_f32 v93, -v157, |v92|, v118
	v_exp_f32_e32 v96, v93
	v_fma_f32 v93, -v157, |v92|, v122
	v_exp_f32_e32 v97, v93
	v_add_f32_e32 v93, -1.0, v92
	v_fma_f32 v94, -v157, |v93|, v119
	v_fma_f32 v93, -v157, |v93|, v123
	v_exp_f32_e32 v119, v93
	v_add_f32_e32 v93, -2.0, v92
	v_exp_f32_e32 v118, v94
	v_fma_f32 v94, -v157, |v93|, v120
	v_exp_f32_e32 v122, v94
	v_fma_f32 v93, -v157, |v93|, v124
	v_add_f32_e32 v92, 0xc0400000, v92
	v_exp_f32_e32 v123, v93
	v_fma_f32 v93, -v157, |v92|, v121
	v_fma_f32 v92, -v157, |v92|, v125
	v_exp_f32_e32 v121, v92
	v_fma_f32 v92, -v157, |v117|, v158
	v_exp_f32_e32 v124, v92
	v_fma_f32 v92, -v157, |v117|, v162
	v_exp_f32_e32 v125, v92
	v_add_f32_e32 v92, -1.0, v117
	v_exp_f32_e32 v120, v93
	v_fma_f32 v93, -v157, |v92|, v159
	v_fma_f32 v92, -v157, |v92|, v163
	v_exp_f32_e32 v159, v92
	v_add_f32_e32 v92, -2.0, v117
	v_exp_f32_e32 v158, v93
	v_fma_f32 v93, -v157, |v92|, v160
	v_fma_f32 v92, -v157, |v92|, v164
	v_exp_f32_e32 v162, v93
	v_exp_f32_e32 v163, v92
	v_add_f32_e32 v92, v98, v96
	v_add_f32_e32 v93, v99, v97
	v_add_f32_e32 v94, 0xc0400000, v117
	v_add_f32_e32 v92, v92, v118
	v_add_f32_e32 v93, v93, v119
	v_fma_f32 v95, -v157, |v94|, v161
	v_add_f32_e32 v92, v92, v122
	v_add_f32_e32 v93, v93, v123
	v_fma_f32 v94, -v157, |v94|, v165
	v_add_f32_e32 v92, v92, v120
	v_add_f32_e32 v93, v93, v121
	v_exp_f32_e32 v98, v95
	v_exp_f32_e32 v99, v94
	v_add_f32_e32 v92, v92, v124
	v_add_f32_e32 v93, v93, v125
	v_cvt_pk_bf16_f32 v91, v173, v91
	v_cvt_pk_bf16_f32 v94, v124, v158
	v_cvt_pk_bf16_f32 v95, v162, v98
	v_add_f32_e32 v92, v92, v158
	v_add_f32_e32 v93, v93, v159
	v_add_f32_e32 v92, v92, v162
	v_add_f32_e32 v93, v93, v163
	v_add_f32_e32 v114, v92, v98
	v_add_f32_e32 v115, v93, v99
	v_cvt_pk_bf16_f32 v92, v96, v118
	v_cvt_pk_bf16_f32 v93, v122, v120
	v_cvt_pk_bf16_f32 v96, v97, v119
	v_cvt_pk_bf16_f32 v97, v123, v121
	v_cvt_pk_bf16_f32 v98, v125, v159
	v_cvt_pk_bf16_f32 v99, v163, v99
	s_or_b64 s[18:19], s[54:55], s[0:1]
	s_and_b64 vcc, exec, s[18:19]
	s_cbranch_vccnz .LBB0_371
.LBB0_375:
	s_lshl_b32 s2, s14, 15
	v_add_u32_e32 v178, s2, v139
	v_add_u32_e32 v210, s2, v154
	ds_read_b128 v[118:121], v178 offset:16384
	ds_read_b128 v[122:125], v178 offset:16896
	ds_read_b128 v[158:161], v178 offset:17408
	ds_read_b128 v[162:165], v178 offset:17920
	ds_read_b128 v[166:169], v178 offset:18432
	ds_read_b128 v[170:173], v178 offset:18944
	ds_read_b128 v[174:177], v178 offset:19456
	ds_read_b128 v[178:181], v178 offset:19968
	ds_read_b128 v[182:185], v210 offset:16384
	ds_read_b128 v[186:189], v210 offset:16896
	ds_read_b128 v[190:193], v210 offset:17408
	ds_read_b128 v[194:197], v210 offset:17920
	ds_read_b128 v[198:201], v210 offset:18432
	ds_read_b128 v[202:205], v210 offset:18944
	ds_read_b128 v[206:209], v210 offset:19456
	ds_read_b128 v[228:231], v210 offset:19968
	s_waitcnt lgkmcnt(0)
	v_mfma_f32_16x16x32_bf16 v[56:59], v[118:121], v[84:87], v[56:59]
	v_mfma_f32_16x16x32_bf16 v[48:51], v[118:121], v[88:91], v[48:51]
	v_mfma_f32_16x16x32_bf16 v[60:63], v[122:125], v[84:87], v[60:63]
	v_mfma_f32_16x16x32_bf16 v[44:47], v[122:125], v[88:91], v[44:47]
	v_mfma_f32_16x16x32_bf16 v[64:67], v[158:161], v[84:87], v[64:67]
	v_mfma_f32_16x16x32_bf16 v[40:43], v[158:161], v[88:91], v[40:43]
	v_mfma_f32_16x16x32_bf16 v[68:71], v[162:165], v[84:87], v[68:71]
	v_mfma_f32_16x16x32_bf16 v[36:39], v[162:165], v[88:91], v[36:39]
	v_mfma_f32_16x16x32_bf16 v[72:75], v[166:169], v[84:87], v[72:75]
	v_mfma_f32_16x16x32_bf16 v[32:35], v[166:169], v[88:91], v[32:35]
	v_mfma_f32_16x16x32_bf16 v[76:79], v[170:173], v[84:87], v[76:79]
	v_mfma_f32_16x16x32_bf16 v[24:27], v[170:173], v[88:91], v[24:27]
	v_mfma_f32_16x16x32_bf16 v[80:83], v[174:177], v[84:87], v[80:83]
	v_mfma_f32_16x16x32_bf16 v[20:23], v[174:177], v[88:91], v[20:23]
	v_mfma_f32_16x16x32_bf16 v[28:31], v[178:181], v[84:87], v[28:31]
	v_mfma_f32_16x16x32_bf16 v[16:19], v[178:181], v[88:91], v[16:19]
	v_mfma_f32_16x16x32_bf16 v[56:59], v[182:185], v[92:95], v[56:59]
	v_mfma_f32_16x16x32_bf16 v[48:51], v[182:185], v[96:99], v[48:51]
	v_mfma_f32_16x16x32_bf16 v[60:63], v[186:189], v[92:95], v[60:63]
	v_mfma_f32_16x16x32_bf16 v[44:47], v[186:189], v[96:99], v[44:47]
	v_mfma_f32_16x16x32_bf16 v[64:67], v[190:193], v[92:95], v[64:67]
	v_mfma_f32_16x16x32_bf16 v[40:43], v[190:193], v[96:99], v[40:43]
	v_mfma_f32_16x16x32_bf16 v[68:71], v[194:197], v[92:95], v[68:71]
	v_mfma_f32_16x16x32_bf16 v[36:39], v[194:197], v[96:99], v[36:39]
	v_mfma_f32_16x16x32_bf16 v[72:75], v[198:201], v[92:95], v[72:75]
	v_mfma_f32_16x16x32_bf16 v[32:35], v[198:201], v[96:99], v[32:35]
	v_mfma_f32_16x16x32_bf16 v[76:79], v[202:205], v[92:95], v[76:79]
	v_mfma_f32_16x16x32_bf16 v[24:27], v[202:205], v[96:99], v[24:27]
	v_mfma_f32_16x16x32_bf16 v[80:83], v[206:209], v[92:95], v[80:83]
	v_mfma_f32_16x16x32_bf16 v[20:23], v[206:209], v[96:99], v[20:23]
	v_mfma_f32_16x16x32_bf16 v[28:31], v[228:231], v[92:95], v[28:31]
	v_mfma_f32_16x16x32_bf16 v[16:19], v[228:231], v[96:99], v[16:19]
	v_add_f32_e32 v117, 0xc2800000, v117
	s_and_b64 vcc, exec, s[0:1]
	s_cbranch_vccnz .LBB0_377

.LBB0_405:
	s_add_i32 s21, s0, 2
	s_add_u32 s1, vcc_lo, 0xfffe0080
	s_addc_u32 s2, vcc_hi, -1
	s_add_i32 s18, 0, 0x10000
	v_add_u32_e32 v164, s18, v178
	ds_read_b128 v[128:131], v164
	ds_read_b128 v[132:135], v164 offset:1024
	ds_read_b128 v[136:139], v164 offset:2048
	ds_read_b128 v[164:167], v164 offset:3072
	s_cmp_eq_u32 s5, s0
	s_cselect_b32 s0, s10, s17
	s_cselect_b32 s89, s9, s2
	s_cselect_b32 s88, s8, s1
	s_cselect_b32 s1, s11, s20
	v_lshl_add_u64 v[176:177], vcc, 0, v[162:163]
	s_add_i32 m0, s97, 0xc000
	ds_read_b128 v[168:171], v179
	ds_read_b128 v[172:175], v179 offset:1024
	ds_read_b128 v[180:183], v179 offset:2048
	ds_read_b128 v[184:187], v179 offset:3072
	ds_read_b128 v[188:191], v179 offset:4096
	ds_read_b128 v[192:195], v179 offset:5120
	ds_read_b128 v[196:199], v179 offset:6144
	ds_read_b128 v[200:203], v179 offset:7168
	global_load_lds_dwordx4 v[176:177], off
	v_lshl_add_u64 v[176:177], vcc, 0, v[160:161]
	s_add_i32 m0, s97, 0xe000
	s_nop 0
	global_load_lds_dwordx4 v[176:177], off
	s_waitcnt lgkmcnt(8)
	s_barrier
	s_waitcnt lgkmcnt(0)
	s_setprio 1
	v_mfma_f32_16x16x32_bf16 v[120:123], v[128:131], v[168:171], v[120:123]
	v_mfma_f32_16x16x32_bf16 v[68:71], v[136:139], v[168:171], v[68:71]
	v_mfma_f32_16x16x32_bf16 v[116:119], v[128:131], v[180:183], v[116:119]
	v_mfma_f32_16x16x32_bf16 v[60:63], v[136:139], v[180:183], v[60:63]
	v_mfma_f32_16x16x32_bf16 v[108:111], v[128:131], v[188:191], v[108:111]
	v_mfma_f32_16x16x32_bf16 v[44:47], v[136:139], v[188:191], v[44:47]
	v_mfma_f32_16x16x32_bf16 v[100:103], v[128:131], v[196:199], v[100:103]
	v_mfma_f32_16x16x32_bf16 v[36:39], v[136:139], v[196:199], v[36:39]
	v_mfma_f32_16x16x32_bf16 v[120:123], v[132:135], v[172:175], v[120:123]
	v_mfma_f32_16x16x32_bf16 v[68:71], v[164:167], v[172:175], v[68:71]
	v_mfma_f32_16x16x32_bf16 v[116:119], v[132:135], v[184:187], v[116:119]
	v_mfma_f32_16x16x32_bf16 v[60:63], v[164:167], v[184:187], v[60:63]
	v_mfma_f32_16x16x32_bf16 v[108:111], v[132:135], v[192:195], v[108:111]
	v_mfma_f32_16x16x32_bf16 v[44:47], v[164:167], v[192:195], v[44:47]
	v_mfma_f32_16x16x32_bf16 v[100:103], v[132:135], v[200:203], v[100:103]
	v_mfma_f32_16x16x32_bf16 v[36:39], v[164:167], v[200:203], v[36:39]
	s_setprio 0
	s_barrier
	s_add_i32 s2, 0, 0x14000
	v_add_u32_e32 v176, s2, v178
	s_add_i32 s18, s18, s59
	ds_read_b128 v[204:207], v176
	ds_read_b128 v[208:211], v176 offset:1024
	ds_read_b128 v[228:231], v176 offset:2048
	s_mov_b32 m0, s18
	ds_read_b128 v[232:235], v176 offset:3072
	global_load_lds_dwordx4 v140, s[0:1]
	s_add_i32 m0, s18, 0x2000
	s_nop 0
	global_load_lds_dwordx4 v158, s[0:1]
	s_barrier
	s_waitcnt lgkmcnt(0)
	s_setprio 1
	v_mfma_f32_16x16x32_bf16 v[124:127], v[204:207], v[168:171], v[124:127]
	v_mfma_f32_16x16x32_bf16 v[64:67], v[228:231], v[168:171], v[64:67]
	v_mfma_f32_16x16x32_bf16 v[112:115], v[204:207], v[180:183], v[112:115]
	v_mfma_f32_16x16x32_bf16 v[56:59], v[228:231], v[180:183], v[56:59]
	v_mfma_f32_16x16x32_bf16 v[104:107], v[204:207], v[188:191], v[104:107]
	v_mfma_f32_16x16x32_bf16 v[40:43], v[228:231], v[188:191], v[40:43]
	v_mfma_f32_16x16x32_bf16 v[96:99], v[204:207], v[196:199], v[96:99]
	v_mfma_f32_16x16x32_bf16 v[32:35], v[228:231], v[196:199], v[32:35]
	v_mfma_f32_16x16x32_bf16 v[124:127], v[208:211], v[172:175], v[124:127]
	v_mfma_f32_16x16x32_bf16 v[64:67], v[232:235], v[172:175], v[64:67]
	v_mfma_f32_16x16x32_bf16 v[112:115], v[208:211], v[184:187], v[112:115]
	v_mfma_f32_16x16x32_bf16 v[56:59], v[232:235], v[184:187], v[56:59]
	v_mfma_f32_16x16x32_bf16 v[104:107], v[208:211], v[192:195], v[104:107]
	v_mfma_f32_16x16x32_bf16 v[40:43], v[232:235], v[192:195], v[40:43]
	v_mfma_f32_16x16x32_bf16 v[96:99], v[208:211], v[200:203], v[96:99]
	v_mfma_f32_16x16x32_bf16 v[32:35], v[232:235], v[200:203], v[32:35]
	s_setprio 0
	s_mov_b32 m0, s97
	s_barrier
	ds_read_b128 v[168:171], v179 offset:16384
	ds_read_b128 v[172:175], v179 offset:17408
	ds_read_b128 v[180:183], v179 offset:18432
	ds_read_b128 v[184:187], v179 offset:19456
	ds_read_b128 v[188:191], v179 offset:20480
	ds_read_b128 v[192:195], v179 offset:21504
	ds_read_b128 v[196:199], v179 offset:22528
	global_load_lds_dwordx4 v154, s[88:89]
	s_mov_b32 m0, s74
	ds_read_b128 v[200:203], v179 offset:23552
	global_load_lds_dwordx4 v156, s[88:89]
	s_barrier
	s_waitcnt lgkmcnt(0)
	s_setprio 1
	v_mfma_f32_16x16x32_bf16 v[92:95], v[128:131], v[168:171], v[92:95]
	v_mfma_f32_16x16x32_bf16 v[28:31], v[136:139], v[168:171], v[28:31]
	v_mfma_f32_16x16x32_bf16 v[84:87], v[128:131], v[180:183], v[84:87]
	v_mfma_f32_16x16x32_bf16 v[20:23], v[136:139], v[180:183], v[20:23]
	v_mfma_f32_16x16x32_bf16 v[76:79], v[128:131], v[188:191], v[76:79]
	v_mfma_f32_16x16x32_bf16 v[12:15], v[136:139], v[188:191], v[12:15]
	v_mfma_f32_16x16x32_bf16 v[52:55], v[128:131], v[196:199], v[52:55]
	v_mfma_f32_16x16x32_bf16 v[4:7], v[136:139], v[196:199], v[4:7]
	v_mfma_f32_16x16x32_bf16 v[92:95], v[132:135], v[172:175], v[92:95]
	v_mfma_f32_16x16x32_bf16 v[28:31], v[164:167], v[172:175], v[28:31]
	v_mfma_f32_16x16x32_bf16 v[84:87], v[132:135], v[184:187], v[84:87]
	v_mfma_f32_16x16x32_bf16 v[20:23], v[164:167], v[184:187], v[20:23]
	v_mfma_f32_16x16x32_bf16 v[76:79], v[132:135], v[192:195], v[76:79]
	v_mfma_f32_16x16x32_bf16 v[12:15], v[164:167], v[192:195], v[12:15]
	v_mfma_f32_16x16x32_bf16 v[52:55], v[132:135], v[200:203], v[52:55]
	v_mfma_f32_16x16x32_bf16 v[4:7], v[164:167], v[200:203], v[4:7]
	s_setprio 0
	s_barrier
	s_add_u32 s18, s0, 0x10000
	s_addc_u32 s19, s1, 0
	s_add_i32 s2, s2, s59
	s_mov_b32 m0, s2
	s_nop 0
	global_load_lds_dwordx4 v140, s[18:19]
	s_add_i32 m0, s2, 0x2000
	s_nop 0
	global_load_lds_dwordx4 v158, s[18:19]
	s_waitcnt vmcnt(6)
	s_barrier
	s_setprio 1
	v_mfma_f32_16x16x32_bf16 v[88:91], v[204:207], v[168:171], v[88:91]
	v_mfma_f32_16x16x32_bf16 v[24:27], v[228:231], v[168:171], v[24:27]
	v_mfma_f32_16x16x32_bf16 v[80:83], v[204:207], v[180:183], v[80:83]
	v_mfma_f32_16x16x32_bf16 v[16:19], v[228:231], v[180:183], v[16:19]
	v_mfma_f32_16x16x32_bf16 v[72:75], v[204:207], v[188:191], v[72:75]
	v_mfma_f32_16x16x32_bf16 v[8:11], v[228:231], v[188:191], v[8:11]
	v_mfma_f32_16x16x32_bf16 v[48:51], v[204:207], v[196:199], v[48:51]
	v_mfma_f32_16x16x32_bf16 v[0:3], v[228:231], v[196:199], v[0:3]
	v_mfma_f32_16x16x32_bf16 v[88:91], v[208:211], v[172:175], v[88:91]
	v_mfma_f32_16x16x32_bf16 v[24:27], v[232:235], v[172:175], v[24:27]
	v_mfma_f32_16x16x32_bf16 v[80:83], v[208:211], v[184:187], v[80:83]
	v_mfma_f32_16x16x32_bf16 v[16:19], v[232:235], v[184:187], v[16:19]
	v_mfma_f32_16x16x32_bf16 v[72:75], v[208:211], v[192:195], v[72:75]
	v_mfma_f32_16x16x32_bf16 v[8:11], v[232:235], v[192:195], v[8:11]
	v_mfma_f32_16x16x32_bf16 v[48:51], v[208:211], v[200:203], v[48:51]
	v_mfma_f32_16x16x32_bf16 v[0:3], v[232:235], v[200:203], v[0:3]
	s_setprio 0
	s_add_i32 s2, 0, 0x18000
	v_add_u32_e32 v164, s2, v178
	s_barrier
	ds_read_b128 v[128:131], v164
	ds_read_b128 v[132:135], v164 offset:1024
	ds_read_b128 v[136:139], v164 offset:2048
	ds_read_b128 v[164:167], v164 offset:3072
	s_add_u32 s18, s88, 0x20000
	s_addc_u32 s19, s89, 0
	s_mov_b32 m0, s75
	ds_read_b128 v[168:171], v179 offset:32768
	ds_read_b128 v[172:175], v179 offset:33792
	ds_read_b128 v[180:183], v179 offset:34816
	ds_read_b128 v[184:187], v179 offset:35840
	ds_read_b128 v[188:191], v179 offset:36864
	ds_read_b128 v[192:195], v179 offset:37888
	ds_read_b128 v[196:199], v179 offset:38912
	global_load_lds_dwordx4 v154, s[18:19]
	s_mov_b32 m0, s72
	ds_read_b128 v[200:203], v179 offset:39936
	global_load_lds_dwordx4 v156, s[18:19]
	s_waitcnt lgkmcnt(8)
	s_barrier
	s_waitcnt lgkmcnt(0)
	s_setprio 1
	v_mfma_f32_16x16x32_bf16 v[120:123], v[128:131], v[168:171], v[120:123]
	v_mfma_f32_16x16x32_bf16 v[68:71], v[136:139], v[168:171], v[68:71]
	v_mfma_f32_16x16x32_bf16 v[116:119], v[128:131], v[180:183], v[116:119]
	v_mfma_f32_16x16x32_bf16 v[60:63], v[136:139], v[180:183], v[60:63]
	v_mfma_f32_16x16x32_bf16 v[108:111], v[128:131], v[188:191], v[108:111]
	v_mfma_f32_16x16x32_bf16 v[44:47], v[136:139], v[188:191], v[44:47]
	v_mfma_f32_16x16x32_bf16 v[100:103], v[128:131], v[196:199], v[100:103]
	v_mfma_f32_16x16x32_bf16 v[36:39], v[136:139], v[196:199], v[36:39]
	v_mfma_f32_16x16x32_bf16 v[120:123], v[132:135], v[172:175], v[120:123]
	v_mfma_f32_16x16x32_bf16 v[68:71], v[164:167], v[172:175], v[68:71]
	v_mfma_f32_16x16x32_bf16 v[116:119], v[132:135], v[184:187], v[116:119]
	v_mfma_f32_16x16x32_bf16 v[60:63], v[164:167], v[184:187], v[60:63]
	v_mfma_f32_16x16x32_bf16 v[108:111], v[132:135], v[192:195], v[108:111]
	v_mfma_f32_16x16x32_bf16 v[44:47], v[164:167], v[192:195], v[44:47]
	v_mfma_f32_16x16x32_bf16 v[100:103], v[132:135], v[200:203], v[100:103]
	v_mfma_f32_16x16x32_bf16 v[36:39], v[164:167], v[200:203], v[36:39]
	s_setprio 0
	s_barrier
	s_add_i32 s18, 0, 0x1c000
	s_add_i32 s2, s2, s59
	v_add_u32_e32 v232, s18, v178
	s_mov_b32 m0, s2
	ds_read_b128 v[204:207], v232
	ds_read_b128 v[208:211], v232 offset:1024
	ds_read_b128 v[228:231], v232 offset:2048
	ds_read_b128 v[232:235], v232 offset:3072
	s_add_u32 s100, s0, 0x80
	s_addc_u32 s101, s1, 0
	global_load_lds_dwordx4 v140, s[100:101]
	s_add_i32 m0, s2, 0x2000
	s_nop 0
	global_load_lds_dwordx4 v158, s[100:101]
	s_barrier
	s_waitcnt lgkmcnt(0)
	s_setprio 1
	v_mfma_f32_16x16x32_bf16 v[124:127], v[204:207], v[168:171], v[124:127]
	v_mfma_f32_16x16x32_bf16 v[64:67], v[228:231], v[168:171], v[64:67]
	v_mfma_f32_16x16x32_bf16 v[112:115], v[204:207], v[180:183], v[112:115]
	v_mfma_f32_16x16x32_bf16 v[56:59], v[228:231], v[180:183], v[56:59]
	v_mfma_f32_16x16x32_bf16 v[104:107], v[204:207], v[188:191], v[104:107]
	v_mfma_f32_16x16x32_bf16 v[40:43], v[228:231], v[188:191], v[40:43]
	v_mfma_f32_16x16x32_bf16 v[96:99], v[204:207], v[196:199], v[96:99]
	v_mfma_f32_16x16x32_bf16 v[32:35], v[228:231], v[196:199], v[32:35]
	v_mfma_f32_16x16x32_bf16 v[124:127], v[208:211], v[172:175], v[124:127]
	v_mfma_f32_16x16x32_bf16 v[64:67], v[232:235], v[172:175], v[64:67]
	v_mfma_f32_16x16x32_bf16 v[112:115], v[208:211], v[184:187], v[112:115]
	v_mfma_f32_16x16x32_bf16 v[56:59], v[232:235], v[184:187], v[56:59]
	v_mfma_f32_16x16x32_bf16 v[104:107], v[208:211], v[192:195], v[104:107]
	v_mfma_f32_16x16x32_bf16 v[40:43], v[232:235], v[192:195], v[40:43]
	v_mfma_f32_16x16x32_bf16 v[96:99], v[208:211], v[200:203], v[96:99]
	v_mfma_f32_16x16x32_bf16 v[32:35], v[232:235], v[200:203], v[32:35]
	s_setprio 0
	s_mov_b32 m0, s38
	s_barrier
	ds_read_b128 v[168:171], v179 offset:49152
	ds_read_b128 v[172:175], v179 offset:50176
	ds_read_b128 v[180:183], v179 offset:51200
	ds_read_b128 v[184:187], v179 offset:52224
	ds_read_b128 v[188:191], v179 offset:53248
	ds_read_b128 v[192:195], v179 offset:54272
	ds_read_b128 v[196:199], v179 offset:55296
	ds_read_b128 v[200:203], v179 offset:56320
	s_add_u32 s100, s88, 0x80
	s_addc_u32 s101, s89, 0
	global_load_lds_dwordx4 v154, s[100:101]
	s_mov_b32 m0, s39
	s_nop 0
	global_load_lds_dwordx4 v156, s[100:101]
	s_barrier
	s_waitcnt lgkmcnt(0)
	s_setprio 1
	v_mfma_f32_16x16x32_bf16 v[92:95], v[128:131], v[168:171], v[92:95]
	v_mfma_f32_16x16x32_bf16 v[28:31], v[136:139], v[168:171], v[28:31]
	v_mfma_f32_16x16x32_bf16 v[84:87], v[128:131], v[180:183], v[84:87]
	v_mfma_f32_16x16x32_bf16 v[20:23], v[136:139], v[180:183], v[20:23]
	v_mfma_f32_16x16x32_bf16 v[76:79], v[128:131], v[188:191], v[76:79]
	v_mfma_f32_16x16x32_bf16 v[12:15], v[136:139], v[188:191], v[12:15]
	v_mfma_f32_16x16x32_bf16 v[52:55], v[128:131], v[196:199], v[52:55]
	v_mfma_f32_16x16x32_bf16 v[4:7], v[136:139], v[196:199], v[4:7]
	v_mfma_f32_16x16x32_bf16 v[92:95], v[132:135], v[172:175], v[92:95]
	v_mfma_f32_16x16x32_bf16 v[28:31], v[164:167], v[172:175], v[28:31]
	v_mfma_f32_16x16x32_bf16 v[84:87], v[132:135], v[184:187], v[84:87]
	v_mfma_f32_16x16x32_bf16 v[20:23], v[164:167], v[184:187], v[20:23]
	v_mfma_f32_16x16x32_bf16 v[76:79], v[132:135], v[192:195], v[76:79]
	v_mfma_f32_16x16x32_bf16 v[12:15], v[164:167], v[192:195], v[12:15]
	v_mfma_f32_16x16x32_bf16 v[52:55], v[132:135], v[200:203], v[52:55]
	v_mfma_f32_16x16x32_bf16 v[4:7], v[164:167], v[200:203], v[4:7]
	s_setprio 0
	s_barrier
	s_add_u32 s0, s0, 0x10080
	s_addc_u32 s1, s1, 0
	s_add_i32 s2, s18, s59
	s_mov_b32 m0, s2
	s_nop 0
	global_load_lds_dwordx4 v140, s[0:1]
	s_add_i32 m0, s2, 0x2000
	s_nop 0
	global_load_lds_dwordx4 v158, s[0:1]
	s_waitcnt vmcnt(6)
	s_barrier
	s_setprio 1
	v_mfma_f32_16x16x32_bf16 v[88:91], v[204:207], v[168:171], v[88:91]
	v_mfma_f32_16x16x32_bf16 v[24:27], v[228:231], v[168:171], v[24:27]
	v_mfma_f32_16x16x32_bf16 v[80:83], v[204:207], v[180:183], v[80:83]
	v_mfma_f32_16x16x32_bf16 v[16:19], v[228:231], v[180:183], v[16:19]
	v_mfma_f32_16x16x32_bf16 v[72:75], v[204:207], v[188:191], v[72:75]
	v_mfma_f32_16x16x32_bf16 v[8:11], v[228:231], v[188:191], v[8:11]
	v_mfma_f32_16x16x32_bf16 v[48:51], v[204:207], v[196:199], v[48:51]
	v_mfma_f32_16x16x32_bf16 v[0:3], v[228:231], v[196:199], v[0:3]
	v_mfma_f32_16x16x32_bf16 v[88:91], v[208:211], v[172:175], v[88:91]
	v_mfma_f32_16x16x32_bf16 v[24:27], v[232:235], v[172:175], v[24:27]
	v_mfma_f32_16x16x32_bf16 v[80:83], v[208:211], v[184:187], v[80:83]
	v_mfma_f32_16x16x32_bf16 v[16:19], v[232:235], v[184:187], v[16:19]
	v_mfma_f32_16x16x32_bf16 v[72:75], v[208:211], v[192:195], v[72:75]
	v_mfma_f32_16x16x32_bf16 v[8:11], v[232:235], v[192:195], v[8:11]
	v_mfma_f32_16x16x32_bf16 v[48:51], v[208:211], v[200:203], v[48:51]
	v_mfma_f32_16x16x32_bf16 v[0:3], v[232:235], v[200:203], v[0:3]
	s_setprio 0
	s_add_u32 s17, s17, 0x100
	s_addc_u32 s20, s20, 0
	s_add_u32 vcc_lo, vcc_lo, 0x100
	s_addc_u32 vcc_hi, vcc_hi, 0
	s_cmp_ge_i32 s21, s36
	s_mov_b32 s0, s21
	s_barrier
	s_cbranch_scc0 .LBB0_405
	s_branch .LBB0_392

.LBB0_507:
	s_add_u32 s0, s8, 0xfffc0080
	s_addc_u32 s1, s9, -1
	s_add_i32 s2, 0, 0x10000
	v_add_u32_e32 v140, s2, v168
	ds_read_b128 v[154:157], v140
	ds_read_b128 v[158:161], v140 offset:1024
	ds_read_b128 v[162:165], v140 offset:2048
	ds_read_b128 v[170:173], v140 offset:3072
	s_cmp_eq_u32 s21, 12
	s_cselect_b32 s31, s29, s1
	s_cselect_b32 s30, s28, s0
	s_cselect_b32 s1, s11, s19
	s_cselect_b32 s0, s10, s17
	s_add_i32 m0, s36, 0xc000
	ds_read_b128 v[174:177], v169
	ds_read_b128 v[178:181], v169 offset:1024
	ds_read_b128 v[182:185], v169 offset:2048
	ds_read_b128 v[186:189], v169 offset:3072
	ds_read_b128 v[190:193], v169 offset:4096
	ds_read_b128 v[194:197], v169 offset:5120
	ds_read_b128 v[198:201], v169 offset:6144
	global_load_lds_dwordx4 v138, s[8:9]
	s_add_i32 m0, s36, 0xe000
	ds_read_b128 v[202:205], v169 offset:7168
	global_load_lds_dwordx4 v136, s[8:9]
	s_waitcnt lgkmcnt(8)
	s_barrier
	s_waitcnt lgkmcnt(0)
	s_setprio 1
	v_mfma_f32_16x16x32_bf16 v[124:127], v[154:157], v[174:177], v[124:127]
	v_mfma_f32_16x16x32_bf16 v[120:123], v[162:165], v[174:177], v[120:123]
	v_mfma_f32_16x16x32_bf16 v[112:115], v[154:157], v[182:185], v[112:115]
	v_mfma_f32_16x16x32_bf16 v[104:107], v[162:165], v[182:185], v[104:107]
	v_mfma_f32_16x16x32_bf16 v[96:99], v[154:157], v[190:193], v[96:99]
	v_mfma_f32_16x16x32_bf16 v[88:91], v[162:165], v[190:193], v[88:91]
	v_mfma_f32_16x16x32_bf16 v[80:83], v[154:157], v[198:201], v[80:83]
	v_mfma_f32_16x16x32_bf16 v[72:75], v[162:165], v[198:201], v[72:75]
	v_mfma_f32_16x16x32_bf16 v[124:127], v[158:161], v[178:181], v[124:127]
	v_mfma_f32_16x16x32_bf16 v[120:123], v[170:173], v[178:181], v[120:123]
	v_mfma_f32_16x16x32_bf16 v[112:115], v[158:161], v[186:189], v[112:115]
	v_mfma_f32_16x16x32_bf16 v[104:107], v[170:173], v[186:189], v[104:107]
	v_mfma_f32_16x16x32_bf16 v[96:99], v[158:161], v[194:197], v[96:99]
	v_mfma_f32_16x16x32_bf16 v[88:91], v[170:173], v[194:197], v[88:91]
	v_mfma_f32_16x16x32_bf16 v[80:83], v[158:161], v[202:205], v[80:83]
	v_mfma_f32_16x16x32_bf16 v[72:75], v[170:173], v[202:205], v[72:75]
	s_setprio 0
	s_barrier
	s_add_i32 s49, 0, 0x14000
	s_add_i32 s2, s2, s35
	v_add_u32_e32 v140, s49, v168
	s_mov_b32 m0, s2
	ds_read_b128 v[206:209], v140
	ds_read_b128 v[228:231], v140 offset:1024
	ds_read_b128 v[232:235], v140 offset:2048
	global_load_lds_dwordx4 v130, s[0:1]
	s_add_i32 m0, s2, 0x2000
	ds_read_b128 v[236:239], v140 offset:3072
	global_load_lds_dwordx4 v134, s[0:1]
	s_barrier
	s_waitcnt lgkmcnt(0)
	s_setprio 1
	v_mfma_f32_16x16x32_bf16 v[116:119], v[206:209], v[174:177], v[116:119]
	v_mfma_f32_16x16x32_bf16 v[108:111], v[232:235], v[174:177], v[108:111]
	v_mfma_f32_16x16x32_bf16 v[100:103], v[206:209], v[182:185], v[100:103]
	v_mfma_f32_16x16x32_bf16 v[92:95], v[232:235], v[182:185], v[92:95]
	v_mfma_f32_16x16x32_bf16 v[84:87], v[206:209], v[190:193], v[84:87]
	v_mfma_f32_16x16x32_bf16 v[76:79], v[232:235], v[190:193], v[76:79]
	v_mfma_f32_16x16x32_bf16 v[68:71], v[206:209], v[198:201], v[68:71]
	v_mfma_f32_16x16x32_bf16 v[64:67], v[232:235], v[198:201], v[64:67]
	v_mfma_f32_16x16x32_bf16 v[116:119], v[228:231], v[178:181], v[116:119]
	v_mfma_f32_16x16x32_bf16 v[108:111], v[236:239], v[178:181], v[108:111]
	v_mfma_f32_16x16x32_bf16 v[100:103], v[228:231], v[186:189], v[100:103]
	v_mfma_f32_16x16x32_bf16 v[92:95], v[236:239], v[186:189], v[92:95]
	v_mfma_f32_16x16x32_bf16 v[84:87], v[228:231], v[194:197], v[84:87]
	v_mfma_f32_16x16x32_bf16 v[76:79], v[236:239], v[194:197], v[76:79]
	v_mfma_f32_16x16x32_bf16 v[68:71], v[228:231], v[202:205], v[68:71]
	v_mfma_f32_16x16x32_bf16 v[64:67], v[236:239], v[202:205], v[64:67]
	s_setprio 0
	s_mov_b32 m0, s36
	v_lshl_add_u64 v[240:241], s[30:31], 0, v[128:129]
	s_barrier
	ds_read_b128 v[174:177], v169 offset:16384
	ds_read_b128 v[178:181], v169 offset:17408
	ds_read_b128 v[182:185], v169 offset:18432
	ds_read_b128 v[186:189], v169 offset:19456
	ds_read_b128 v[190:193], v169 offset:20480
	ds_read_b128 v[194:197], v169 offset:21504
	ds_read_b128 v[198:201], v169 offset:22528
	ds_read_b128 v[202:205], v169 offset:23552
	global_load_lds_dwordx4 v128, s[30:31]
	v_lshl_add_u64 v[242:243], s[30:31], 0, v[132:133]
	s_mov_b32 m0, s37
	s_nop 0
	global_load_lds_dwordx4 v132, s[30:31]
	s_barrier
	s_waitcnt lgkmcnt(0)
	s_setprio 1
	v_mfma_f32_16x16x32_bf16 v[60:63], v[154:157], v[174:177], v[60:63]
	v_mfma_f32_16x16x32_bf16 v[56:59], v[162:165], v[174:177], v[56:59]
	v_mfma_f32_16x16x32_bf16 v[48:51], v[154:157], v[182:185], v[48:51]
	v_mfma_f32_16x16x32_bf16 v[40:43], v[162:165], v[182:185], v[40:43]
	v_mfma_f32_16x16x32_bf16 v[32:35], v[154:157], v[190:193], v[32:35]
	v_mfma_f32_16x16x32_bf16 v[24:27], v[162:165], v[190:193], v[24:27]
	v_mfma_f32_16x16x32_bf16 v[16:19], v[154:157], v[198:201], v[16:19]
	v_mfma_f32_16x16x32_bf16 v[8:11], v[162:165], v[198:201], v[8:11]
	v_mfma_f32_16x16x32_bf16 v[60:63], v[158:161], v[178:181], v[60:63]
	v_mfma_f32_16x16x32_bf16 v[56:59], v[170:173], v[178:181], v[56:59]
	v_mfma_f32_16x16x32_bf16 v[48:51], v[158:161], v[186:189], v[48:51]
	v_mfma_f32_16x16x32_bf16 v[40:43], v[170:173], v[186:189], v[40:43]
	v_mfma_f32_16x16x32_bf16 v[32:35], v[158:161], v[194:197], v[32:35]
	v_mfma_f32_16x16x32_bf16 v[24:27], v[170:173], v[194:197], v[24:27]
	v_mfma_f32_16x16x32_bf16 v[16:19], v[158:161], v[202:205], v[16:19]
	v_mfma_f32_16x16x32_bf16 v[8:11], v[170:173], v[202:205], v[8:11]
	s_setprio 0
	s_barrier
	s_add_u32 s42, s0, 0x40000
	s_addc_u32 s43, s1, 0
	s_add_i32 s2, s49, s35
	s_mov_b32 m0, s2
	s_nop 0
	global_load_lds_dwordx4 v130, s[42:43]
	s_add_i32 m0, s2, 0x2000
	s_nop 0
	global_load_lds_dwordx4 v134, s[42:43]
	s_waitcnt vmcnt(6)
	s_barrier
	s_setprio 1
	v_mfma_f32_16x16x32_bf16 v[52:55], v[206:209], v[174:177], v[52:55]
	v_mfma_f32_16x16x32_bf16 v[44:47], v[232:235], v[174:177], v[44:47]
	v_mfma_f32_16x16x32_bf16 v[36:39], v[206:209], v[182:185], v[36:39]
	v_mfma_f32_16x16x32_bf16 v[28:31], v[232:235], v[182:185], v[28:31]
	v_mfma_f32_16x16x32_bf16 v[20:23], v[206:209], v[190:193], v[20:23]
	v_mfma_f32_16x16x32_bf16 v[12:15], v[232:235], v[190:193], v[12:15]
	v_mfma_f32_16x16x32_bf16 v[4:7], v[206:209], v[198:201], v[4:7]
	v_mfma_f32_16x16x32_bf16 v[0:3], v[232:235], v[198:201], v[0:3]
	v_mfma_f32_16x16x32_bf16 v[52:55], v[228:231], v[178:181], v[52:55]
	v_mfma_f32_16x16x32_bf16 v[44:47], v[236:239], v[178:181], v[44:47]
	v_mfma_f32_16x16x32_bf16 v[36:39], v[228:231], v[186:189], v[36:39]
	v_mfma_f32_16x16x32_bf16 v[28:31], v[236:239], v[186:189], v[28:31]
	v_mfma_f32_16x16x32_bf16 v[20:23], v[228:231], v[194:197], v[20:23]
	v_mfma_f32_16x16x32_bf16 v[12:15], v[236:239], v[194:197], v[12:15]
	v_mfma_f32_16x16x32_bf16 v[4:7], v[228:231], v[202:205], v[4:7]
	v_mfma_f32_16x16x32_bf16 v[0:3], v[236:239], v[202:205], v[0:3]
	s_setprio 0
	s_add_i32 s2, 0, 0x18000
	v_add_u32_e32 v140, s2, v168
	s_barrier
	ds_read_b128 v[154:157], v140
	ds_read_b128 v[158:161], v140 offset:1024
	ds_read_b128 v[162:165], v140 offset:2048
	ds_read_b128 v[170:173], v140 offset:3072
	s_add_u32 s30, s30, 0x40000
	s_addc_u32 s31, s31, 0
	s_mov_b32 m0, s38
	ds_read_b128 v[174:177], v169 offset:32768
	ds_read_b128 v[178:181], v169 offset:33792
	ds_read_b128 v[182:185], v169 offset:34816
	ds_read_b128 v[186:189], v169 offset:35840
	ds_read_b128 v[190:193], v169 offset:36864
	ds_read_b128 v[194:197], v169 offset:37888
	ds_read_b128 v[198:201], v169 offset:38912
	global_load_lds_dwordx4 v128, s[30:31]
	s_mov_b32 m0, s39
	ds_read_b128 v[202:205], v169 offset:39936
	global_load_lds_dwordx4 v132, s[30:31]
	s_waitcnt lgkmcnt(8)
	s_barrier
	s_waitcnt lgkmcnt(0)
	s_setprio 1
	v_mfma_f32_16x16x32_bf16 v[124:127], v[154:157], v[174:177], v[124:127]
	v_mfma_f32_16x16x32_bf16 v[120:123], v[162:165], v[174:177], v[120:123]
	v_mfma_f32_16x16x32_bf16 v[112:115], v[154:157], v[182:185], v[112:115]
	v_mfma_f32_16x16x32_bf16 v[104:107], v[162:165], v[182:185], v[104:107]
	v_mfma_f32_16x16x32_bf16 v[96:99], v[154:157], v[190:193], v[96:99]
	v_mfma_f32_16x16x32_bf16 v[88:91], v[162:165], v[190:193], v[88:91]
	v_mfma_f32_16x16x32_bf16 v[80:83], v[154:157], v[198:201], v[80:83]
	v_mfma_f32_16x16x32_bf16 v[72:75], v[162:165], v[198:201], v[72:75]
	v_mfma_f32_16x16x32_bf16 v[124:127], v[158:161], v[178:181], v[124:127]
	v_mfma_f32_16x16x32_bf16 v[120:123], v[170:173], v[178:181], v[120:123]
	v_mfma_f32_16x16x32_bf16 v[112:115], v[158:161], v[186:189], v[112:115]
	v_mfma_f32_16x16x32_bf16 v[104:107], v[170:173], v[186:189], v[104:107]
	v_mfma_f32_16x16x32_bf16 v[96:99], v[158:161], v[194:197], v[96:99]
	v_mfma_f32_16x16x32_bf16 v[88:91], v[170:173], v[194:197], v[88:91]
	v_mfma_f32_16x16x32_bf16 v[80:83], v[158:161], v[202:205], v[80:83]
	v_mfma_f32_16x16x32_bf16 v[72:75], v[170:173], v[202:205], v[72:75]
	s_setprio 0
	s_barrier
	s_add_i32 s30, 0, 0x1c000
	s_add_i32 s2, s2, s35
	v_add_u32_e32 v140, s30, v168
	s_mov_b32 m0, s2
	ds_read_b128 v[206:209], v140
	ds_read_b128 v[228:231], v140 offset:1024
	ds_read_b128 v[232:235], v140 offset:2048
	ds_read_b128 v[236:239], v140 offset:3072
	s_add_u32 s100, s0, 0x80
	s_addc_u32 s101, s1, 0
	global_load_lds_dwordx4 v130, s[100:101]
	s_add_i32 m0, s2, 0x2000
	s_nop 0
	global_load_lds_dwordx4 v134, s[100:101]
	s_barrier
	s_waitcnt lgkmcnt(0)
	s_setprio 1
	v_mfma_f32_16x16x32_bf16 v[116:119], v[206:209], v[174:177], v[116:119]
	v_mfma_f32_16x16x32_bf16 v[108:111], v[232:235], v[174:177], v[108:111]
	v_mfma_f32_16x16x32_bf16 v[100:103], v[206:209], v[182:185], v[100:103]
	v_mfma_f32_16x16x32_bf16 v[92:95], v[232:235], v[182:185], v[92:95]
	v_mfma_f32_16x16x32_bf16 v[84:87], v[206:209], v[190:193], v[84:87]
	v_mfma_f32_16x16x32_bf16 v[76:79], v[232:235], v[190:193], v[76:79]
	v_mfma_f32_16x16x32_bf16 v[68:71], v[206:209], v[198:201], v[68:71]
	v_mfma_f32_16x16x32_bf16 v[64:67], v[232:235], v[198:201], v[64:67]
	v_mfma_f32_16x16x32_bf16 v[116:119], v[228:231], v[178:181], v[116:119]
	v_mfma_f32_16x16x32_bf16 v[108:111], v[236:239], v[178:181], v[108:111]
	v_mfma_f32_16x16x32_bf16 v[100:103], v[228:231], v[186:189], v[100:103]
	v_mfma_f32_16x16x32_bf16 v[92:95], v[236:239], v[186:189], v[92:95]
	v_mfma_f32_16x16x32_bf16 v[84:87], v[228:231], v[194:197], v[84:87]
	v_mfma_f32_16x16x32_bf16 v[76:79], v[236:239], v[194:197], v[76:79]
	v_mfma_f32_16x16x32_bf16 v[68:71], v[228:231], v[202:205], v[68:71]
	v_mfma_f32_16x16x32_bf16 v[64:67], v[236:239], v[202:205], v[64:67]
	s_setprio 0
	s_mov_b32 m0, s44
	v_lshl_add_u64 v[166:167], v[240:241], 0, s[82:83]
	s_barrier
	ds_read_b128 v[174:177], v169 offset:49152
	ds_read_b128 v[178:181], v169 offset:50176
	ds_read_b128 v[182:185], v169 offset:51200
	ds_read_b128 v[186:189], v169 offset:52224
	ds_read_b128 v[190:193], v169 offset:53248
	ds_read_b128 v[194:197], v169 offset:54272
	ds_read_b128 v[198:201], v169 offset:55296
	ds_read_b128 v[202:205], v169 offset:56320
	global_load_lds_dwordx4 v[166:167], off
	v_lshl_add_u64 v[166:167], v[242:243], 0, s[82:83]
	s_mov_b32 m0, s45
	s_nop 0
	global_load_lds_dwordx4 v[166:167], off
	s_barrier
	s_waitcnt lgkmcnt(0)
	s_setprio 1
	v_mfma_f32_16x16x32_bf16 v[60:63], v[154:157], v[174:177], v[60:63]
	v_mfma_f32_16x16x32_bf16 v[56:59], v[162:165], v[174:177], v[56:59]
	v_mfma_f32_16x16x32_bf16 v[48:51], v[154:157], v[182:185], v[48:51]
	v_mfma_f32_16x16x32_bf16 v[40:43], v[162:165], v[182:185], v[40:43]
	v_mfma_f32_16x16x32_bf16 v[32:35], v[154:157], v[190:193], v[32:35]
	v_mfma_f32_16x16x32_bf16 v[24:27], v[162:165], v[190:193], v[24:27]
	v_mfma_f32_16x16x32_bf16 v[16:19], v[154:157], v[198:201], v[16:19]
	v_mfma_f32_16x16x32_bf16 v[8:11], v[162:165], v[198:201], v[8:11]
	v_mfma_f32_16x16x32_bf16 v[60:63], v[158:161], v[178:181], v[60:63]
	v_mfma_f32_16x16x32_bf16 v[56:59], v[170:173], v[178:181], v[56:59]
	v_mfma_f32_16x16x32_bf16 v[48:51], v[158:161], v[186:189], v[48:51]
	v_mfma_f32_16x16x32_bf16 v[40:43], v[170:173], v[186:189], v[40:43]
	v_mfma_f32_16x16x32_bf16 v[32:35], v[158:161], v[194:197], v[32:35]
	v_mfma_f32_16x16x32_bf16 v[24:27], v[170:173], v[194:197], v[24:27]
	v_mfma_f32_16x16x32_bf16 v[16:19], v[158:161], v[202:205], v[16:19]
	v_mfma_f32_16x16x32_bf16 v[8:11], v[170:173], v[202:205], v[8:11]
	s_setprio 0
	s_barrier
	s_add_u32 s0, s0, 0x40080
	s_addc_u32 s1, s1, 0
	s_add_i32 s2, s30, s35
	s_mov_b32 m0, s2
	s_nop 0
	global_load_lds_dwordx4 v130, s[0:1]
	s_add_i32 m0, s2, 0x2000
	s_nop 0
	global_load_lds_dwordx4 v134, s[0:1]
	s_waitcnt vmcnt(6)
	s_barrier
	s_setprio 1
	v_mfma_f32_16x16x32_bf16 v[52:55], v[206:209], v[174:177], v[52:55]
	v_mfma_f32_16x16x32_bf16 v[44:47], v[232:235], v[174:177], v[44:47]
	v_mfma_f32_16x16x32_bf16 v[36:39], v[206:209], v[182:185], v[36:39]
	v_mfma_f32_16x16x32_bf16 v[28:31], v[232:235], v[182:185], v[28:31]
	v_mfma_f32_16x16x32_bf16 v[20:23], v[206:209], v[190:193], v[20:23]
	v_mfma_f32_16x16x32_bf16 v[12:15], v[232:235], v[190:193], v[12:15]
	v_mfma_f32_16x16x32_bf16 v[4:7], v[206:209], v[198:201], v[4:7]
	v_mfma_f32_16x16x32_bf16 v[0:3], v[232:235], v[198:201], v[0:3]
	v_mfma_f32_16x16x32_bf16 v[52:55], v[228:231], v[178:181], v[52:55]
	v_mfma_f32_16x16x32_bf16 v[44:47], v[236:239], v[178:181], v[44:47]
	v_mfma_f32_16x16x32_bf16 v[36:39], v[228:231], v[186:189], v[36:39]
	v_mfma_f32_16x16x32_bf16 v[28:31], v[236:239], v[186:189], v[28:31]
	v_mfma_f32_16x16x32_bf16 v[20:23], v[228:231], v[194:197], v[20:23]
	v_mfma_f32_16x16x32_bf16 v[12:15], v[236:239], v[194:197], v[12:15]
	v_mfma_f32_16x16x32_bf16 v[4:7], v[228:231], v[202:205], v[4:7]
	v_mfma_f32_16x16x32_bf16 v[0:3], v[236:239], v[202:205], v[0:3]
	s_setprio 0
	s_add_i32 s21, s21, 2
	s_add_u32 s17, s17, 0x100
	s_addc_u32 s19, s19, 0
	s_add_u32 s8, s8, 0x100
	s_addc_u32 s9, s9, 0
	s_cmp_gt_u32 s21, 13
	s_barrier
	s_cbranch_scc0 .LBB0_507
	v_mbcnt_lo_u32_b32 v154, -1, 0
	v_mbcnt_hi_u32_b32 v154, -1, v154
	s_lshl_b32 s19, s16, 8
	v_and_b32_e32 v140, 15, v154
	v_ashrrev_i32_e32 v154, 1, v154
	s_cmp_lt_i32 s48, 8
	v_and_b32_e32 v170, -8, v154
	s_mov_b64 s[0:1], -1
	s_cbranch_scc0 .LBB0_552
	s_ashr_i32 s2, s48, 1
	s_mov_b32 s30, 0x3e38aa3b
	s_cmp_lt_u32 s48, 2
	s_mov_b64 s[8:9], s[24:25]
	s_cbranch_scc1 .LBB0_519
	s_cmp_lt_i32 s2, 2
	s_cbranch_scc1 .LBB0_514
	s_cmp_eq_u32 s2, 2
	s_cbranch_scc0 .LBB0_513
	s_mov_b64 s[0:1], 0
